# A/B: all s_setprio flips deleted from the six GEMM K-loops (they were already outside the compute segments); everything else as the peeled-K-loop version
# speedup vs baseline: 1.0134x; 1.0061x over previous
; #define PG8_STAGE(bufoff, gbase, voff) do { _Pragma("unroll") for (int _i = 0; _i < 2; ++_i) \
;         __builtin_amdgcn_global_load_lds((const unsigned*)((const char*)(gbase) + (voff)[_i]), (LAS unsigned*)(lds + (bufoff) + ldsw + _i * 8192), 16, 0, 0); } while (0)
; #define PG8_LDA(dst, b, h) do { _Pragma("unroll") for (int m = 0; m < 4; ++m) _Pragma("unroll") for (int k = 0; k < 2; ++k) dst[m][k] = *(const LAS bf16x8*)(lds + PG8_SA(b, h) + aoff + m * 2048 + k * 1024); } while (0)
; #define PG8_LDB(dst, b, h) do { _Pragma("unroll") for (int n = 0; n < 2; ++n) _Pragma("unroll") for (int k = 0; k < 2; ++k) dst[n][k] = *(const LAS bf16x8*)(lds + PG8_SB(b, h) + boff + n * 2048 + k * 1024); } while (0)
; #define PG8_WAIT_V(n) asm volatile("s_waitcnt vmcnt(" #n ")" ::: "memory")
; #define PG8_BAR __builtin_amdgcn_s_barrier()
; template <class Epi, class Sched = StaticOrder, class EpiSub = NoSub, bool FAST = false>
; __device__ __forceinline__ void gemm_phase(LAS unsigned char* lds, const Gemm g, const Sched& S, const Epi& E, const EpiSub& ES = EpiSub()) {
;     ...
;         const bool has_next = S.next(ui + 1, nxt);
;         const size_t nko = (has_next && nxt.kb >= 0) ? nxt.kb * ksubB : 0;
;         const char* nA = has_next ? (const char*)g.A + (size_t)nxt.pm * tstepA + (size_t)nxt.pn * g.acs + nko : cA; const char* nB = has_next ? (const char*)g.Bt + (size_t)nxt.pn * tstepB + nko : cB;
;         const int nt = cur.kb < 0 ? ntMain : ntSub;
;         for (int t = 0; t < nt; t += 2) {
;             const bool last = (t == nt - 2);
;             const char* a1 = cA + (size_t)(t + 1) * kstep;
;             const char* a2 = last ? nA : cA + (size_t)(t + 2) * kstep; const char* b2 = last ? nB : cB + (size_t)(t + 2) * kstep;
;             const char* a3 = a2 + kstep; const char* b3 = b2 + kstep;
;             if constexpr (FAST && PG8_SP2) {
;             PG8_LDB(B0, 0, 0); PG8_LDB(B1, 0, 1); PG8_SCHED; PG8_LDA(At, 0, 0); PG8_STAGE(PG8_SA(1, 1), a1 + hstepA, voffA);
;             PG8_WAIT_V(8); PG8_WAIT_L(0); PG8_BAR; PG8_MMA(0, 0, At, B0); PG8_MMA(0, 1, At, B1); PG8_BAR; PG8_SCHED;
;             PG8_LDA(At, 0, 1); PG8_STAGE(PG8_SB(0, 0), b2, voffB); PG8_STAGE(PG8_SB(0, 1), b2 + hstepB, voffB); PG8_STAGE(PG8_SA(0, 0), a2, voffA);
;             PG8_WAIT_V(8); PG8_WAIT_L(0); PG8_BAR; PG8_MMA(1, 0, At, B0); PG8_MMA(1, 1, At, B1); PG8_BAR; PG8_SCHED;
.LBB0_215:
	s_ashr_i32 s15, s14, 31
	s_lshl_b64 s[2:3], s[14:15], 20
	v_readlane_b32 s16, v254, 36
	v_readlane_b32 s17, v254, 37
	s_add_u32 s16, s16, s2
	s_addc_u32 s17, s17, s3
	s_and_b64 s[2:3], s[0:1], exec
	s_cselect_b32 s2, s17, s23
	s_cselect_b32 s3, s16, s22
	s_ashr_i32 s13, s12, 31
	s_lshl_b64 s[18:19], s[12:13], 20
	s_add_u32 s18, s28, s18
	s_addc_u32 s19, s29, s19
	s_and_b64 s[26:27], s[0:1], exec
	s_cselect_b32 s13, s19, s25
	s_cselect_b32 s15, s18, s24
	s_add_u32 s22, s22, 0x80080
	s_addc_u32 s23, s23, 0
	s_add_u32 s48, s24, 0x100
	s_addc_u32 s49, s25, 0
	s_mov_b32 s50, -2
	ds_read_b128 v[154:157], v150
	ds_read_b128 v[158:161], v150 offset:1024
	ds_read_b128 v[162:165], v150 offset:2048
	ds_read_b128 v[166:169], v150 offset:3072
	ds_read_b128 v[170:173], v151
	ds_read_b128 v[174:177], v151 offset:1024
	ds_read_b128 v[178:181], v151 offset:2048
	ds_read_b128 v[182:185], v151 offset:3072
	s_add_u32 s24, s22, 0xfff80080
	s_addc_u32 s25, s23, -1
	s_cmp_eq_u32 s50, 28
	s_cselect_b32 s27, s2, s25
	s_cselect_b32 s26, s3, s24
	s_cselect_b32 s25, s13, s49
	s_cselect_b32 s24, s15, s48
	v_lshl_add_u64 v[144:145], s[22:23], 0, v[136:137]
	s_add_i32 m0, s21, 0xc000
	ds_read_b128 v[186:189], v152
	ds_read_b128 v[194:197], v152 offset:1024
	ds_read_b128 v[198:201], v152 offset:2048
	ds_read_b128 v[202:205], v152 offset:3072
	ds_read_b128 v[206:209], v152 offset:4096
	ds_read_b128 v[210:213], v152 offset:5120
	ds_read_b128 v[214:217], v152 offset:6144
	ds_read_b128 v[218:221], v152 offset:7168
	global_load_lds_dwordx4 v[144:145], off
	v_lshl_add_u64 v[144:145], s[22:23], 0, v[138:139]
	s_add_i32 m0, s21, 0xe000
	s_nop 0
	global_load_lds_dwordx4 v[144:145], off
	s_waitcnt vmcnt(8)
	s_waitcnt lgkmcnt(0)
	s_barrier
	v_mfma_f32_16x16x32_bf16 v[124:127], v[154:157], v[186:189], 0
	v_mfma_f32_16x16x32_bf16 v[120:123], v[162:165], v[186:189], 0
	v_mfma_f32_16x16x32_bf16 v[116:119], v[154:157], v[198:201], 0
	v_mfma_f32_16x16x32_bf16 v[108:111], v[162:165], v[198:201], 0
	v_mfma_f32_16x16x32_bf16 v[100:103], v[154:157], v[206:209], 0
	v_mfma_f32_16x16x32_bf16 v[92:95], v[162:165], v[206:209], 0
	v_mfma_f32_16x16x32_bf16 v[84:87], v[154:157], v[214:217], 0
	v_mfma_f32_16x16x32_bf16 v[76:79], v[162:165], v[214:217], 0
	v_mfma_f32_16x16x32_bf16 v[124:127], v[158:161], v[194:197], v[124:127]
	v_mfma_f32_16x16x32_bf16 v[120:123], v[166:169], v[194:197], v[120:123]
	v_mfma_f32_16x16x32_bf16 v[116:119], v[158:161], v[202:205], v[116:119]
	v_mfma_f32_16x16x32_bf16 v[108:111], v[166:169], v[202:205], v[108:111]
	v_mfma_f32_16x16x32_bf16 v[100:103], v[158:161], v[210:213], v[100:103]
	v_mfma_f32_16x16x32_bf16 v[92:95], v[166:169], v[210:213], v[92:95]
	v_mfma_f32_16x16x32_bf16 v[84:87], v[158:161], v[218:221], v[84:87]
	v_mfma_f32_16x16x32_bf16 v[76:79], v[166:169], v[218:221], v[76:79]
	v_mfma_f32_16x16x32_bf16 v[112:115], v[170:173], v[186:189], 0
	v_mfma_f32_16x16x32_bf16 v[104:107], v[178:181], v[186:189], 0
	v_mfma_f32_16x16x32_bf16 v[96:99], v[170:173], v[198:201], 0
	v_mfma_f32_16x16x32_bf16 v[88:91], v[178:181], v[198:201], 0
	v_mfma_f32_16x16x32_bf16 v[80:83], v[170:173], v[206:209], 0
	v_mfma_f32_16x16x32_bf16 v[72:75], v[178:181], v[206:209], 0
	v_mfma_f32_16x16x32_bf16 v[68:71], v[170:173], v[214:217], 0
	v_mfma_f32_16x16x32_bf16 v[64:67], v[178:181], v[214:217], 0
	v_mfma_f32_16x16x32_bf16 v[112:115], v[174:177], v[194:197], v[112:115]
	v_mfma_f32_16x16x32_bf16 v[104:107], v[182:185], v[194:197], v[104:107]
	v_mfma_f32_16x16x32_bf16 v[96:99], v[174:177], v[202:205], v[96:99]
	v_mfma_f32_16x16x32_bf16 v[88:91], v[182:185], v[202:205], v[88:91]
	v_mfma_f32_16x16x32_bf16 v[80:83], v[174:177], v[210:213], v[80:83]
	v_mfma_f32_16x16x32_bf16 v[72:75], v[182:185], v[210:213], v[72:75]
	v_mfma_f32_16x16x32_bf16 v[68:71], v[174:177], v[218:221], v[68:71]
	v_mfma_f32_16x16x32_bf16 v[64:67], v[182:185], v[218:221], v[64:67]
	s_barrier
	s_add_i32 s51, s41, s30
	v_lshl_add_u64 v[144:145], s[24:25], 0, v[130:131]
	s_mov_b32 m0, s51
	ds_read_b128 v[186:189], v152 offset:16384
	ds_read_b128 v[194:197], v152 offset:17408
	ds_read_b128 v[198:201], v152 offset:18432
	ds_read_b128 v[202:205], v152 offset:19456
	ds_read_b128 v[206:209], v152 offset:20480
	ds_read_b128 v[210:213], v152 offset:21504
	ds_read_b128 v[214:217], v152 offset:22528
	ds_read_b128 v[218:221], v152 offset:23552
	global_load_lds_dwordx4 v[144:145], off
	s_add_i32 m0, s51, 0x2000
	s_add_u32 s68, s24, 0x80000
	v_lshl_add_u64 v[190:191], s[24:25], 0, v[134:135]
	s_addc_u32 s69, s25, 0
	s_add_i32 s51, s42, s30
	global_load_lds_dwordx4 v[190:191], off
	v_lshl_add_u64 v[222:223], s[68:69], 0, v[130:131]
	s_mov_b32 m0, s51
	v_lshl_add_u64 v[224:225], s[26:27], 0, v[132:133]
	global_load_lds_dwordx4 v[222:223], off
	v_lshl_add_u64 v[222:223], s[68:69], 0, v[134:135]
	s_add_i32 m0, s51, 0x2000
	s_nop 0
	global_load_lds_dwordx4 v[222:223], off
	v_lshl_add_u64 v[222:223], s[26:27], 0, v[128:129]
	s_mov_b32 m0, s21
	s_nop 0
	global_load_lds_dwordx4 v[222:223], off
	s_mov_b32 m0, s34
	s_nop 0
	global_load_lds_dwordx4 v[224:225], off
	s_waitcnt vmcnt(8)
	s_waitcnt lgkmcnt(0)
	s_barrier
; #define PG8_STAGE(bufoff, gbase, voff) do { _Pragma("unroll") for (int _i = 0; _i < 2; ++_i) \
;         __builtin_amdgcn_global_load_lds((const unsigned*)((const char*)(gbase) + (voff)[_i]), (LAS unsigned*)(lds + (bufoff) + ldsw + _i * 8192), 16, 0, 0); } while (0)
; #define PG8_LDA(dst, b, h) do { _Pragma("unroll") for (int m = 0; m < 4; ++m) _Pragma("unroll") for (int k = 0; k < 2; ++k) dst[m][k] = *(const LAS bf16x8*)(lds + PG8_SA(b, h) + aoff + m * 2048 + k * 1024); } while (0)
; #define PG8_LDB(dst, b, h) do { _Pragma("unroll") for (int n = 0; n < 2; ++n) _Pragma("unroll") for (int k = 0; k < 2; ++k) dst[n][k] = *(const LAS bf16x8*)(lds + PG8_SB(b, h) + boff + n * 2048 + k * 1024); } while (0)
; #define PG8_MMA(ai, bj, At, Bt) do { __builtin_amdgcn_s_setprio(1); _Pragma("unroll") for (int m = 0; m < 4; ++m) _Pragma("unroll") for (int n = 0; n < 2; ++n) _Pragma("unroll") for (int k = 0; k < 2; ++k) \
;         acc[ai][bj][m][n] = __builtin_amdgcn_mfma_f32_16x16x32_bf16(Bt[n][k], At[m][k], acc[ai][bj][m][n], 0, 0, 0); __builtin_amdgcn_s_setprio(0); } while (0)
; #define PG8_WAIT_V(n) asm volatile("s_waitcnt vmcnt(" #n ")" ::: "memory")
; #define PG8_WAIT_L(n) asm volatile("s_waitcnt lgkmcnt(" #n ")" ::: "memory")
; #define PG8_BAR __builtin_amdgcn_s_barrier()
; #define PG8_SCHED __builtin_amdgcn_sched_barrier(0)
; template <class Epi, class Sched = StaticOrder, class EpiSub = NoSub, bool FAST = false>
; __device__ __forceinline__ void gemm_phase(LAS unsigned char* lds, const Gemm g, const Sched& S, const Epi& E, const EpiSub& ES = EpiSub()) {
;     ...
;             PG8_WAIT_V(8); PG8_WAIT_L(0); PG8_BAR; PG8_MMA(1, 0, At, B0); PG8_MMA(1, 1, At, B1); PG8_BAR; PG8_SCHED;
;             PG8_LDB(B0, 1, 0); PG8_LDB(B1, 1, 1); PG8_SCHED; PG8_LDA(At, 1, 0); PG8_STAGE(PG8_SA(0, 1), a2 + hstepA, voffA);
;             PG8_WAIT_V(8); PG8_WAIT_L(0); PG8_BAR; PG8_MMA(0, 0, At, B0); PG8_MMA(0, 1, At, B1); PG8_BAR; PG8_SCHED;
	v_mfma_f32_16x16x32_bf16 v[60:63], v[154:157], v[186:189], 0
	v_mfma_f32_16x16x32_bf16 v[56:59], v[162:165], v[186:189], 0
	v_mfma_f32_16x16x32_bf16 v[52:55], v[154:157], v[198:201], 0
	v_mfma_f32_16x16x32_bf16 v[44:47], v[162:165], v[198:201], 0
	v_mfma_f32_16x16x32_bf16 v[36:39], v[154:157], v[206:209], 0
	v_mfma_f32_16x16x32_bf16 v[28:31], v[162:165], v[206:209], 0
	v_mfma_f32_16x16x32_bf16 v[20:23], v[154:157], v[214:217], 0
	v_mfma_f32_16x16x32_bf16 v[12:15], v[162:165], v[214:217], 0
	v_mfma_f32_16x16x32_bf16 v[60:63], v[158:161], v[194:197], v[60:63]
	v_mfma_f32_16x16x32_bf16 v[56:59], v[166:169], v[194:197], v[56:59]
	v_mfma_f32_16x16x32_bf16 v[52:55], v[158:161], v[202:205], v[52:55]
	v_mfma_f32_16x16x32_bf16 v[44:47], v[166:169], v[202:205], v[44:47]
	v_mfma_f32_16x16x32_bf16 v[36:39], v[158:161], v[210:213], v[36:39]
	v_mfma_f32_16x16x32_bf16 v[28:31], v[166:169], v[210:213], v[28:31]
	v_mfma_f32_16x16x32_bf16 v[20:23], v[158:161], v[218:221], v[20:23]
	v_mfma_f32_16x16x32_bf16 v[12:15], v[166:169], v[218:221], v[12:15]
	v_mfma_f32_16x16x32_bf16 v[48:51], v[170:173], v[186:189], 0
	v_mfma_f32_16x16x32_bf16 v[40:43], v[178:181], v[186:189], 0
	v_mfma_f32_16x16x32_bf16 v[32:35], v[170:173], v[198:201], 0
	v_mfma_f32_16x16x32_bf16 v[24:27], v[178:181], v[198:201], 0
	v_mfma_f32_16x16x32_bf16 v[16:19], v[170:173], v[206:209], 0
	v_mfma_f32_16x16x32_bf16 v[8:11], v[178:181], v[206:209], 0
	v_mfma_f32_16x16x32_bf16 v[4:7], v[170:173], v[214:217], 0
	v_mfma_f32_16x16x32_bf16 v[0:3], v[178:181], v[214:217], 0
	v_mfma_f32_16x16x32_bf16 v[48:51], v[174:177], v[194:197], v[48:51]
	v_mfma_f32_16x16x32_bf16 v[40:43], v[182:185], v[194:197], v[40:43]
	v_mfma_f32_16x16x32_bf16 v[32:35], v[174:177], v[202:205], v[32:35]
	v_mfma_f32_16x16x32_bf16 v[24:27], v[182:185], v[202:205], v[24:27]
	v_mfma_f32_16x16x32_bf16 v[16:19], v[174:177], v[210:213], v[16:19]
	v_mfma_f32_16x16x32_bf16 v[8:11], v[182:185], v[210:213], v[8:11]
	v_mfma_f32_16x16x32_bf16 v[4:7], v[174:177], v[218:221], v[4:7]
	v_mfma_f32_16x16x32_bf16 v[0:3], v[182:185], v[218:221], v[0:3]
	s_barrier
	s_add_i32 s51, 0, 0x18000
	v_add_u32_e32 v153, s51, v148
	s_add_i32 s68, 0, 0x1c000
	ds_read_b128 v[154:157], v153
	ds_read_b128 v[158:161], v153 offset:1024
	ds_read_b128 v[162:165], v153 offset:2048
	ds_read_b128 v[166:169], v153 offset:3072
	v_add_u32_e32 v153, s68, v148
	ds_read_b128 v[170:173], v153
	ds_read_b128 v[174:177], v153 offset:1024
	ds_read_b128 v[178:181], v153 offset:2048
	ds_read_b128 v[182:185], v153 offset:3072
	s_add_u32 s26, s26, 0x80000
	s_addc_u32 s27, s27, 0
	s_mov_b32 m0, s35
	v_lshl_add_u64 v[226:227], s[26:27], 0, v[128:129]
	ds_read_b128 v[186:189], v152 offset:32768
	ds_read_b128 v[194:197], v152 offset:33792
	ds_read_b128 v[198:201], v152 offset:34816
	ds_read_b128 v[202:205], v152 offset:35840
	ds_read_b128 v[206:209], v152 offset:36864
	ds_read_b128 v[210:213], v152 offset:37888
	ds_read_b128 v[214:217], v152 offset:38912
	ds_read_b128 v[218:221], v152 offset:39936
	global_load_lds_dwordx4 v[226:227], off
	v_lshl_add_u64 v[226:227], s[26:27], 0, v[132:133]
	s_mov_b32 m0, s36
	s_nop 0
	global_load_lds_dwordx4 v[226:227], off
	s_waitcnt vmcnt(8)
	s_waitcnt lgkmcnt(0)
	s_barrier
	v_mfma_f32_16x16x32_bf16 v[124:127], v[154:157], v[186:189], v[124:127]
	v_mfma_f32_16x16x32_bf16 v[120:123], v[162:165], v[186:189], v[120:123]
	v_mfma_f32_16x16x32_bf16 v[116:119], v[154:157], v[198:201], v[116:119]
	v_mfma_f32_16x16x32_bf16 v[108:111], v[162:165], v[198:201], v[108:111]
	v_mfma_f32_16x16x32_bf16 v[100:103], v[154:157], v[206:209], v[100:103]
	v_mfma_f32_16x16x32_bf16 v[92:95], v[162:165], v[206:209], v[92:95]
	v_mfma_f32_16x16x32_bf16 v[84:87], v[154:157], v[214:217], v[84:87]
	v_mfma_f32_16x16x32_bf16 v[76:79], v[162:165], v[214:217], v[76:79]
	v_mfma_f32_16x16x32_bf16 v[124:127], v[158:161], v[194:197], v[124:127]
	v_mfma_f32_16x16x32_bf16 v[120:123], v[166:169], v[194:197], v[120:123]
	v_mfma_f32_16x16x32_bf16 v[116:119], v[158:161], v[202:205], v[116:119]
	v_mfma_f32_16x16x32_bf16 v[108:111], v[166:169], v[202:205], v[108:111]
	v_mfma_f32_16x16x32_bf16 v[100:103], v[158:161], v[210:213], v[100:103]
	v_mfma_f32_16x16x32_bf16 v[92:95], v[166:169], v[210:213], v[92:95]
	v_mfma_f32_16x16x32_bf16 v[84:87], v[158:161], v[218:221], v[84:87]
	v_mfma_f32_16x16x32_bf16 v[76:79], v[166:169], v[218:221], v[76:79]
	v_mfma_f32_16x16x32_bf16 v[112:115], v[170:173], v[186:189], v[112:115]
	v_mfma_f32_16x16x32_bf16 v[104:107], v[178:181], v[186:189], v[104:107]
	v_mfma_f32_16x16x32_bf16 v[96:99], v[170:173], v[198:201], v[96:99]
	v_mfma_f32_16x16x32_bf16 v[88:91], v[178:181], v[198:201], v[88:91]
	v_mfma_f32_16x16x32_bf16 v[80:83], v[170:173], v[206:209], v[80:83]
	v_mfma_f32_16x16x32_bf16 v[72:75], v[178:181], v[206:209], v[72:75]
	v_mfma_f32_16x16x32_bf16 v[68:71], v[170:173], v[214:217], v[68:71]
	v_mfma_f32_16x16x32_bf16 v[64:67], v[178:181], v[214:217], v[64:67]
	v_mfma_f32_16x16x32_bf16 v[112:115], v[174:177], v[194:197], v[112:115]
	v_mfma_f32_16x16x32_bf16 v[104:107], v[182:185], v[194:197], v[104:107]
	v_mfma_f32_16x16x32_bf16 v[96:99], v[174:177], v[202:205], v[96:99]
	v_mfma_f32_16x16x32_bf16 v[88:91], v[182:185], v[202:205], v[88:91]
	v_mfma_f32_16x16x32_bf16 v[80:83], v[174:177], v[210:213], v[80:83]
	v_mfma_f32_16x16x32_bf16 v[72:75], v[182:185], v[210:213], v[72:75]
	v_mfma_f32_16x16x32_bf16 v[68:71], v[174:177], v[218:221], v[68:71]
	v_mfma_f32_16x16x32_bf16 v[64:67], v[182:185], v[218:221], v[64:67]
	s_barrier
; #define PG8_STAGE(bufoff, gbase, voff) do { _Pragma("unroll") for (int _i = 0; _i < 2; ++_i) \
;         __builtin_amdgcn_global_load_lds((const unsigned*)((const char*)(gbase) + (voff)[_i]), (LAS unsigned*)(lds + (bufoff) + ldsw + _i * 8192), 16, 0, 0); } while (0)
; #define PG8_LDA(dst, b, h) do { _Pragma("unroll") for (int m = 0; m < 4; ++m) _Pragma("unroll") for (int k = 0; k < 2; ++k) dst[m][k] = *(const LAS bf16x8*)(lds + PG8_SA(b, h) + aoff + m * 2048 + k * 1024); } while (0)
; #define PG8_LDB(dst, b, h) do { _Pragma("unroll") for (int n = 0; n < 2; ++n) _Pragma("unroll") for (int k = 0; k < 2; ++k) dst[n][k] = *(const LAS bf16x8*)(lds + PG8_SB(b, h) + boff + n * 2048 + k * 1024); } while (0)
; template <class Epi, class Sched = StaticOrder, class EpiSub = NoSub, bool FAST = false>
; __device__ __forceinline__ void gemm_phase(LAS unsigned char* lds, const Gemm g, const Sched& S, const Epi& E, const EpiSub& ES = EpiSub()) {
;     ...
;         for (int t = 0; t < nt; t += 2) {
;             const bool last = (t == nt - 2);
;             const char* a1 = cA + (size_t)(t + 1) * kstep;
;             const char* a2 = last ? nA : cA + (size_t)(t + 2) * kstep; const char* b2 = last ? nB : cB + (size_t)(t + 2) * kstep;
;             const char* a3 = a2 + kstep; const char* b3 = b2 + kstep;
;             if constexpr (FAST && PG8_SP2) {
;             PG8_LDB(B0, 0, 0); PG8_LDB(B1, 0, 1); PG8_SCHED; PG8_LDA(At, 0, 0); PG8_STAGE(PG8_SA(1, 1), a1 + hstepA, voffA);
;             PG8_WAIT_V(8); PG8_WAIT_L(0); PG8_BAR; PG8_MMA(0, 0, At, B0); PG8_MMA(0, 1, At, B1); PG8_BAR; PG8_SCHED;
;             PG8_LDA(At, 0, 1); PG8_STAGE(PG8_SB(0, 0), b2, voffB); PG8_STAGE(PG8_SB(0, 1), b2 + hstepB, voffB); PG8_STAGE(PG8_SA(0, 0), a2, voffA);
;             PG8_WAIT_V(8); PG8_WAIT_L(0); PG8_BAR; PG8_MMA(1, 0, At, B0); PG8_MMA(1, 1, At, B1); PG8_BAR; PG8_SCHED;
;             PG8_LDB(B0, 1, 0); PG8_LDB(B1, 1, 1); PG8_SCHED; PG8_LDA(At, 1, 0); PG8_STAGE(PG8_SA(0, 1), a2 + hstepA, voffA);
;             PG8_WAIT_V(8); PG8_WAIT_L(0); PG8_BAR; PG8_MMA(0, 0, At, B0); PG8_MMA(0, 1, At, B1); PG8_BAR; PG8_SCHED;
;             PG8_LDA(At, 1, 1); PG8_STAGE(PG8_SB(1, 0), b3, voffB); PG8_STAGE(PG8_SB(1, 1), b3 + hstepB, voffB); PG8_STAGE(PG8_SA(1, 0), a3, voffA);
;             PG8_WAIT_V(8); PG8_WAIT_L(0); PG8_BAR; PG8_MMA(1, 0, At, B0); PG8_MMA(1, 1, At, B1); PG8_BAR; PG8_SCHED;
	s_add_i32 s26, s51, s30
	v_lshl_add_u64 v[144:145], v[144:145], 0, s[8:9]
	s_mov_b32 m0, s26
	ds_read_b128 v[186:189], v152 offset:49152
	ds_read_b128 v[194:197], v152 offset:50176
	ds_read_b128 v[198:201], v152 offset:51200
	ds_read_b128 v[202:205], v152 offset:52224
	ds_read_b128 v[206:209], v152 offset:53248
	ds_read_b128 v[210:213], v152 offset:54272
	ds_read_b128 v[214:217], v152 offset:55296
	ds_read_b128 v[218:221], v152 offset:56320
	global_load_lds_dwordx4 v[144:145], off
	s_add_i32 m0, s26, 0x2000
	s_add_u32 s24, s24, 0x80080
	v_lshl_add_u64 v[144:145], v[190:191], 0, s[8:9]
	s_addc_u32 s25, s25, 0
	s_add_i32 s26, s68, s30
	global_load_lds_dwordx4 v[144:145], off
	v_lshl_add_u64 v[144:145], s[24:25], 0, v[130:131]
	s_mov_b32 m0, s26
	s_nop 0
	global_load_lds_dwordx4 v[144:145], off
	v_lshl_add_u64 v[144:145], s[24:25], 0, v[134:135]
	s_add_i32 m0, s26, 0x2000
	s_nop 0
	global_load_lds_dwordx4 v[144:145], off
	v_lshl_add_u64 v[144:145], v[222:223], 0, s[8:9]
	s_mov_b32 m0, s39
	s_nop 0
	global_load_lds_dwordx4 v[144:145], off
	v_lshl_add_u64 v[144:145], v[224:225], 0, s[8:9]
	s_mov_b32 m0, s40
	s_nop 0
	global_load_lds_dwordx4 v[144:145], off
	s_waitcnt vmcnt(8)
	s_waitcnt lgkmcnt(0)
	s_barrier
	v_mfma_f32_16x16x32_bf16 v[60:63], v[154:157], v[186:189], v[60:63]
	v_mfma_f32_16x16x32_bf16 v[56:59], v[162:165], v[186:189], v[56:59]
	v_mfma_f32_16x16x32_bf16 v[52:55], v[154:157], v[198:201], v[52:55]
	v_mfma_f32_16x16x32_bf16 v[44:47], v[162:165], v[198:201], v[44:47]
	v_mfma_f32_16x16x32_bf16 v[36:39], v[154:157], v[206:209], v[36:39]
	v_mfma_f32_16x16x32_bf16 v[28:31], v[162:165], v[206:209], v[28:31]
	v_mfma_f32_16x16x32_bf16 v[20:23], v[154:157], v[214:217], v[20:23]
	v_mfma_f32_16x16x32_bf16 v[12:15], v[162:165], v[214:217], v[12:15]
	v_mfma_f32_16x16x32_bf16 v[60:63], v[158:161], v[194:197], v[60:63]
	v_mfma_f32_16x16x32_bf16 v[56:59], v[166:169], v[194:197], v[56:59]
	v_mfma_f32_16x16x32_bf16 v[52:55], v[158:161], v[202:205], v[52:55]
	v_mfma_f32_16x16x32_bf16 v[44:47], v[166:169], v[202:205], v[44:47]
	v_mfma_f32_16x16x32_bf16 v[36:39], v[158:161], v[210:213], v[36:39]
	v_mfma_f32_16x16x32_bf16 v[28:31], v[166:169], v[210:213], v[28:31]
	v_mfma_f32_16x16x32_bf16 v[20:23], v[158:161], v[218:221], v[20:23]
	v_mfma_f32_16x16x32_bf16 v[12:15], v[166:169], v[218:221], v[12:15]
	v_mfma_f32_16x16x32_bf16 v[48:51], v[170:173], v[186:189], v[48:51]
	v_mfma_f32_16x16x32_bf16 v[40:43], v[178:181], v[186:189], v[40:43]
	v_mfma_f32_16x16x32_bf16 v[32:35], v[170:173], v[198:201], v[32:35]
	v_mfma_f32_16x16x32_bf16 v[24:27], v[178:181], v[198:201], v[24:27]
	v_mfma_f32_16x16x32_bf16 v[16:19], v[170:173], v[206:209], v[16:19]
	v_mfma_f32_16x16x32_bf16 v[8:11], v[178:181], v[206:209], v[8:11]
	v_mfma_f32_16x16x32_bf16 v[4:7], v[170:173], v[214:217], v[4:7]
	v_mfma_f32_16x16x32_bf16 v[0:3], v[178:181], v[214:217], v[0:3]
	v_mfma_f32_16x16x32_bf16 v[48:51], v[174:177], v[194:197], v[48:51]
	v_mfma_f32_16x16x32_bf16 v[40:43], v[182:185], v[194:197], v[40:43]
	v_mfma_f32_16x16x32_bf16 v[32:35], v[174:177], v[202:205], v[32:35]
	v_mfma_f32_16x16x32_bf16 v[24:27], v[182:185], v[202:205], v[24:27]
	v_mfma_f32_16x16x32_bf16 v[16:19], v[174:177], v[210:213], v[16:19]
	v_mfma_f32_16x16x32_bf16 v[8:11], v[182:185], v[210:213], v[8:11]
	v_mfma_f32_16x16x32_bf16 v[4:7], v[174:177], v[218:221], v[4:7]
	v_mfma_f32_16x16x32_bf16 v[0:3], v[182:185], v[218:221], v[0:3]
	s_barrier
	s_add_i32 s50, s50, 2
	s_add_u32 s22, s22, 0x100
	s_addc_u32 s23, s23, 0
	s_add_u32 s48, s48, 0x100
	s_addc_u32 s49, s49, 0
	s_cmp_gt_u32 s50, 29
	s_cbranch_scc1 .Lkpeel_216_exit
.LBB0_216:
	ds_read_b128 v[154:157], v150
	ds_read_b128 v[158:161], v150 offset:1024
	ds_read_b128 v[162:165], v150 offset:2048
	ds_read_b128 v[166:169], v150 offset:3072
	ds_read_b128 v[170:173], v151
	ds_read_b128 v[174:177], v151 offset:1024
	ds_read_b128 v[178:181], v151 offset:2048
	ds_read_b128 v[182:185], v151 offset:3072
	s_add_u32 s24, s22, 0xfff80080
	s_addc_u32 s25, s23, -1
	s_cmp_eq_u32 s50, 28
	s_cselect_b32 s27, s2, s25
	s_cselect_b32 s26, s3, s24
	s_cselect_b32 s25, s13, s49
	s_cselect_b32 s24, s15, s48
	v_lshl_add_u64 v[144:145], s[22:23], 0, v[136:137]
	s_add_i32 m0, s21, 0xc000
	ds_read_b128 v[186:189], v152
	ds_read_b128 v[194:197], v152 offset:1024
	ds_read_b128 v[198:201], v152 offset:2048
	ds_read_b128 v[202:205], v152 offset:3072
	ds_read_b128 v[206:209], v152 offset:4096
	ds_read_b128 v[210:213], v152 offset:5120
	ds_read_b128 v[214:217], v152 offset:6144
	ds_read_b128 v[218:221], v152 offset:7168
	global_load_lds_dwordx4 v[144:145], off
	v_lshl_add_u64 v[144:145], s[22:23], 0, v[138:139]
	s_add_i32 m0, s21, 0xe000
	s_nop 0
	global_load_lds_dwordx4 v[144:145], off
	s_waitcnt vmcnt(8)
	s_waitcnt lgkmcnt(0)
	s_barrier
; #define PG8_STAGE(bufoff, gbase, voff) do { _Pragma("unroll") for (int _i = 0; _i < 2; ++_i) \
;         __builtin_amdgcn_global_load_lds((const unsigned*)((const char*)(gbase) + (voff)[_i]), (LAS unsigned*)(lds + (bufoff) + ldsw + _i * 8192), 16, 0, 0); } while (0)
; #define PG8_LDA(dst, b, h) do { _Pragma("unroll") for (int m = 0; m < 4; ++m) _Pragma("unroll") for (int k = 0; k < 2; ++k) dst[m][k] = *(const LAS bf16x8*)(lds + PG8_SA(b, h) + aoff + m * 2048 + k * 1024); } while (0)
; #define PG8_MMA(ai, bj, At, Bt) do { __builtin_amdgcn_s_setprio(1); _Pragma("unroll") for (int m = 0; m < 4; ++m) _Pragma("unroll") for (int n = 0; n < 2; ++n) _Pragma("unroll") for (int k = 0; k < 2; ++k) \
;         acc[ai][bj][m][n] = __builtin_amdgcn_mfma_f32_16x16x32_bf16(Bt[n][k], At[m][k], acc[ai][bj][m][n], 0, 0, 0); __builtin_amdgcn_s_setprio(0); } while (0)
; #define PG8_WAIT_V(n) asm volatile("s_waitcnt vmcnt(" #n ")" ::: "memory")
; #define PG8_WAIT_L(n) asm volatile("s_waitcnt lgkmcnt(" #n ")" ::: "memory")
; #define PG8_BAR __builtin_amdgcn_s_barrier()
; #define PG8_SCHED __builtin_amdgcn_sched_barrier(0)
; template <class Epi, class Sched = StaticOrder, class EpiSub = NoSub, bool FAST = false>
; __device__ __forceinline__ void gemm_phase(LAS unsigned char* lds, const Gemm g, const Sched& S, const Epi& E, const EpiSub& ES = EpiSub()) {
;     ...
;             PG8_WAIT_V(8); PG8_WAIT_L(0); PG8_BAR; PG8_MMA(0, 0, At, B0); PG8_MMA(0, 1, At, B1); PG8_BAR; PG8_SCHED;
;             PG8_LDA(At, 0, 1); PG8_STAGE(PG8_SB(0, 0), b2, voffB); PG8_STAGE(PG8_SB(0, 1), b2 + hstepB, voffB); PG8_STAGE(PG8_SA(0, 0), a2, voffA);
;             PG8_WAIT_V(8); PG8_WAIT_L(0); PG8_BAR; PG8_MMA(1, 0, At, B0); PG8_MMA(1, 1, At, B1); PG8_BAR; PG8_SCHED;
	v_mfma_f32_16x16x32_bf16 v[124:127], v[154:157], v[186:189], v[124:127]
	v_mfma_f32_16x16x32_bf16 v[120:123], v[162:165], v[186:189], v[120:123]
	v_mfma_f32_16x16x32_bf16 v[116:119], v[154:157], v[198:201], v[116:119]
	v_mfma_f32_16x16x32_bf16 v[108:111], v[162:165], v[198:201], v[108:111]
	v_mfma_f32_16x16x32_bf16 v[100:103], v[154:157], v[206:209], v[100:103]
	v_mfma_f32_16x16x32_bf16 v[92:95], v[162:165], v[206:209], v[92:95]
	v_mfma_f32_16x16x32_bf16 v[84:87], v[154:157], v[214:217], v[84:87]
	v_mfma_f32_16x16x32_bf16 v[76:79], v[162:165], v[214:217], v[76:79]
	v_mfma_f32_16x16x32_bf16 v[124:127], v[158:161], v[194:197], v[124:127]
	v_mfma_f32_16x16x32_bf16 v[120:123], v[166:169], v[194:197], v[120:123]
	v_mfma_f32_16x16x32_bf16 v[116:119], v[158:161], v[202:205], v[116:119]
	v_mfma_f32_16x16x32_bf16 v[108:111], v[166:169], v[202:205], v[108:111]
	v_mfma_f32_16x16x32_bf16 v[100:103], v[158:161], v[210:213], v[100:103]
	v_mfma_f32_16x16x32_bf16 v[92:95], v[166:169], v[210:213], v[92:95]
	v_mfma_f32_16x16x32_bf16 v[84:87], v[158:161], v[218:221], v[84:87]
	v_mfma_f32_16x16x32_bf16 v[76:79], v[166:169], v[218:221], v[76:79]
	v_mfma_f32_16x16x32_bf16 v[112:115], v[170:173], v[186:189], v[112:115]
	v_mfma_f32_16x16x32_bf16 v[104:107], v[178:181], v[186:189], v[104:107]
	v_mfma_f32_16x16x32_bf16 v[96:99], v[170:173], v[198:201], v[96:99]
	v_mfma_f32_16x16x32_bf16 v[88:91], v[178:181], v[198:201], v[88:91]
	v_mfma_f32_16x16x32_bf16 v[80:83], v[170:173], v[206:209], v[80:83]
	v_mfma_f32_16x16x32_bf16 v[72:75], v[178:181], v[206:209], v[72:75]
	v_mfma_f32_16x16x32_bf16 v[68:71], v[170:173], v[214:217], v[68:71]
	v_mfma_f32_16x16x32_bf16 v[64:67], v[178:181], v[214:217], v[64:67]
	v_mfma_f32_16x16x32_bf16 v[112:115], v[174:177], v[194:197], v[112:115]
	v_mfma_f32_16x16x32_bf16 v[104:107], v[182:185], v[194:197], v[104:107]
	v_mfma_f32_16x16x32_bf16 v[96:99], v[174:177], v[202:205], v[96:99]
	v_mfma_f32_16x16x32_bf16 v[88:91], v[182:185], v[202:205], v[88:91]
	v_mfma_f32_16x16x32_bf16 v[80:83], v[174:177], v[210:213], v[80:83]
	v_mfma_f32_16x16x32_bf16 v[72:75], v[182:185], v[210:213], v[72:75]
	v_mfma_f32_16x16x32_bf16 v[68:71], v[174:177], v[218:221], v[68:71]
	v_mfma_f32_16x16x32_bf16 v[64:67], v[182:185], v[218:221], v[64:67]
	s_barrier
	s_add_i32 s51, s41, s30
	v_lshl_add_u64 v[144:145], s[24:25], 0, v[130:131]
	s_mov_b32 m0, s51
	ds_read_b128 v[186:189], v152 offset:16384
	ds_read_b128 v[194:197], v152 offset:17408
	ds_read_b128 v[198:201], v152 offset:18432
	ds_read_b128 v[202:205], v152 offset:19456
	ds_read_b128 v[206:209], v152 offset:20480
	ds_read_b128 v[210:213], v152 offset:21504
	ds_read_b128 v[214:217], v152 offset:22528
	ds_read_b128 v[218:221], v152 offset:23552
	global_load_lds_dwordx4 v[144:145], off
	s_add_i32 m0, s51, 0x2000
	s_add_u32 s68, s24, 0x80000
	v_lshl_add_u64 v[190:191], s[24:25], 0, v[134:135]
	s_addc_u32 s69, s25, 0
	s_add_i32 s51, s42, s30
	global_load_lds_dwordx4 v[190:191], off
	v_lshl_add_u64 v[222:223], s[68:69], 0, v[130:131]
	s_mov_b32 m0, s51
	v_lshl_add_u64 v[224:225], s[26:27], 0, v[132:133]
	global_load_lds_dwordx4 v[222:223], off
	v_lshl_add_u64 v[222:223], s[68:69], 0, v[134:135]
	s_add_i32 m0, s51, 0x2000
	s_nop 0
	global_load_lds_dwordx4 v[222:223], off
	v_lshl_add_u64 v[222:223], s[26:27], 0, v[128:129]
	s_mov_b32 m0, s21
	s_nop 0
	global_load_lds_dwordx4 v[222:223], off
	s_mov_b32 m0, s34
	s_nop 0
	global_load_lds_dwordx4 v[224:225], off
	s_waitcnt vmcnt(8)
	s_waitcnt lgkmcnt(0)
	s_barrier
	v_mfma_f32_16x16x32_bf16 v[60:63], v[154:157], v[186:189], v[60:63]
	v_mfma_f32_16x16x32_bf16 v[56:59], v[162:165], v[186:189], v[56:59]
	v_mfma_f32_16x16x32_bf16 v[52:55], v[154:157], v[198:201], v[52:55]
	v_mfma_f32_16x16x32_bf16 v[44:47], v[162:165], v[198:201], v[44:47]
	v_mfma_f32_16x16x32_bf16 v[36:39], v[154:157], v[206:209], v[36:39]
	v_mfma_f32_16x16x32_bf16 v[28:31], v[162:165], v[206:209], v[28:31]
	v_mfma_f32_16x16x32_bf16 v[20:23], v[154:157], v[214:217], v[20:23]
	v_mfma_f32_16x16x32_bf16 v[12:15], v[162:165], v[214:217], v[12:15]
	v_mfma_f32_16x16x32_bf16 v[60:63], v[158:161], v[194:197], v[60:63]
	v_mfma_f32_16x16x32_bf16 v[56:59], v[166:169], v[194:197], v[56:59]
	v_mfma_f32_16x16x32_bf16 v[52:55], v[158:161], v[202:205], v[52:55]
	v_mfma_f32_16x16x32_bf16 v[44:47], v[166:169], v[202:205], v[44:47]
	v_mfma_f32_16x16x32_bf16 v[36:39], v[158:161], v[210:213], v[36:39]
	v_mfma_f32_16x16x32_bf16 v[28:31], v[166:169], v[210:213], v[28:31]
	v_mfma_f32_16x16x32_bf16 v[20:23], v[158:161], v[218:221], v[20:23]
	v_mfma_f32_16x16x32_bf16 v[12:15], v[166:169], v[218:221], v[12:15]
	v_mfma_f32_16x16x32_bf16 v[48:51], v[170:173], v[186:189], v[48:51]
	v_mfma_f32_16x16x32_bf16 v[40:43], v[178:181], v[186:189], v[40:43]
	v_mfma_f32_16x16x32_bf16 v[32:35], v[170:173], v[198:201], v[32:35]
	v_mfma_f32_16x16x32_bf16 v[24:27], v[178:181], v[198:201], v[24:27]
	v_mfma_f32_16x16x32_bf16 v[16:19], v[170:173], v[206:209], v[16:19]
	v_mfma_f32_16x16x32_bf16 v[8:11], v[178:181], v[206:209], v[8:11]
	v_mfma_f32_16x16x32_bf16 v[4:7], v[170:173], v[214:217], v[4:7]
	v_mfma_f32_16x16x32_bf16 v[0:3], v[178:181], v[214:217], v[0:3]
	v_mfma_f32_16x16x32_bf16 v[48:51], v[174:177], v[194:197], v[48:51]
	v_mfma_f32_16x16x32_bf16 v[40:43], v[182:185], v[194:197], v[40:43]
	v_mfma_f32_16x16x32_bf16 v[32:35], v[174:177], v[202:205], v[32:35]
	v_mfma_f32_16x16x32_bf16 v[24:27], v[182:185], v[202:205], v[24:27]
	v_mfma_f32_16x16x32_bf16 v[16:19], v[174:177], v[210:213], v[16:19]
	v_mfma_f32_16x16x32_bf16 v[8:11], v[182:185], v[210:213], v[8:11]
	v_mfma_f32_16x16x32_bf16 v[4:7], v[174:177], v[218:221], v[4:7]
	v_mfma_f32_16x16x32_bf16 v[0:3], v[182:185], v[218:221], v[0:3]
	s_barrier
; #define PG8_STAGE(bufoff, gbase, voff) do { _Pragma("unroll") for (int _i = 0; _i < 2; ++_i) \
;         __builtin_amdgcn_global_load_lds((const unsigned*)((const char*)(gbase) + (voff)[_i]), (LAS unsigned*)(lds + (bufoff) + ldsw + _i * 8192), 16, 0, 0); } while (0)
; #define PG8_LDA(dst, b, h) do { _Pragma("unroll") for (int m = 0; m < 4; ++m) _Pragma("unroll") for (int k = 0; k < 2; ++k) dst[m][k] = *(const LAS bf16x8*)(lds + PG8_SA(b, h) + aoff + m * 2048 + k * 1024); } while (0)
; #define PG8_LDB(dst, b, h) do { _Pragma("unroll") for (int n = 0; n < 2; ++n) _Pragma("unroll") for (int k = 0; k < 2; ++k) dst[n][k] = *(const LAS bf16x8*)(lds + PG8_SB(b, h) + boff + n * 2048 + k * 1024); } while (0)
; #define PG8_MMA(ai, bj, At, Bt) do { __builtin_amdgcn_s_setprio(1); _Pragma("unroll") for (int m = 0; m < 4; ++m) _Pragma("unroll") for (int n = 0; n < 2; ++n) _Pragma("unroll") for (int k = 0; k < 2; ++k) \
;         acc[ai][bj][m][n] = __builtin_amdgcn_mfma_f32_16x16x32_bf16(Bt[n][k], At[m][k], acc[ai][bj][m][n], 0, 0, 0); __builtin_amdgcn_s_setprio(0); } while (0)
; #define PG8_WAIT_V(n) asm volatile("s_waitcnt vmcnt(" #n ")" ::: "memory")
; #define PG8_WAIT_L(n) asm volatile("s_waitcnt lgkmcnt(" #n ")" ::: "memory")
; #define PG8_BAR __builtin_amdgcn_s_barrier()
; #define PG8_SCHED __builtin_amdgcn_sched_barrier(0)
; template <class Epi, class Sched = StaticOrder, class EpiSub = NoSub, bool FAST = false>
; __device__ __forceinline__ void gemm_phase(LAS unsigned char* lds, const Gemm g, const Sched& S, const Epi& E, const EpiSub& ES = EpiSub()) {
;     ...
;             PG8_LDB(B0, 1, 0); PG8_LDB(B1, 1, 1); PG8_SCHED; PG8_LDA(At, 1, 0); PG8_STAGE(PG8_SA(0, 1), a2 + hstepA, voffA);
;             PG8_WAIT_V(8); PG8_WAIT_L(0); PG8_BAR; PG8_MMA(0, 0, At, B0); PG8_MMA(0, 1, At, B1); PG8_BAR; PG8_SCHED;
;             PG8_LDA(At, 1, 1); PG8_STAGE(PG8_SB(1, 0), b3, voffB); PG8_STAGE(PG8_SB(1, 1), b3 + hstepB, voffB); PG8_STAGE(PG8_SA(1, 0), a3, voffA);
;             PG8_WAIT_V(8); PG8_WAIT_L(0); PG8_BAR; PG8_MMA(1, 0, At, B0); PG8_MMA(1, 1, At, B1); PG8_BAR; PG8_SCHED;
	s_add_i32 s51, 0, 0x18000
	v_add_u32_e32 v153, s51, v148
	s_add_i32 s68, 0, 0x1c000
	ds_read_b128 v[154:157], v153
	ds_read_b128 v[158:161], v153 offset:1024
	ds_read_b128 v[162:165], v153 offset:2048
	ds_read_b128 v[166:169], v153 offset:3072
	v_add_u32_e32 v153, s68, v148
	ds_read_b128 v[170:173], v153
	ds_read_b128 v[174:177], v153 offset:1024
	ds_read_b128 v[178:181], v153 offset:2048
	ds_read_b128 v[182:185], v153 offset:3072
	s_add_u32 s26, s26, 0x80000
	s_addc_u32 s27, s27, 0
	s_mov_b32 m0, s35
	v_lshl_add_u64 v[226:227], s[26:27], 0, v[128:129]
	ds_read_b128 v[186:189], v152 offset:32768
	ds_read_b128 v[194:197], v152 offset:33792
	ds_read_b128 v[198:201], v152 offset:34816
	ds_read_b128 v[202:205], v152 offset:35840
	ds_read_b128 v[206:209], v152 offset:36864
	ds_read_b128 v[210:213], v152 offset:37888
	ds_read_b128 v[214:217], v152 offset:38912
	ds_read_b128 v[218:221], v152 offset:39936
	global_load_lds_dwordx4 v[226:227], off
	v_lshl_add_u64 v[226:227], s[26:27], 0, v[132:133]
	s_mov_b32 m0, s36
	s_nop 0
	global_load_lds_dwordx4 v[226:227], off
	s_waitcnt vmcnt(8)
	s_waitcnt lgkmcnt(0)
	s_barrier
	v_mfma_f32_16x16x32_bf16 v[124:127], v[154:157], v[186:189], v[124:127]
	v_mfma_f32_16x16x32_bf16 v[120:123], v[162:165], v[186:189], v[120:123]
	v_mfma_f32_16x16x32_bf16 v[116:119], v[154:157], v[198:201], v[116:119]
	v_mfma_f32_16x16x32_bf16 v[108:111], v[162:165], v[198:201], v[108:111]
	v_mfma_f32_16x16x32_bf16 v[100:103], v[154:157], v[206:209], v[100:103]
	v_mfma_f32_16x16x32_bf16 v[92:95], v[162:165], v[206:209], v[92:95]
	v_mfma_f32_16x16x32_bf16 v[84:87], v[154:157], v[214:217], v[84:87]
	v_mfma_f32_16x16x32_bf16 v[76:79], v[162:165], v[214:217], v[76:79]
	v_mfma_f32_16x16x32_bf16 v[124:127], v[158:161], v[194:197], v[124:127]
	v_mfma_f32_16x16x32_bf16 v[120:123], v[166:169], v[194:197], v[120:123]
	v_mfma_f32_16x16x32_bf16 v[116:119], v[158:161], v[202:205], v[116:119]
	v_mfma_f32_16x16x32_bf16 v[108:111], v[166:169], v[202:205], v[108:111]
	v_mfma_f32_16x16x32_bf16 v[100:103], v[158:161], v[210:213], v[100:103]
	v_mfma_f32_16x16x32_bf16 v[92:95], v[166:169], v[210:213], v[92:95]
	v_mfma_f32_16x16x32_bf16 v[84:87], v[158:161], v[218:221], v[84:87]
	v_mfma_f32_16x16x32_bf16 v[76:79], v[166:169], v[218:221], v[76:79]
	v_mfma_f32_16x16x32_bf16 v[112:115], v[170:173], v[186:189], v[112:115]
	v_mfma_f32_16x16x32_bf16 v[104:107], v[178:181], v[186:189], v[104:107]
	v_mfma_f32_16x16x32_bf16 v[96:99], v[170:173], v[198:201], v[96:99]
	v_mfma_f32_16x16x32_bf16 v[88:91], v[178:181], v[198:201], v[88:91]
	v_mfma_f32_16x16x32_bf16 v[80:83], v[170:173], v[206:209], v[80:83]
	v_mfma_f32_16x16x32_bf16 v[72:75], v[178:181], v[206:209], v[72:75]
	v_mfma_f32_16x16x32_bf16 v[68:71], v[170:173], v[214:217], v[68:71]
	v_mfma_f32_16x16x32_bf16 v[64:67], v[178:181], v[214:217], v[64:67]
	v_mfma_f32_16x16x32_bf16 v[112:115], v[174:177], v[194:197], v[112:115]
	v_mfma_f32_16x16x32_bf16 v[104:107], v[182:185], v[194:197], v[104:107]
	v_mfma_f32_16x16x32_bf16 v[96:99], v[174:177], v[202:205], v[96:99]
	v_mfma_f32_16x16x32_bf16 v[88:91], v[182:185], v[202:205], v[88:91]
	v_mfma_f32_16x16x32_bf16 v[80:83], v[174:177], v[210:213], v[80:83]
	v_mfma_f32_16x16x32_bf16 v[72:75], v[182:185], v[210:213], v[72:75]
	v_mfma_f32_16x16x32_bf16 v[68:71], v[174:177], v[218:221], v[68:71]
	v_mfma_f32_16x16x32_bf16 v[64:67], v[182:185], v[218:221], v[64:67]
	s_barrier
	s_add_i32 s26, s51, s30
	v_lshl_add_u64 v[144:145], v[144:145], 0, s[8:9]
	s_mov_b32 m0, s26
	ds_read_b128 v[186:189], v152 offset:49152
	ds_read_b128 v[194:197], v152 offset:50176
	ds_read_b128 v[198:201], v152 offset:51200
	ds_read_b128 v[202:205], v152 offset:52224
	ds_read_b128 v[206:209], v152 offset:53248
	ds_read_b128 v[210:213], v152 offset:54272
	ds_read_b128 v[214:217], v152 offset:55296
	ds_read_b128 v[218:221], v152 offset:56320
	global_load_lds_dwordx4 v[144:145], off
	s_add_i32 m0, s26, 0x2000
	s_add_u32 s24, s24, 0x80080
	v_lshl_add_u64 v[144:145], v[190:191], 0, s[8:9]
	s_addc_u32 s25, s25, 0
	s_add_i32 s26, s68, s30
	global_load_lds_dwordx4 v[144:145], off
	v_lshl_add_u64 v[144:145], s[24:25], 0, v[130:131]
	s_mov_b32 m0, s26
	s_nop 0
	global_load_lds_dwordx4 v[144:145], off
	v_lshl_add_u64 v[144:145], s[24:25], 0, v[134:135]
	s_add_i32 m0, s26, 0x2000
	s_nop 0
	global_load_lds_dwordx4 v[144:145], off
	v_lshl_add_u64 v[144:145], v[222:223], 0, s[8:9]
	s_mov_b32 m0, s39
	s_nop 0
	global_load_lds_dwordx4 v[144:145], off
	v_lshl_add_u64 v[144:145], v[224:225], 0, s[8:9]
	s_mov_b32 m0, s40
	s_nop 0
	global_load_lds_dwordx4 v[144:145], off
	s_waitcnt vmcnt(8)
	s_waitcnt lgkmcnt(0)
	s_barrier
	v_mfma_f32_16x16x32_bf16 v[60:63], v[154:157], v[186:189], v[60:63]
	v_mfma_f32_16x16x32_bf16 v[56:59], v[162:165], v[186:189], v[56:59]
	v_mfma_f32_16x16x32_bf16 v[52:55], v[154:157], v[198:201], v[52:55]
	v_mfma_f32_16x16x32_bf16 v[44:47], v[162:165], v[198:201], v[44:47]
	v_mfma_f32_16x16x32_bf16 v[36:39], v[154:157], v[206:209], v[36:39]
	v_mfma_f32_16x16x32_bf16 v[28:31], v[162:165], v[206:209], v[28:31]
	v_mfma_f32_16x16x32_bf16 v[20:23], v[154:157], v[214:217], v[20:23]
	v_mfma_f32_16x16x32_bf16 v[12:15], v[162:165], v[214:217], v[12:15]
	v_mfma_f32_16x16x32_bf16 v[60:63], v[158:161], v[194:197], v[60:63]
	v_mfma_f32_16x16x32_bf16 v[56:59], v[166:169], v[194:197], v[56:59]
	v_mfma_f32_16x16x32_bf16 v[52:55], v[158:161], v[202:205], v[52:55]
	v_mfma_f32_16x16x32_bf16 v[44:47], v[166:169], v[202:205], v[44:47]
	v_mfma_f32_16x16x32_bf16 v[36:39], v[158:161], v[210:213], v[36:39]
	v_mfma_f32_16x16x32_bf16 v[28:31], v[166:169], v[210:213], v[28:31]
	v_mfma_f32_16x16x32_bf16 v[20:23], v[158:161], v[218:221], v[20:23]
	v_mfma_f32_16x16x32_bf16 v[12:15], v[166:169], v[218:221], v[12:15]
	v_mfma_f32_16x16x32_bf16 v[48:51], v[170:173], v[186:189], v[48:51]
	v_mfma_f32_16x16x32_bf16 v[40:43], v[178:181], v[186:189], v[40:43]
	v_mfma_f32_16x16x32_bf16 v[32:35], v[170:173], v[198:201], v[32:35]
	v_mfma_f32_16x16x32_bf16 v[24:27], v[178:181], v[198:201], v[24:27]
	v_mfma_f32_16x16x32_bf16 v[16:19], v[170:173], v[206:209], v[16:19]
	v_mfma_f32_16x16x32_bf16 v[8:11], v[178:181], v[206:209], v[8:11]
	v_mfma_f32_16x16x32_bf16 v[4:7], v[170:173], v[214:217], v[4:7]
	v_mfma_f32_16x16x32_bf16 v[0:3], v[178:181], v[214:217], v[0:3]
	v_mfma_f32_16x16x32_bf16 v[48:51], v[174:177], v[194:197], v[48:51]
	v_mfma_f32_16x16x32_bf16 v[40:43], v[182:185], v[194:197], v[40:43]
	v_mfma_f32_16x16x32_bf16 v[32:35], v[174:177], v[202:205], v[32:35]
	v_mfma_f32_16x16x32_bf16 v[24:27], v[182:185], v[202:205], v[24:27]
	v_mfma_f32_16x16x32_bf16 v[16:19], v[174:177], v[210:213], v[16:19]
	v_mfma_f32_16x16x32_bf16 v[8:11], v[182:185], v[210:213], v[8:11]
	v_mfma_f32_16x16x32_bf16 v[4:7], v[174:177], v[218:221], v[4:7]
	v_mfma_f32_16x16x32_bf16 v[0:3], v[182:185], v[218:221], v[0:3]
	s_barrier
	s_add_i32 s50, s50, 2
	s_add_u32 s22, s22, 0x100
	s_addc_u32 s23, s23, 0
	s_add_u32 s48, s48, 0x100
	s_addc_u32 s49, s49, 0
	s_cmp_gt_u32 s50, 29
	s_cbranch_scc0 .LBB0_216

; #define PG8_STAGE(bufoff, gbase, voff) do { _Pragma("unroll") for (int _i = 0; _i < 2; ++_i) \
;         __builtin_amdgcn_global_load_lds((const unsigned*)((const char*)(gbase) + (voff)[_i]), (LAS unsigned*)(lds + (bufoff) + ldsw + _i * 8192), 16, 0, 0); } while (0)
; #define PG8_LDA(dst, b, h) do { _Pragma("unroll") for (int m = 0; m < 4; ++m) _Pragma("unroll") for (int k = 0; k < 2; ++k) dst[m][k] = *(const LAS bf16x8*)(lds + PG8_SA(b, h) + aoff + m * 2048 + k * 1024); } while (0)
; #define PG8_LDB(dst, b, h) do { _Pragma("unroll") for (int n = 0; n < 2; ++n) _Pragma("unroll") for (int k = 0; k < 2; ++k) dst[n][k] = *(const LAS bf16x8*)(lds + PG8_SB(b, h) + boff + n * 2048 + k * 1024); } while (0)
; #define PG8_WAIT_V(n) asm volatile("s_waitcnt vmcnt(" #n ")" ::: "memory")
; #define PG8_BAR __builtin_amdgcn_s_barrier()
; template <class Epi, class Sched = StaticOrder, class EpiSub = NoSub, bool FAST = false>
; __device__ __forceinline__ void gemm_phase(LAS unsigned char* lds, const Gemm g, const Sched& S, const Epi& E, const EpiSub& ES = EpiSub()) {
;     ...
;         const bool has_next = S.next(ui + 1, nxt);
;         const size_t nko = (has_next && nxt.kb >= 0) ? nxt.kb * ksubB : 0;
;         const char* nA = has_next ? (const char*)g.A + (size_t)nxt.pm * tstepA + (size_t)nxt.pn * g.acs + nko : cA; const char* nB = has_next ? (const char*)g.Bt + (size_t)nxt.pn * tstepB + nko : cB;
;         const int nt = cur.kb < 0 ? ntMain : ntSub;
;         for (int t = 0; t < nt; t += 2) {
;             const bool last = (t == nt - 2);
;             const char* a1 = cA + (size_t)(t + 1) * kstep;
;             const char* a2 = last ? nA : cA + (size_t)(t + 2) * kstep; const char* b2 = last ? nB : cB + (size_t)(t + 2) * kstep;
;             const char* a3 = a2 + kstep; const char* b3 = b2 + kstep;
;             if constexpr (FAST && PG8_SP2) {
;             PG8_LDB(B0, 0, 0); PG8_LDB(B1, 0, 1); PG8_SCHED; PG8_LDA(At, 0, 0); PG8_STAGE(PG8_SA(1, 1), a1 + hstepA, voffA);
;             PG8_WAIT_V(8); PG8_WAIT_L(0); PG8_BAR; PG8_MMA(0, 0, At, B0); PG8_MMA(0, 1, At, B1); PG8_BAR; PG8_SCHED;
;             PG8_LDA(At, 0, 1); PG8_STAGE(PG8_SB(0, 0), b2, voffB); PG8_STAGE(PG8_SB(0, 1), b2 + hstepB, voffB); PG8_STAGE(PG8_SA(0, 0), a2, voffA);
;             PG8_WAIT_V(8); PG8_WAIT_L(0); PG8_BAR; PG8_MMA(1, 0, At, B0); PG8_MMA(1, 1, At, B1); PG8_BAR; PG8_SCHED;
.LBB0_599:
	s_cmp_gt_i32 s8, -1
	s_cselect_b64 s[30:31], -1, 0
	s_and_b64 s[30:31], s[28:29], s[30:31]
	s_lshl_b64 s[36:37], s[8:9], 9
	s_and_b64 s[30:31], s[30:31], exec
	s_cselect_b32 s7, s37, 0
	s_cselect_b32 s33, s36, 0
	s_ashr_i32 s27, s26, 31
	s_lshl_b64 s[30:31], s[26:27], 19
	s_add_u32 s1, s78, s30
	s_addc_u32 s5, s79, s31
	s_add_u32 s30, s1, s33
	s_addc_u32 s31, s5, s7
	s_and_b64 s[36:37], s[28:29], exec
	s_cselect_b32 s1, s31, s41
	s_cselect_b32 s5, s30, s40
	s_ashr_i32 s25, s24, 31
	s_lshl_b64 s[36:37], s[24:25], 19
	s_add_u32 s25, s2, s36
	s_addc_u32 s27, s3, s37
	s_add_u32 s36, s25, s33
	s_addc_u32 s37, s27, s7
	s_and_b64 s[38:39], s[28:29], exec
	s_cselect_b32 s7, s37, s43
	s_cselect_b32 s25, s36, s42
	s_cmp_gt_i32 s0, -1
	s_cselect_b64 s[38:39], -1, 0
	s_cmp_lt_i32 s0, 0
	s_cselect_b32 s27, 16, 4
	s_add_i32 s33, s27, -2
	s_add_u32 s40, s40, 0x40080
	s_addc_u32 s41, s41, 0
	s_add_u32 s48, s42, 0x100
	s_mov_b32 s50, 0
	s_addc_u32 s49, s43, 0
	ds_read_b128 v[100:103], v186
	ds_read_b128 v[112:115], v186 offset:1024
	ds_read_b128 v[124:127], v186 offset:2048
	ds_read_b128 v[136:139], v186 offset:3072
	ds_read_b128 v[144:147], v187
	ds_read_b128 v[148:151], v187 offset:1024
	ds_read_b128 v[152:155], v187 offset:2048
	ds_read_b128 v[170:173], v187 offset:3072
	s_add_i32 s51, s50, 2
	s_add_u32 s42, s40, 0xfffc0080
	s_addc_u32 s43, s41, -1
	s_cmp_eq_u32 s33, s50
	s_cselect_b32 s53, s1, s43
	s_cselect_b32 s52, s5, s42
	s_cselect_b32 s43, s7, s49
	s_cselect_b32 s42, s25, s48
	v_lshl_add_u64 v[190:191], s[40:41], 0, v[164:165]
	s_add_i32 m0, s55, 0xc000
	ds_read_b128 v[174:177], v188
	ds_read_b128 v[178:181], v188 offset:1024
	ds_read_b128 v[194:197], v188 offset:2048
	ds_read_b128 v[198:201], v188 offset:3072
	ds_read_b128 v[202:205], v188 offset:4096
	ds_read_b128 v[206:209], v188 offset:5120
	ds_read_b128 v[210:213], v188 offset:6144
	ds_read_b128 v[214:217], v188 offset:7168
	global_load_lds_dwordx4 v[190:191], off
	v_lshl_add_u64 v[190:191], s[40:41], 0, v[166:167]
	s_add_i32 m0, s55, 0xe000
	s_nop 0
	global_load_lds_dwordx4 v[190:191], off
	s_waitcnt vmcnt(8)
	s_waitcnt lgkmcnt(0)
	s_barrier
	v_mfma_f32_16x16x32_bf16 v[140:143], v[100:103], v[174:177], 0
	v_mfma_f32_16x16x32_bf16 v[132:135], v[124:127], v[174:177], 0
	v_mfma_f32_16x16x32_bf16 v[116:119], v[100:103], v[194:197], 0
	v_mfma_f32_16x16x32_bf16 v[108:111], v[124:127], v[194:197], 0
	v_mfma_f32_16x16x32_bf16 v[92:95], v[100:103], v[202:205], 0
	v_mfma_f32_16x16x32_bf16 v[88:91], v[124:127], v[202:205], 0
	v_mfma_f32_16x16x32_bf16 v[76:79], v[100:103], v[210:213], 0
	v_mfma_f32_16x16x32_bf16 v[72:75], v[124:127], v[210:213], 0
	v_mfma_f32_16x16x32_bf16 v[140:143], v[112:115], v[178:181], v[140:143]
	v_mfma_f32_16x16x32_bf16 v[132:135], v[136:139], v[178:181], v[132:135]
	v_mfma_f32_16x16x32_bf16 v[116:119], v[112:115], v[198:201], v[116:119]
	v_mfma_f32_16x16x32_bf16 v[108:111], v[136:139], v[198:201], v[108:111]
	v_mfma_f32_16x16x32_bf16 v[92:95], v[112:115], v[206:209], v[92:95]
	v_mfma_f32_16x16x32_bf16 v[88:91], v[136:139], v[206:209], v[88:91]
	v_mfma_f32_16x16x32_bf16 v[76:79], v[112:115], v[214:217], v[76:79]
	v_mfma_f32_16x16x32_bf16 v[72:75], v[136:139], v[214:217], v[72:75]
	v_mfma_f32_16x16x32_bf16 v[128:131], v[144:147], v[174:177], 0
	v_mfma_f32_16x16x32_bf16 v[120:123], v[152:155], v[174:177], 0
	v_mfma_f32_16x16x32_bf16 v[104:107], v[144:147], v[194:197], 0
	v_mfma_f32_16x16x32_bf16 v[96:99], v[152:155], v[194:197], 0
	v_mfma_f32_16x16x32_bf16 v[84:87], v[144:147], v[202:205], 0
	v_mfma_f32_16x16x32_bf16 v[80:83], v[152:155], v[202:205], 0
	v_mfma_f32_16x16x32_bf16 v[68:71], v[144:147], v[210:213], 0
	v_mfma_f32_16x16x32_bf16 v[64:67], v[152:155], v[210:213], 0
	v_mfma_f32_16x16x32_bf16 v[128:131], v[148:151], v[178:181], v[128:131]
	v_mfma_f32_16x16x32_bf16 v[120:123], v[170:173], v[178:181], v[120:123]
	v_mfma_f32_16x16x32_bf16 v[104:107], v[148:151], v[198:201], v[104:107]
	v_mfma_f32_16x16x32_bf16 v[96:99], v[170:173], v[198:201], v[96:99]
	v_mfma_f32_16x16x32_bf16 v[84:87], v[148:151], v[206:209], v[84:87]
	v_mfma_f32_16x16x32_bf16 v[80:83], v[170:173], v[206:209], v[80:83]
	v_mfma_f32_16x16x32_bf16 v[68:71], v[148:151], v[214:217], v[68:71]
	v_mfma_f32_16x16x32_bf16 v[64:67], v[170:173], v[214:217], v[64:67]
	s_barrier
	s_add_i32 s50, s75, s54
	v_lshl_add_u64 v[190:191], s[42:43], 0, v[158:159]
	s_mov_b32 m0, s50
	ds_read_b128 v[174:177], v188 offset:16384
	ds_read_b128 v[178:181], v188 offset:17408
	ds_read_b128 v[194:197], v188 offset:18432
	ds_read_b128 v[198:201], v188 offset:19456
	ds_read_b128 v[202:205], v188 offset:20480
	ds_read_b128 v[206:209], v188 offset:21504
	ds_read_b128 v[210:213], v188 offset:22528
	ds_read_b128 v[214:217], v188 offset:23552
	global_load_lds_dwordx4 v[190:191], off
	s_add_i32 m0, s50, 0x2000
	s_add_u32 s70, s42, 0x40000
	v_lshl_add_u64 v[218:219], s[42:43], 0, v[162:163]
	s_addc_u32 s71, s43, 0
	s_add_i32 s50, s80, s54
	global_load_lds_dwordx4 v[218:219], off
	v_lshl_add_u64 v[220:221], s[70:71], 0, v[158:159]
	s_mov_b32 m0, s50
	v_lshl_add_u64 v[222:223], s[52:53], 0, v[160:161]
	global_load_lds_dwordx4 v[220:221], off
	v_lshl_add_u64 v[220:221], s[70:71], 0, v[162:163]
	s_add_i32 m0, s50, 0x2000
	s_nop 0
	global_load_lds_dwordx4 v[220:221], off
	v_lshl_add_u64 v[220:221], s[52:53], 0, v[156:157]
	s_mov_b32 m0, s55
	s_nop 0
	global_load_lds_dwordx4 v[220:221], off
	s_mov_b32 m0, s56
	s_nop 0
	global_load_lds_dwordx4 v[222:223], off
	s_waitcnt vmcnt(8)
	s_waitcnt lgkmcnt(0)
	s_barrier
; #define PG8_STAGE(bufoff, gbase, voff) do { _Pragma("unroll") for (int _i = 0; _i < 2; ++_i) \
;         __builtin_amdgcn_global_load_lds((const unsigned*)((const char*)(gbase) + (voff)[_i]), (LAS unsigned*)(lds + (bufoff) + ldsw + _i * 8192), 16, 0, 0); } while (0)
; #define PG8_LDA(dst, b, h) do { _Pragma("unroll") for (int m = 0; m < 4; ++m) _Pragma("unroll") for (int k = 0; k < 2; ++k) dst[m][k] = *(const LAS bf16x8*)(lds + PG8_SA(b, h) + aoff + m * 2048 + k * 1024); } while (0)
; #define PG8_LDB(dst, b, h) do { _Pragma("unroll") for (int n = 0; n < 2; ++n) _Pragma("unroll") for (int k = 0; k < 2; ++k) dst[n][k] = *(const LAS bf16x8*)(lds + PG8_SB(b, h) + boff + n * 2048 + k * 1024); } while (0)
; #define PG8_MMA(ai, bj, At, Bt) do { __builtin_amdgcn_s_setprio(1); _Pragma("unroll") for (int m = 0; m < 4; ++m) _Pragma("unroll") for (int n = 0; n < 2; ++n) _Pragma("unroll") for (int k = 0; k < 2; ++k) \
;         acc[ai][bj][m][n] = __builtin_amdgcn_mfma_f32_16x16x32_bf16(Bt[n][k], At[m][k], acc[ai][bj][m][n], 0, 0, 0); __builtin_amdgcn_s_setprio(0); } while (0)
; #define PG8_WAIT_V(n) asm volatile("s_waitcnt vmcnt(" #n ")" ::: "memory")
; #define PG8_WAIT_L(n) asm volatile("s_waitcnt lgkmcnt(" #n ")" ::: "memory")
; #define PG8_BAR __builtin_amdgcn_s_barrier()
; #define PG8_SCHED __builtin_amdgcn_sched_barrier(0)
; template <class Epi, class Sched = StaticOrder, class EpiSub = NoSub, bool FAST = false>
; __device__ __forceinline__ void gemm_phase(LAS unsigned char* lds, const Gemm g, const Sched& S, const Epi& E, const EpiSub& ES = EpiSub()) {
;     ...
;             PG8_WAIT_V(8); PG8_WAIT_L(0); PG8_BAR; PG8_MMA(1, 0, At, B0); PG8_MMA(1, 1, At, B1); PG8_BAR; PG8_SCHED;
;             PG8_LDB(B0, 1, 0); PG8_LDB(B1, 1, 1); PG8_SCHED; PG8_LDA(At, 1, 0); PG8_STAGE(PG8_SA(0, 1), a2 + hstepA, voffA);
;             PG8_WAIT_V(8); PG8_WAIT_L(0); PG8_BAR; PG8_MMA(0, 0, At, B0); PG8_MMA(0, 1, At, B1); PG8_BAR; PG8_SCHED;
	v_mfma_f32_16x16x32_bf16 v[60:63], v[100:103], v[174:177], 0
	v_mfma_f32_16x16x32_bf16 v[56:59], v[124:127], v[174:177], 0
	v_mfma_f32_16x16x32_bf16 v[44:47], v[100:103], v[194:197], 0
	v_mfma_f32_16x16x32_bf16 v[40:43], v[124:127], v[194:197], 0
	v_mfma_f32_16x16x32_bf16 v[28:31], v[100:103], v[202:205], 0
	v_mfma_f32_16x16x32_bf16 v[24:27], v[124:127], v[202:205], 0
	v_mfma_f32_16x16x32_bf16 v[12:15], v[100:103], v[210:213], 0
	v_mfma_f32_16x16x32_bf16 v[8:11], v[124:127], v[210:213], 0
	v_mfma_f32_16x16x32_bf16 v[60:63], v[112:115], v[178:181], v[60:63]
	v_mfma_f32_16x16x32_bf16 v[56:59], v[136:139], v[178:181], v[56:59]
	v_mfma_f32_16x16x32_bf16 v[44:47], v[112:115], v[198:201], v[44:47]
	v_mfma_f32_16x16x32_bf16 v[40:43], v[136:139], v[198:201], v[40:43]
	v_mfma_f32_16x16x32_bf16 v[28:31], v[112:115], v[206:209], v[28:31]
	v_mfma_f32_16x16x32_bf16 v[24:27], v[136:139], v[206:209], v[24:27]
	v_mfma_f32_16x16x32_bf16 v[12:15], v[112:115], v[214:217], v[12:15]
	v_mfma_f32_16x16x32_bf16 v[8:11], v[136:139], v[214:217], v[8:11]
	v_mfma_f32_16x16x32_bf16 v[52:55], v[144:147], v[174:177], 0
	v_mfma_f32_16x16x32_bf16 v[48:51], v[152:155], v[174:177], 0
	v_mfma_f32_16x16x32_bf16 v[36:39], v[144:147], v[194:197], 0
	v_mfma_f32_16x16x32_bf16 v[32:35], v[152:155], v[194:197], 0
	v_mfma_f32_16x16x32_bf16 v[20:23], v[144:147], v[202:205], 0
	v_mfma_f32_16x16x32_bf16 v[16:19], v[152:155], v[202:205], 0
	v_mfma_f32_16x16x32_bf16 v[4:7], v[144:147], v[210:213], 0
	v_mfma_f32_16x16x32_bf16 v[0:3], v[152:155], v[210:213], 0
	v_mfma_f32_16x16x32_bf16 v[52:55], v[148:151], v[178:181], v[52:55]
	v_mfma_f32_16x16x32_bf16 v[48:51], v[170:173], v[178:181], v[48:51]
	v_mfma_f32_16x16x32_bf16 v[36:39], v[148:151], v[198:201], v[36:39]
	v_mfma_f32_16x16x32_bf16 v[32:35], v[170:173], v[198:201], v[32:35]
	v_mfma_f32_16x16x32_bf16 v[20:23], v[148:151], v[206:209], v[20:23]
	v_mfma_f32_16x16x32_bf16 v[16:19], v[170:173], v[206:209], v[16:19]
	v_mfma_f32_16x16x32_bf16 v[4:7], v[148:151], v[214:217], v[4:7]
	v_mfma_f32_16x16x32_bf16 v[0:3], v[170:173], v[214:217], v[0:3]
	s_barrier
	s_add_i32 s50, 0, 0x18000
	s_add_i32 s70, 0, 0x1c000
	v_add_u32_e32 v136, s50, v183
	v_add_u32_e32 v170, s70, v183
	ds_read_b128 v[100:103], v136
	ds_read_b128 v[112:115], v136 offset:1024
	ds_read_b128 v[124:127], v136 offset:2048
	ds_read_b128 v[136:139], v136 offset:3072
	ds_read_b128 v[144:147], v170
	ds_read_b128 v[148:151], v170 offset:1024
	ds_read_b128 v[152:155], v170 offset:2048
	ds_read_b128 v[170:173], v170 offset:3072
	s_add_u32 s52, s52, 0x40000
	s_addc_u32 s53, s53, 0
	s_mov_b32 m0, s57
	v_lshl_add_u64 v[224:225], s[52:53], 0, v[156:157]
	ds_read_b128 v[174:177], v188 offset:32768
	ds_read_b128 v[178:181], v188 offset:33792
	ds_read_b128 v[194:197], v188 offset:34816
	ds_read_b128 v[198:201], v188 offset:35840
	ds_read_b128 v[202:205], v188 offset:36864
	ds_read_b128 v[206:209], v188 offset:37888
	ds_read_b128 v[210:213], v188 offset:38912
	ds_read_b128 v[214:217], v188 offset:39936
	global_load_lds_dwordx4 v[224:225], off
	v_lshl_add_u64 v[224:225], s[52:53], 0, v[160:161]
	s_mov_b32 m0, s58
	s_nop 0
	global_load_lds_dwordx4 v[224:225], off
	s_waitcnt vmcnt(8)
	s_waitcnt lgkmcnt(0)
	s_barrier
	v_mfma_f32_16x16x32_bf16 v[140:143], v[100:103], v[174:177], v[140:143]
	v_mfma_f32_16x16x32_bf16 v[132:135], v[124:127], v[174:177], v[132:135]
	v_mfma_f32_16x16x32_bf16 v[116:119], v[100:103], v[194:197], v[116:119]
	v_mfma_f32_16x16x32_bf16 v[108:111], v[124:127], v[194:197], v[108:111]
	v_mfma_f32_16x16x32_bf16 v[92:95], v[100:103], v[202:205], v[92:95]
	v_mfma_f32_16x16x32_bf16 v[88:91], v[124:127], v[202:205], v[88:91]
	v_mfma_f32_16x16x32_bf16 v[76:79], v[100:103], v[210:213], v[76:79]
	v_mfma_f32_16x16x32_bf16 v[72:75], v[124:127], v[210:213], v[72:75]
	v_mfma_f32_16x16x32_bf16 v[140:143], v[112:115], v[178:181], v[140:143]
	v_mfma_f32_16x16x32_bf16 v[132:135], v[136:139], v[178:181], v[132:135]
	v_mfma_f32_16x16x32_bf16 v[116:119], v[112:115], v[198:201], v[116:119]
	v_mfma_f32_16x16x32_bf16 v[108:111], v[136:139], v[198:201], v[108:111]
	v_mfma_f32_16x16x32_bf16 v[92:95], v[112:115], v[206:209], v[92:95]
	v_mfma_f32_16x16x32_bf16 v[88:91], v[136:139], v[206:209], v[88:91]
	v_mfma_f32_16x16x32_bf16 v[76:79], v[112:115], v[214:217], v[76:79]
	v_mfma_f32_16x16x32_bf16 v[72:75], v[136:139], v[214:217], v[72:75]
	v_mfma_f32_16x16x32_bf16 v[128:131], v[144:147], v[174:177], v[128:131]
	v_mfma_f32_16x16x32_bf16 v[120:123], v[152:155], v[174:177], v[120:123]
	v_mfma_f32_16x16x32_bf16 v[104:107], v[144:147], v[194:197], v[104:107]
	v_mfma_f32_16x16x32_bf16 v[96:99], v[152:155], v[194:197], v[96:99]
	v_mfma_f32_16x16x32_bf16 v[84:87], v[144:147], v[202:205], v[84:87]
	v_mfma_f32_16x16x32_bf16 v[80:83], v[152:155], v[202:205], v[80:83]
	v_mfma_f32_16x16x32_bf16 v[68:71], v[144:147], v[210:213], v[68:71]
	v_mfma_f32_16x16x32_bf16 v[64:67], v[152:155], v[210:213], v[64:67]
	v_mfma_f32_16x16x32_bf16 v[128:131], v[148:151], v[178:181], v[128:131]
	v_mfma_f32_16x16x32_bf16 v[120:123], v[170:173], v[178:181], v[120:123]
	v_mfma_f32_16x16x32_bf16 v[104:107], v[148:151], v[198:201], v[104:107]
	v_mfma_f32_16x16x32_bf16 v[96:99], v[170:173], v[198:201], v[96:99]
	v_mfma_f32_16x16x32_bf16 v[84:87], v[148:151], v[206:209], v[84:87]
	v_mfma_f32_16x16x32_bf16 v[80:83], v[170:173], v[206:209], v[80:83]
	v_mfma_f32_16x16x32_bf16 v[68:71], v[148:151], v[214:217], v[68:71]
	v_mfma_f32_16x16x32_bf16 v[64:67], v[170:173], v[214:217], v[64:67]
	s_barrier
; #define PG8_STAGE(bufoff, gbase, voff) do { _Pragma("unroll") for (int _i = 0; _i < 2; ++_i) \
;         __builtin_amdgcn_global_load_lds((const unsigned*)((const char*)(gbase) + (voff)[_i]), (LAS unsigned*)(lds + (bufoff) + ldsw + _i * 8192), 16, 0, 0); } while (0)
; #define PG8_LDA(dst, b, h) do { _Pragma("unroll") for (int m = 0; m < 4; ++m) _Pragma("unroll") for (int k = 0; k < 2; ++k) dst[m][k] = *(const LAS bf16x8*)(lds + PG8_SA(b, h) + aoff + m * 2048 + k * 1024); } while (0)
; #define PG8_LDB(dst, b, h) do { _Pragma("unroll") for (int n = 0; n < 2; ++n) _Pragma("unroll") for (int k = 0; k < 2; ++k) dst[n][k] = *(const LAS bf16x8*)(lds + PG8_SB(b, h) + boff + n * 2048 + k * 1024); } while (0)
; template <class Epi, class Sched = StaticOrder, class EpiSub = NoSub, bool FAST = false>
; __device__ __forceinline__ void gemm_phase(LAS unsigned char* lds, const Gemm g, const Sched& S, const Epi& E, const EpiSub& ES = EpiSub()) {
;     ...
;         for (int t = 0; t < nt; t += 2) {
;             const bool last = (t == nt - 2);
;             const char* a1 = cA + (size_t)(t + 1) * kstep;
;             const char* a2 = last ? nA : cA + (size_t)(t + 2) * kstep; const char* b2 = last ? nB : cB + (size_t)(t + 2) * kstep;
;             const char* a3 = a2 + kstep; const char* b3 = b2 + kstep;
;             if constexpr (FAST && PG8_SP2) {
;             PG8_LDB(B0, 0, 0); PG8_LDB(B1, 0, 1); PG8_SCHED; PG8_LDA(At, 0, 0); PG8_STAGE(PG8_SA(1, 1), a1 + hstepA, voffA);
;             PG8_WAIT_V(8); PG8_WAIT_L(0); PG8_BAR; PG8_MMA(0, 0, At, B0); PG8_MMA(0, 1, At, B1); PG8_BAR; PG8_SCHED;
;             PG8_LDA(At, 0, 1); PG8_STAGE(PG8_SB(0, 0), b2, voffB); PG8_STAGE(PG8_SB(0, 1), b2 + hstepB, voffB); PG8_STAGE(PG8_SA(0, 0), a2, voffA);
;             PG8_WAIT_V(8); PG8_WAIT_L(0); PG8_BAR; PG8_MMA(1, 0, At, B0); PG8_MMA(1, 1, At, B1); PG8_BAR; PG8_SCHED;
;             PG8_LDB(B0, 1, 0); PG8_LDB(B1, 1, 1); PG8_SCHED; PG8_LDA(At, 1, 0); PG8_STAGE(PG8_SA(0, 1), a2 + hstepA, voffA);
;             PG8_WAIT_V(8); PG8_WAIT_L(0); PG8_BAR; PG8_MMA(0, 0, At, B0); PG8_MMA(0, 1, At, B1); PG8_BAR; PG8_SCHED;
;             PG8_LDA(At, 1, 1); PG8_STAGE(PG8_SB(1, 0), b3, voffB); PG8_STAGE(PG8_SB(1, 1), b3 + hstepB, voffB); PG8_STAGE(PG8_SA(1, 0), a3, voffA);
;             PG8_WAIT_V(8); PG8_WAIT_L(0); PG8_BAR; PG8_MMA(1, 0, At, B0); PG8_MMA(1, 1, At, B1); PG8_BAR; PG8_SCHED;
	s_add_i32 s50, s50, s54
	v_lshl_add_u64 v[190:191], v[190:191], 0, s[12:13]
	s_mov_b32 m0, s50
	ds_read_b128 v[174:177], v188 offset:49152
	ds_read_b128 v[178:181], v188 offset:50176
	ds_read_b128 v[194:197], v188 offset:51200
	ds_read_b128 v[198:201], v188 offset:52224
	ds_read_b128 v[202:205], v188 offset:53248
	ds_read_b128 v[206:209], v188 offset:54272
	ds_read_b128 v[210:213], v188 offset:55296
	ds_read_b128 v[214:217], v188 offset:56320
	global_load_lds_dwordx4 v[190:191], off
	s_add_i32 m0, s50, 0x2000
	s_add_u32 s42, s42, 0x40080
	v_lshl_add_u64 v[190:191], v[218:219], 0, s[12:13]
	s_addc_u32 s43, s43, 0
	s_add_i32 s50, s70, s54
	global_load_lds_dwordx4 v[190:191], off
	v_lshl_add_u64 v[190:191], s[42:43], 0, v[158:159]
	s_mov_b32 m0, s50
	s_nop 0
	global_load_lds_dwordx4 v[190:191], off
	v_lshl_add_u64 v[190:191], s[42:43], 0, v[162:163]
	s_add_i32 m0, s50, 0x2000
	s_nop 0
	global_load_lds_dwordx4 v[190:191], off
	v_lshl_add_u64 v[190:191], v[220:221], 0, s[12:13]
	s_mov_b32 m0, s69
	s_nop 0
	global_load_lds_dwordx4 v[190:191], off
	v_lshl_add_u64 v[190:191], v[222:223], 0, s[12:13]
	s_mov_b32 m0, s74
	s_nop 0
	global_load_lds_dwordx4 v[190:191], off
	s_waitcnt vmcnt(8)
	s_waitcnt lgkmcnt(0)
	s_barrier
	v_mfma_f32_16x16x32_bf16 v[60:63], v[100:103], v[174:177], v[60:63]
	v_mfma_f32_16x16x32_bf16 v[56:59], v[124:127], v[174:177], v[56:59]
	v_mfma_f32_16x16x32_bf16 v[44:47], v[100:103], v[194:197], v[44:47]
	v_mfma_f32_16x16x32_bf16 v[40:43], v[124:127], v[194:197], v[40:43]
	v_mfma_f32_16x16x32_bf16 v[28:31], v[100:103], v[202:205], v[28:31]
	v_mfma_f32_16x16x32_bf16 v[24:27], v[124:127], v[202:205], v[24:27]
	v_mfma_f32_16x16x32_bf16 v[12:15], v[100:103], v[210:213], v[12:15]
	v_mfma_f32_16x16x32_bf16 v[8:11], v[124:127], v[210:213], v[8:11]
	v_mfma_f32_16x16x32_bf16 v[60:63], v[112:115], v[178:181], v[60:63]
	v_mfma_f32_16x16x32_bf16 v[56:59], v[136:139], v[178:181], v[56:59]
	v_mfma_f32_16x16x32_bf16 v[44:47], v[112:115], v[198:201], v[44:47]
	v_mfma_f32_16x16x32_bf16 v[40:43], v[136:139], v[198:201], v[40:43]
	v_mfma_f32_16x16x32_bf16 v[28:31], v[112:115], v[206:209], v[28:31]
	v_mfma_f32_16x16x32_bf16 v[24:27], v[136:139], v[206:209], v[24:27]
	v_mfma_f32_16x16x32_bf16 v[12:15], v[112:115], v[214:217], v[12:15]
	v_mfma_f32_16x16x32_bf16 v[8:11], v[136:139], v[214:217], v[8:11]
	v_mfma_f32_16x16x32_bf16 v[52:55], v[144:147], v[174:177], v[52:55]
	v_mfma_f32_16x16x32_bf16 v[48:51], v[152:155], v[174:177], v[48:51]
	v_mfma_f32_16x16x32_bf16 v[36:39], v[144:147], v[194:197], v[36:39]
	v_mfma_f32_16x16x32_bf16 v[32:35], v[152:155], v[194:197], v[32:35]
	v_mfma_f32_16x16x32_bf16 v[20:23], v[144:147], v[202:205], v[20:23]
	v_mfma_f32_16x16x32_bf16 v[16:19], v[152:155], v[202:205], v[16:19]
	v_mfma_f32_16x16x32_bf16 v[4:7], v[144:147], v[210:213], v[4:7]
	v_mfma_f32_16x16x32_bf16 v[0:3], v[152:155], v[210:213], v[0:3]
	v_mfma_f32_16x16x32_bf16 v[52:55], v[148:151], v[178:181], v[52:55]
	v_mfma_f32_16x16x32_bf16 v[48:51], v[170:173], v[178:181], v[48:51]
	v_mfma_f32_16x16x32_bf16 v[36:39], v[148:151], v[198:201], v[36:39]
	v_mfma_f32_16x16x32_bf16 v[32:35], v[170:173], v[198:201], v[32:35]
	v_mfma_f32_16x16x32_bf16 v[20:23], v[148:151], v[206:209], v[20:23]
	v_mfma_f32_16x16x32_bf16 v[16:19], v[170:173], v[206:209], v[16:19]
	v_mfma_f32_16x16x32_bf16 v[4:7], v[148:151], v[214:217], v[4:7]
	v_mfma_f32_16x16x32_bf16 v[0:3], v[170:173], v[214:217], v[0:3]
	s_barrier
	s_add_u32 s40, s40, 0x100
	s_addc_u32 s41, s41, 0
	s_add_u32 s48, s48, 0x100
	s_addc_u32 s49, s49, 0
	s_cmp_ge_u32 s51, s27
	s_mov_b32 s50, s51
	s_cbranch_scc1 .Lkpeel_600_exit
.LBB0_600:
	ds_read_b128 v[100:103], v186
	ds_read_b128 v[112:115], v186 offset:1024
	ds_read_b128 v[124:127], v186 offset:2048
	ds_read_b128 v[136:139], v186 offset:3072
	ds_read_b128 v[144:147], v187
	ds_read_b128 v[148:151], v187 offset:1024
	ds_read_b128 v[152:155], v187 offset:2048
	ds_read_b128 v[170:173], v187 offset:3072
	s_add_i32 s51, s50, 2
	s_add_u32 s42, s40, 0xfffc0080
	s_addc_u32 s43, s41, -1
	s_cmp_eq_u32 s33, s50
	s_cselect_b32 s53, s1, s43
	s_cselect_b32 s52, s5, s42
	s_cselect_b32 s43, s7, s49
	s_cselect_b32 s42, s25, s48
	v_lshl_add_u64 v[190:191], s[40:41], 0, v[164:165]
	s_add_i32 m0, s55, 0xc000
	ds_read_b128 v[174:177], v188
	ds_read_b128 v[178:181], v188 offset:1024
	ds_read_b128 v[194:197], v188 offset:2048
	ds_read_b128 v[198:201], v188 offset:3072
	ds_read_b128 v[202:205], v188 offset:4096
	ds_read_b128 v[206:209], v188 offset:5120
	ds_read_b128 v[210:213], v188 offset:6144
	ds_read_b128 v[214:217], v188 offset:7168
	global_load_lds_dwordx4 v[190:191], off
	v_lshl_add_u64 v[190:191], s[40:41], 0, v[166:167]
	s_add_i32 m0, s55, 0xe000
	s_nop 0
	global_load_lds_dwordx4 v[190:191], off
	s_waitcnt vmcnt(8)
	s_waitcnt lgkmcnt(0)
	s_barrier
; #define PG8_STAGE(bufoff, gbase, voff) do { _Pragma("unroll") for (int _i = 0; _i < 2; ++_i) \
;         __builtin_amdgcn_global_load_lds((const unsigned*)((const char*)(gbase) + (voff)[_i]), (LAS unsigned*)(lds + (bufoff) + ldsw + _i * 8192), 16, 0, 0); } while (0)
; #define PG8_LDA(dst, b, h) do { _Pragma("unroll") for (int m = 0; m < 4; ++m) _Pragma("unroll") for (int k = 0; k < 2; ++k) dst[m][k] = *(const LAS bf16x8*)(lds + PG8_SA(b, h) + aoff + m * 2048 + k * 1024); } while (0)
; #define PG8_MMA(ai, bj, At, Bt) do { __builtin_amdgcn_s_setprio(1); _Pragma("unroll") for (int m = 0; m < 4; ++m) _Pragma("unroll") for (int n = 0; n < 2; ++n) _Pragma("unroll") for (int k = 0; k < 2; ++k) \
;         acc[ai][bj][m][n] = __builtin_amdgcn_mfma_f32_16x16x32_bf16(Bt[n][k], At[m][k], acc[ai][bj][m][n], 0, 0, 0); __builtin_amdgcn_s_setprio(0); } while (0)
; #define PG8_WAIT_V(n) asm volatile("s_waitcnt vmcnt(" #n ")" ::: "memory")
; #define PG8_WAIT_L(n) asm volatile("s_waitcnt lgkmcnt(" #n ")" ::: "memory")
; #define PG8_BAR __builtin_amdgcn_s_barrier()
; #define PG8_SCHED __builtin_amdgcn_sched_barrier(0)
; template <class Epi, class Sched = StaticOrder, class EpiSub = NoSub, bool FAST = false>
; __device__ __forceinline__ void gemm_phase(LAS unsigned char* lds, const Gemm g, const Sched& S, const Epi& E, const EpiSub& ES = EpiSub()) {
;     ...
;             PG8_WAIT_V(8); PG8_WAIT_L(0); PG8_BAR; PG8_MMA(0, 0, At, B0); PG8_MMA(0, 1, At, B1); PG8_BAR; PG8_SCHED;
;             PG8_LDA(At, 0, 1); PG8_STAGE(PG8_SB(0, 0), b2, voffB); PG8_STAGE(PG8_SB(0, 1), b2 + hstepB, voffB); PG8_STAGE(PG8_SA(0, 0), a2, voffA);
;             PG8_WAIT_V(8); PG8_WAIT_L(0); PG8_BAR; PG8_MMA(1, 0, At, B0); PG8_MMA(1, 1, At, B1); PG8_BAR; PG8_SCHED;
	v_mfma_f32_16x16x32_bf16 v[140:143], v[100:103], v[174:177], v[140:143]
	v_mfma_f32_16x16x32_bf16 v[132:135], v[124:127], v[174:177], v[132:135]
	v_mfma_f32_16x16x32_bf16 v[116:119], v[100:103], v[194:197], v[116:119]
	v_mfma_f32_16x16x32_bf16 v[108:111], v[124:127], v[194:197], v[108:111]
	v_mfma_f32_16x16x32_bf16 v[92:95], v[100:103], v[202:205], v[92:95]
	v_mfma_f32_16x16x32_bf16 v[88:91], v[124:127], v[202:205], v[88:91]
	v_mfma_f32_16x16x32_bf16 v[76:79], v[100:103], v[210:213], v[76:79]
	v_mfma_f32_16x16x32_bf16 v[72:75], v[124:127], v[210:213], v[72:75]
	v_mfma_f32_16x16x32_bf16 v[140:143], v[112:115], v[178:181], v[140:143]
	v_mfma_f32_16x16x32_bf16 v[132:135], v[136:139], v[178:181], v[132:135]
	v_mfma_f32_16x16x32_bf16 v[116:119], v[112:115], v[198:201], v[116:119]
	v_mfma_f32_16x16x32_bf16 v[108:111], v[136:139], v[198:201], v[108:111]
	v_mfma_f32_16x16x32_bf16 v[92:95], v[112:115], v[206:209], v[92:95]
	v_mfma_f32_16x16x32_bf16 v[88:91], v[136:139], v[206:209], v[88:91]
	v_mfma_f32_16x16x32_bf16 v[76:79], v[112:115], v[214:217], v[76:79]
	v_mfma_f32_16x16x32_bf16 v[72:75], v[136:139], v[214:217], v[72:75]
	v_mfma_f32_16x16x32_bf16 v[128:131], v[144:147], v[174:177], v[128:131]
	v_mfma_f32_16x16x32_bf16 v[120:123], v[152:155], v[174:177], v[120:123]
	v_mfma_f32_16x16x32_bf16 v[104:107], v[144:147], v[194:197], v[104:107]
	v_mfma_f32_16x16x32_bf16 v[96:99], v[152:155], v[194:197], v[96:99]
	v_mfma_f32_16x16x32_bf16 v[84:87], v[144:147], v[202:205], v[84:87]
	v_mfma_f32_16x16x32_bf16 v[80:83], v[152:155], v[202:205], v[80:83]
	v_mfma_f32_16x16x32_bf16 v[68:71], v[144:147], v[210:213], v[68:71]
	v_mfma_f32_16x16x32_bf16 v[64:67], v[152:155], v[210:213], v[64:67]
	v_mfma_f32_16x16x32_bf16 v[128:131], v[148:151], v[178:181], v[128:131]
	v_mfma_f32_16x16x32_bf16 v[120:123], v[170:173], v[178:181], v[120:123]
	v_mfma_f32_16x16x32_bf16 v[104:107], v[148:151], v[198:201], v[104:107]
	v_mfma_f32_16x16x32_bf16 v[96:99], v[170:173], v[198:201], v[96:99]
	v_mfma_f32_16x16x32_bf16 v[84:87], v[148:151], v[206:209], v[84:87]
	v_mfma_f32_16x16x32_bf16 v[80:83], v[170:173], v[206:209], v[80:83]
	v_mfma_f32_16x16x32_bf16 v[68:71], v[148:151], v[214:217], v[68:71]
	v_mfma_f32_16x16x32_bf16 v[64:67], v[170:173], v[214:217], v[64:67]
	s_barrier
	s_add_i32 s50, s75, s54
	v_lshl_add_u64 v[190:191], s[42:43], 0, v[158:159]
	s_mov_b32 m0, s50
	ds_read_b128 v[174:177], v188 offset:16384
	ds_read_b128 v[178:181], v188 offset:17408
	ds_read_b128 v[194:197], v188 offset:18432
	ds_read_b128 v[198:201], v188 offset:19456
	ds_read_b128 v[202:205], v188 offset:20480
	ds_read_b128 v[206:209], v188 offset:21504
	ds_read_b128 v[210:213], v188 offset:22528
	ds_read_b128 v[214:217], v188 offset:23552
	global_load_lds_dwordx4 v[190:191], off
	s_add_i32 m0, s50, 0x2000
	s_add_u32 s70, s42, 0x40000
	v_lshl_add_u64 v[218:219], s[42:43], 0, v[162:163]
	s_addc_u32 s71, s43, 0
	s_add_i32 s50, s80, s54
	global_load_lds_dwordx4 v[218:219], off
	v_lshl_add_u64 v[220:221], s[70:71], 0, v[158:159]
	s_mov_b32 m0, s50
	v_lshl_add_u64 v[222:223], s[52:53], 0, v[160:161]
	global_load_lds_dwordx4 v[220:221], off
	v_lshl_add_u64 v[220:221], s[70:71], 0, v[162:163]
	s_add_i32 m0, s50, 0x2000
	s_nop 0
	global_load_lds_dwordx4 v[220:221], off
	v_lshl_add_u64 v[220:221], s[52:53], 0, v[156:157]
	s_mov_b32 m0, s55
	s_nop 0
	global_load_lds_dwordx4 v[220:221], off
	s_mov_b32 m0, s56
	s_nop 0
	global_load_lds_dwordx4 v[222:223], off
	s_waitcnt vmcnt(8)
	s_waitcnt lgkmcnt(0)
	s_barrier
	v_mfma_f32_16x16x32_bf16 v[60:63], v[100:103], v[174:177], v[60:63]
	v_mfma_f32_16x16x32_bf16 v[56:59], v[124:127], v[174:177], v[56:59]
	v_mfma_f32_16x16x32_bf16 v[44:47], v[100:103], v[194:197], v[44:47]
	v_mfma_f32_16x16x32_bf16 v[40:43], v[124:127], v[194:197], v[40:43]
	v_mfma_f32_16x16x32_bf16 v[28:31], v[100:103], v[202:205], v[28:31]
	v_mfma_f32_16x16x32_bf16 v[24:27], v[124:127], v[202:205], v[24:27]
	v_mfma_f32_16x16x32_bf16 v[12:15], v[100:103], v[210:213], v[12:15]
	v_mfma_f32_16x16x32_bf16 v[8:11], v[124:127], v[210:213], v[8:11]
	v_mfma_f32_16x16x32_bf16 v[60:63], v[112:115], v[178:181], v[60:63]
	v_mfma_f32_16x16x32_bf16 v[56:59], v[136:139], v[178:181], v[56:59]
	v_mfma_f32_16x16x32_bf16 v[44:47], v[112:115], v[198:201], v[44:47]
	v_mfma_f32_16x16x32_bf16 v[40:43], v[136:139], v[198:201], v[40:43]
	v_mfma_f32_16x16x32_bf16 v[28:31], v[112:115], v[206:209], v[28:31]
	v_mfma_f32_16x16x32_bf16 v[24:27], v[136:139], v[206:209], v[24:27]
	v_mfma_f32_16x16x32_bf16 v[12:15], v[112:115], v[214:217], v[12:15]
	v_mfma_f32_16x16x32_bf16 v[8:11], v[136:139], v[214:217], v[8:11]
	v_mfma_f32_16x16x32_bf16 v[52:55], v[144:147], v[174:177], v[52:55]
	v_mfma_f32_16x16x32_bf16 v[48:51], v[152:155], v[174:177], v[48:51]
	v_mfma_f32_16x16x32_bf16 v[36:39], v[144:147], v[194:197], v[36:39]
	v_mfma_f32_16x16x32_bf16 v[32:35], v[152:155], v[194:197], v[32:35]
	v_mfma_f32_16x16x32_bf16 v[20:23], v[144:147], v[202:205], v[20:23]
	v_mfma_f32_16x16x32_bf16 v[16:19], v[152:155], v[202:205], v[16:19]
	v_mfma_f32_16x16x32_bf16 v[4:7], v[144:147], v[210:213], v[4:7]
	v_mfma_f32_16x16x32_bf16 v[0:3], v[152:155], v[210:213], v[0:3]
	v_mfma_f32_16x16x32_bf16 v[52:55], v[148:151], v[178:181], v[52:55]
	v_mfma_f32_16x16x32_bf16 v[48:51], v[170:173], v[178:181], v[48:51]
	v_mfma_f32_16x16x32_bf16 v[36:39], v[148:151], v[198:201], v[36:39]
	v_mfma_f32_16x16x32_bf16 v[32:35], v[170:173], v[198:201], v[32:35]
	v_mfma_f32_16x16x32_bf16 v[20:23], v[148:151], v[206:209], v[20:23]
	v_mfma_f32_16x16x32_bf16 v[16:19], v[170:173], v[206:209], v[16:19]
	v_mfma_f32_16x16x32_bf16 v[4:7], v[148:151], v[214:217], v[4:7]
	v_mfma_f32_16x16x32_bf16 v[0:3], v[170:173], v[214:217], v[0:3]
	s_barrier
; #define PG8_STAGE(bufoff, gbase, voff) do { _Pragma("unroll") for (int _i = 0; _i < 2; ++_i) \
;         __builtin_amdgcn_global_load_lds((const unsigned*)((const char*)(gbase) + (voff)[_i]), (LAS unsigned*)(lds + (bufoff) + ldsw + _i * 8192), 16, 0, 0); } while (0)
; #define PG8_LDA(dst, b, h) do { _Pragma("unroll") for (int m = 0; m < 4; ++m) _Pragma("unroll") for (int k = 0; k < 2; ++k) dst[m][k] = *(const LAS bf16x8*)(lds + PG8_SA(b, h) + aoff + m * 2048 + k * 1024); } while (0)
; #define PG8_LDB(dst, b, h) do { _Pragma("unroll") for (int n = 0; n < 2; ++n) _Pragma("unroll") for (int k = 0; k < 2; ++k) dst[n][k] = *(const LAS bf16x8*)(lds + PG8_SB(b, h) + boff + n * 2048 + k * 1024); } while (0)
; #define PG8_MMA(ai, bj, At, Bt) do { __builtin_amdgcn_s_setprio(1); _Pragma("unroll") for (int m = 0; m < 4; ++m) _Pragma("unroll") for (int n = 0; n < 2; ++n) _Pragma("unroll") for (int k = 0; k < 2; ++k) \
;         acc[ai][bj][m][n] = __builtin_amdgcn_mfma_f32_16x16x32_bf16(Bt[n][k], At[m][k], acc[ai][bj][m][n], 0, 0, 0); __builtin_amdgcn_s_setprio(0); } while (0)
; #define PG8_WAIT_V(n) asm volatile("s_waitcnt vmcnt(" #n ")" ::: "memory")
; #define PG8_WAIT_L(n) asm volatile("s_waitcnt lgkmcnt(" #n ")" ::: "memory")
; #define PG8_BAR __builtin_amdgcn_s_barrier()
; #define PG8_SCHED __builtin_amdgcn_sched_barrier(0)
; template <class Epi, class Sched = StaticOrder, class EpiSub = NoSub, bool FAST = false>
; __device__ __forceinline__ void gemm_phase(LAS unsigned char* lds, const Gemm g, const Sched& S, const Epi& E, const EpiSub& ES = EpiSub()) {
;     ...
;             PG8_LDB(B0, 1, 0); PG8_LDB(B1, 1, 1); PG8_SCHED; PG8_LDA(At, 1, 0); PG8_STAGE(PG8_SA(0, 1), a2 + hstepA, voffA);
;             PG8_WAIT_V(8); PG8_WAIT_L(0); PG8_BAR; PG8_MMA(0, 0, At, B0); PG8_MMA(0, 1, At, B1); PG8_BAR; PG8_SCHED;
;             PG8_LDA(At, 1, 1); PG8_STAGE(PG8_SB(1, 0), b3, voffB); PG8_STAGE(PG8_SB(1, 1), b3 + hstepB, voffB); PG8_STAGE(PG8_SA(1, 0), a3, voffA);
;             PG8_WAIT_V(8); PG8_WAIT_L(0); PG8_BAR; PG8_MMA(1, 0, At, B0); PG8_MMA(1, 1, At, B1); PG8_BAR; PG8_SCHED;
	s_add_i32 s50, 0, 0x18000
	s_add_i32 s70, 0, 0x1c000
	v_add_u32_e32 v136, s50, v183
	v_add_u32_e32 v170, s70, v183
	ds_read_b128 v[100:103], v136
	ds_read_b128 v[112:115], v136 offset:1024
	ds_read_b128 v[124:127], v136 offset:2048
	ds_read_b128 v[136:139], v136 offset:3072
	ds_read_b128 v[144:147], v170
	ds_read_b128 v[148:151], v170 offset:1024
	ds_read_b128 v[152:155], v170 offset:2048
	ds_read_b128 v[170:173], v170 offset:3072
	s_add_u32 s52, s52, 0x40000
	s_addc_u32 s53, s53, 0
	s_mov_b32 m0, s57
	v_lshl_add_u64 v[224:225], s[52:53], 0, v[156:157]
	ds_read_b128 v[174:177], v188 offset:32768
	ds_read_b128 v[178:181], v188 offset:33792
	ds_read_b128 v[194:197], v188 offset:34816
	ds_read_b128 v[198:201], v188 offset:35840
	ds_read_b128 v[202:205], v188 offset:36864
	ds_read_b128 v[206:209], v188 offset:37888
	ds_read_b128 v[210:213], v188 offset:38912
	ds_read_b128 v[214:217], v188 offset:39936
	global_load_lds_dwordx4 v[224:225], off
	v_lshl_add_u64 v[224:225], s[52:53], 0, v[160:161]
	s_mov_b32 m0, s58
	s_nop 0
	global_load_lds_dwordx4 v[224:225], off
	s_waitcnt vmcnt(8)
	s_waitcnt lgkmcnt(0)
	s_barrier
	v_mfma_f32_16x16x32_bf16 v[140:143], v[100:103], v[174:177], v[140:143]
	v_mfma_f32_16x16x32_bf16 v[132:135], v[124:127], v[174:177], v[132:135]
	v_mfma_f32_16x16x32_bf16 v[116:119], v[100:103], v[194:197], v[116:119]
	v_mfma_f32_16x16x32_bf16 v[108:111], v[124:127], v[194:197], v[108:111]
	v_mfma_f32_16x16x32_bf16 v[92:95], v[100:103], v[202:205], v[92:95]
	v_mfma_f32_16x16x32_bf16 v[88:91], v[124:127], v[202:205], v[88:91]
	v_mfma_f32_16x16x32_bf16 v[76:79], v[100:103], v[210:213], v[76:79]
	v_mfma_f32_16x16x32_bf16 v[72:75], v[124:127], v[210:213], v[72:75]
	v_mfma_f32_16x16x32_bf16 v[140:143], v[112:115], v[178:181], v[140:143]
	v_mfma_f32_16x16x32_bf16 v[132:135], v[136:139], v[178:181], v[132:135]
	v_mfma_f32_16x16x32_bf16 v[116:119], v[112:115], v[198:201], v[116:119]
	v_mfma_f32_16x16x32_bf16 v[108:111], v[136:139], v[198:201], v[108:111]
	v_mfma_f32_16x16x32_bf16 v[92:95], v[112:115], v[206:209], v[92:95]
	v_mfma_f32_16x16x32_bf16 v[88:91], v[136:139], v[206:209], v[88:91]
	v_mfma_f32_16x16x32_bf16 v[76:79], v[112:115], v[214:217], v[76:79]
	v_mfma_f32_16x16x32_bf16 v[72:75], v[136:139], v[214:217], v[72:75]
	v_mfma_f32_16x16x32_bf16 v[128:131], v[144:147], v[174:177], v[128:131]
	v_mfma_f32_16x16x32_bf16 v[120:123], v[152:155], v[174:177], v[120:123]
	v_mfma_f32_16x16x32_bf16 v[104:107], v[144:147], v[194:197], v[104:107]
	v_mfma_f32_16x16x32_bf16 v[96:99], v[152:155], v[194:197], v[96:99]
	v_mfma_f32_16x16x32_bf16 v[84:87], v[144:147], v[202:205], v[84:87]
	v_mfma_f32_16x16x32_bf16 v[80:83], v[152:155], v[202:205], v[80:83]
	v_mfma_f32_16x16x32_bf16 v[68:71], v[144:147], v[210:213], v[68:71]
	v_mfma_f32_16x16x32_bf16 v[64:67], v[152:155], v[210:213], v[64:67]
	v_mfma_f32_16x16x32_bf16 v[128:131], v[148:151], v[178:181], v[128:131]
	v_mfma_f32_16x16x32_bf16 v[120:123], v[170:173], v[178:181], v[120:123]
	v_mfma_f32_16x16x32_bf16 v[104:107], v[148:151], v[198:201], v[104:107]
	v_mfma_f32_16x16x32_bf16 v[96:99], v[170:173], v[198:201], v[96:99]
	v_mfma_f32_16x16x32_bf16 v[84:87], v[148:151], v[206:209], v[84:87]
	v_mfma_f32_16x16x32_bf16 v[80:83], v[170:173], v[206:209], v[80:83]
	v_mfma_f32_16x16x32_bf16 v[68:71], v[148:151], v[214:217], v[68:71]
	v_mfma_f32_16x16x32_bf16 v[64:67], v[170:173], v[214:217], v[64:67]
	s_barrier
	s_add_i32 s50, s50, s54
	v_lshl_add_u64 v[190:191], v[190:191], 0, s[12:13]
	s_mov_b32 m0, s50
	ds_read_b128 v[174:177], v188 offset:49152
	ds_read_b128 v[178:181], v188 offset:50176
	ds_read_b128 v[194:197], v188 offset:51200
	ds_read_b128 v[198:201], v188 offset:52224
	ds_read_b128 v[202:205], v188 offset:53248
	ds_read_b128 v[206:209], v188 offset:54272
	ds_read_b128 v[210:213], v188 offset:55296
	ds_read_b128 v[214:217], v188 offset:56320
	global_load_lds_dwordx4 v[190:191], off
	s_add_i32 m0, s50, 0x2000
	s_add_u32 s42, s42, 0x40080
	v_lshl_add_u64 v[190:191], v[218:219], 0, s[12:13]
	s_addc_u32 s43, s43, 0
	s_add_i32 s50, s70, s54
	global_load_lds_dwordx4 v[190:191], off
	v_lshl_add_u64 v[190:191], s[42:43], 0, v[158:159]
	s_mov_b32 m0, s50
	s_nop 0
	global_load_lds_dwordx4 v[190:191], off
	v_lshl_add_u64 v[190:191], s[42:43], 0, v[162:163]
	s_add_i32 m0, s50, 0x2000
	s_nop 0
	global_load_lds_dwordx4 v[190:191], off
	v_lshl_add_u64 v[190:191], v[220:221], 0, s[12:13]
	s_mov_b32 m0, s69
	s_nop 0
	global_load_lds_dwordx4 v[190:191], off
	v_lshl_add_u64 v[190:191], v[222:223], 0, s[12:13]
	s_mov_b32 m0, s74
	s_nop 0
	global_load_lds_dwordx4 v[190:191], off
	s_waitcnt vmcnt(8)
	s_waitcnt lgkmcnt(0)
	s_barrier
	v_mfma_f32_16x16x32_bf16 v[60:63], v[100:103], v[174:177], v[60:63]
	v_mfma_f32_16x16x32_bf16 v[56:59], v[124:127], v[174:177], v[56:59]
	v_mfma_f32_16x16x32_bf16 v[44:47], v[100:103], v[194:197], v[44:47]
	v_mfma_f32_16x16x32_bf16 v[40:43], v[124:127], v[194:197], v[40:43]
	v_mfma_f32_16x16x32_bf16 v[28:31], v[100:103], v[202:205], v[28:31]
	v_mfma_f32_16x16x32_bf16 v[24:27], v[124:127], v[202:205], v[24:27]
	v_mfma_f32_16x16x32_bf16 v[12:15], v[100:103], v[210:213], v[12:15]
	v_mfma_f32_16x16x32_bf16 v[8:11], v[124:127], v[210:213], v[8:11]
	v_mfma_f32_16x16x32_bf16 v[60:63], v[112:115], v[178:181], v[60:63]
	v_mfma_f32_16x16x32_bf16 v[56:59], v[136:139], v[178:181], v[56:59]
	v_mfma_f32_16x16x32_bf16 v[44:47], v[112:115], v[198:201], v[44:47]
	v_mfma_f32_16x16x32_bf16 v[40:43], v[136:139], v[198:201], v[40:43]
	v_mfma_f32_16x16x32_bf16 v[28:31], v[112:115], v[206:209], v[28:31]
	v_mfma_f32_16x16x32_bf16 v[24:27], v[136:139], v[206:209], v[24:27]
	v_mfma_f32_16x16x32_bf16 v[12:15], v[112:115], v[214:217], v[12:15]
	v_mfma_f32_16x16x32_bf16 v[8:11], v[136:139], v[214:217], v[8:11]
	v_mfma_f32_16x16x32_bf16 v[52:55], v[144:147], v[174:177], v[52:55]
	v_mfma_f32_16x16x32_bf16 v[48:51], v[152:155], v[174:177], v[48:51]
	v_mfma_f32_16x16x32_bf16 v[36:39], v[144:147], v[194:197], v[36:39]
	v_mfma_f32_16x16x32_bf16 v[32:35], v[152:155], v[194:197], v[32:35]
	v_mfma_f32_16x16x32_bf16 v[20:23], v[144:147], v[202:205], v[20:23]
	v_mfma_f32_16x16x32_bf16 v[16:19], v[152:155], v[202:205], v[16:19]
	v_mfma_f32_16x16x32_bf16 v[4:7], v[144:147], v[210:213], v[4:7]
	v_mfma_f32_16x16x32_bf16 v[0:3], v[152:155], v[210:213], v[0:3]
	v_mfma_f32_16x16x32_bf16 v[52:55], v[148:151], v[178:181], v[52:55]
	v_mfma_f32_16x16x32_bf16 v[48:51], v[170:173], v[178:181], v[48:51]
	v_mfma_f32_16x16x32_bf16 v[36:39], v[148:151], v[198:201], v[36:39]
	v_mfma_f32_16x16x32_bf16 v[32:35], v[170:173], v[198:201], v[32:35]
	v_mfma_f32_16x16x32_bf16 v[20:23], v[148:151], v[206:209], v[20:23]
	v_mfma_f32_16x16x32_bf16 v[16:19], v[170:173], v[206:209], v[16:19]
	v_mfma_f32_16x16x32_bf16 v[4:7], v[148:151], v[214:217], v[4:7]
	v_mfma_f32_16x16x32_bf16 v[0:3], v[170:173], v[214:217], v[0:3]
	s_barrier
	s_add_u32 s40, s40, 0x100
	s_addc_u32 s41, s41, 0
	s_add_u32 s48, s48, 0x100
	s_addc_u32 s49, s49, 0
	s_cmp_ge_u32 s51, s27
	s_mov_b32 s50, s51
	s_cbranch_scc0 .LBB0_600

; #define PG8_STAGE(bufoff, gbase, voff) do { _Pragma("unroll") for (int _i = 0; _i < 2; ++_i) \
;         __builtin_amdgcn_global_load_lds((const unsigned*)((const char*)(gbase) + (voff)[_i]), (LAS unsigned*)(lds + (bufoff) + ldsw + _i * 8192), 16, 0, 0); } while (0)
; #define PG8_LDA(dst, b, h) do { _Pragma("unroll") for (int m = 0; m < 4; ++m) _Pragma("unroll") for (int k = 0; k < 2; ++k) dst[m][k] = *(const LAS bf16x8*)(lds + PG8_SA(b, h) + aoff + m * 2048 + k * 1024); } while (0)
; #define PG8_LDB(dst, b, h) do { _Pragma("unroll") for (int n = 0; n < 2; ++n) _Pragma("unroll") for (int k = 0; k < 2; ++k) dst[n][k] = *(const LAS bf16x8*)(lds + PG8_SB(b, h) + boff + n * 2048 + k * 1024); } while (0)
; #define PG8_WAIT_V(n) asm volatile("s_waitcnt vmcnt(" #n ")" ::: "memory")
; #define PG8_BAR __builtin_amdgcn_s_barrier()
; template <class Epi, class Sched = StaticOrder, class EpiSub = NoSub, bool FAST = false>
; __device__ __forceinline__ void gemm_phase(LAS unsigned char* lds, const Gemm g, const Sched& S, const Epi& E, const EpiSub& ES = EpiSub()) {
;     ...
;         const bool has_next = S.next(ui + 1, nxt);
;         const size_t nko = (has_next && nxt.kb >= 0) ? nxt.kb * ksubB : 0;
;         const char* nA = has_next ? (const char*)g.A + (size_t)nxt.pm * tstepA + (size_t)nxt.pn * g.acs + nko : cA; const char* nB = has_next ? (const char*)g.Bt + (size_t)nxt.pn * tstepB + nko : cB;
;         const int nt = cur.kb < 0 ? ntMain : ntSub;
;         for (int t = 0; t < nt; t += 2) {
;             const bool last = (t == nt - 2);
;             const char* a1 = cA + (size_t)(t + 1) * kstep;
;             const char* a2 = last ? nA : cA + (size_t)(t + 2) * kstep; const char* b2 = last ? nB : cB + (size_t)(t + 2) * kstep;
;             const char* a3 = a2 + kstep; const char* b3 = b2 + kstep;
;             if constexpr (FAST && PG8_SP2) {
;             PG8_LDB(B0, 0, 0); PG8_LDB(B1, 0, 1); PG8_SCHED; PG8_LDA(At, 0, 0); PG8_STAGE(PG8_SA(1, 1), a1 + hstepA, voffA);
;             PG8_WAIT_V(8); PG8_WAIT_L(0); PG8_BAR; PG8_MMA(0, 0, At, B0); PG8_MMA(0, 1, At, B1); PG8_BAR; PG8_SCHED;
;             PG8_LDA(At, 0, 1); PG8_STAGE(PG8_SB(0, 0), b2, voffB); PG8_STAGE(PG8_SB(0, 1), b2 + hstepB, voffB); PG8_STAGE(PG8_SA(0, 0), a2, voffA);
;             PG8_WAIT_V(8); PG8_WAIT_L(0); PG8_BAR; PG8_MMA(1, 0, At, B0); PG8_MMA(1, 1, At, B1); PG8_BAR; PG8_SCHED;
.LBB0_631:
	s_cmp_gt_i32 s8, -1
	s_cselect_b64 s[26:27], -1, 0
	s_and_b64 s[26:27], s[24:25], s[26:27]
	s_lshl_b64 s[28:29], s[8:9], 10
	s_and_b64 s[26:27], s[26:27], exec
	s_cselect_b32 s31, s29, 0
	s_cselect_b32 s33, s28, 0
	s_ashr_i32 s23, s22, 31
	s_lshl_b64 s[26:27], s[22:23], 20
	v_readlane_b32 s28, v254, 36
	v_readlane_b32 s29, v254, 37
	s_add_u32 s1, s28, s26
	s_addc_u32 s5, s29, s27
	s_add_u32 s26, s1, s33
	s_addc_u32 s27, s5, s31
	s_and_b64 s[28:29], s[24:25], exec
	s_cselect_b32 s1, s27, s39
	s_cselect_b32 s5, s26, s38
	s_ashr_i32 s21, s20, 31
	s_lshl_b64 s[28:29], s[20:21], 20
	s_add_u32 s21, s2, s28
	s_addc_u32 s23, s3, s29
	s_add_u32 s28, s21, s33
	s_addc_u32 s29, s23, s31
	s_and_b64 s[36:37], s[24:25], exec
	s_cselect_b32 s21, s29, s41
	s_cselect_b32 s23, s28, s40
	s_cmp_gt_i32 s0, -1
	s_cselect_b64 s[36:37], -1, 0
	s_cmp_lt_i32 s0, 0
	s_cselect_b32 s31, 32, 8
	s_add_i32 s33, s31, -2
	s_add_u32 s38, s38, 0x80080
	s_addc_u32 s39, s39, 0
	s_add_u32 s48, s40, 0x100
	s_mov_b32 s42, 0
	s_addc_u32 s49, s41, 0
	ds_read_b128 v[104:107], v224
	ds_read_b128 v[108:111], v224 offset:1024
	ds_read_b128 v[120:123], v224 offset:2048
	ds_read_b128 v[124:127], v224 offset:3072
	ds_read_b128 v[136:139], v225
	ds_read_b128 v[140:143], v225 offset:1024
	ds_read_b128 v[152:155], v225 offset:2048
	ds_read_b128 v[156:159], v225 offset:3072
	s_add_i32 s50, s42, 2
	s_add_u32 s40, s38, 0xfff80080
	s_addc_u32 s41, s39, -1
	s_cmp_eq_u32 s33, s42
	s_cselect_b32 s42, s5, s40
	s_cselect_b32 s43, s1, s41
	s_cselect_b32 s41, s21, s49
	s_cselect_b32 s40, s23, s48
	v_lshl_add_u64 v[208:209], s[38:39], 0, v[202:203]
	s_add_i32 m0, s53, 0xc000
	ds_read_b128 v[160:163], v226
	ds_read_b128 v[164:167], v226 offset:1024
	ds_read_b128 v[168:171], v226 offset:2048
	ds_read_b128 v[172:175], v226 offset:3072
	ds_read_b128 v[176:179], v226 offset:4096
	ds_read_b128 v[180:183], v226 offset:5120
	ds_read_b128 v[184:187], v226 offset:6144
	ds_read_b128 v[188:191], v226 offset:7168
	global_load_lds_dwordx4 v[208:209], off
	v_lshl_add_u64 v[208:209], s[38:39], 0, v[204:205]
	s_add_i32 m0, s53, 0xe000
	s_nop 0
	global_load_lds_dwordx4 v[208:209], off
	s_waitcnt vmcnt(8)
	s_waitcnt lgkmcnt(0)
	s_barrier
	v_mfma_f32_16x16x32_bf16 v[148:151], v[104:107], v[160:163], 0
	v_mfma_f32_16x16x32_bf16 v[144:147], v[120:123], v[160:163], 0
	v_mfma_f32_16x16x32_bf16 v[116:119], v[104:107], v[168:171], 0
	v_mfma_f32_16x16x32_bf16 v[112:115], v[120:123], v[168:171], 0
	v_mfma_f32_16x16x32_bf16 v[92:95], v[104:107], v[176:179], 0
	v_mfma_f32_16x16x32_bf16 v[88:91], v[120:123], v[176:179], 0
	v_mfma_f32_16x16x32_bf16 v[76:79], v[104:107], v[184:187], 0
	v_mfma_f32_16x16x32_bf16 v[72:75], v[120:123], v[184:187], 0
	v_mfma_f32_16x16x32_bf16 v[148:151], v[108:111], v[164:167], v[148:151]
	v_mfma_f32_16x16x32_bf16 v[144:147], v[124:127], v[164:167], v[144:147]
	v_mfma_f32_16x16x32_bf16 v[116:119], v[108:111], v[172:175], v[116:119]
	v_mfma_f32_16x16x32_bf16 v[112:115], v[124:127], v[172:175], v[112:115]
	v_mfma_f32_16x16x32_bf16 v[92:95], v[108:111], v[180:183], v[92:95]
	v_mfma_f32_16x16x32_bf16 v[88:91], v[124:127], v[180:183], v[88:91]
	v_mfma_f32_16x16x32_bf16 v[76:79], v[108:111], v[188:191], v[76:79]
	v_mfma_f32_16x16x32_bf16 v[72:75], v[124:127], v[188:191], v[72:75]
	v_mfma_f32_16x16x32_bf16 v[132:135], v[136:139], v[160:163], 0
	v_mfma_f32_16x16x32_bf16 v[128:131], v[152:155], v[160:163], 0
	v_mfma_f32_16x16x32_bf16 v[100:103], v[136:139], v[168:171], 0
	v_mfma_f32_16x16x32_bf16 v[96:99], v[152:155], v[168:171], 0
	v_mfma_f32_16x16x32_bf16 v[84:87], v[136:139], v[176:179], 0
	v_mfma_f32_16x16x32_bf16 v[80:83], v[152:155], v[176:179], 0
	v_mfma_f32_16x16x32_bf16 v[68:71], v[136:139], v[184:187], 0
	v_mfma_f32_16x16x32_bf16 v[64:67], v[152:155], v[184:187], 0
	v_mfma_f32_16x16x32_bf16 v[132:135], v[140:143], v[164:167], v[132:135]
	v_mfma_f32_16x16x32_bf16 v[128:131], v[156:159], v[164:167], v[128:131]
	v_mfma_f32_16x16x32_bf16 v[100:103], v[140:143], v[172:175], v[100:103]
	v_mfma_f32_16x16x32_bf16 v[96:99], v[156:159], v[172:175], v[96:99]
	v_mfma_f32_16x16x32_bf16 v[84:87], v[140:143], v[180:183], v[84:87]
	v_mfma_f32_16x16x32_bf16 v[80:83], v[156:159], v[180:183], v[80:83]
	v_mfma_f32_16x16x32_bf16 v[68:71], v[140:143], v[188:191], v[68:71]
	v_mfma_f32_16x16x32_bf16 v[64:67], v[156:159], v[188:191], v[64:67]
	s_barrier
	s_add_i32 s51, s75, s52
	v_lshl_add_u64 v[208:209], s[40:41], 0, v[196:197]
	s_mov_b32 m0, s51
	ds_read_b128 v[160:163], v226 offset:16384
	ds_read_b128 v[164:167], v226 offset:17408
	ds_read_b128 v[168:171], v226 offset:18432
	ds_read_b128 v[172:175], v226 offset:19456
	ds_read_b128 v[176:179], v226 offset:20480
	ds_read_b128 v[180:183], v226 offset:21504
	ds_read_b128 v[184:187], v226 offset:22528
	ds_read_b128 v[188:191], v226 offset:23552
	global_load_lds_dwordx4 v[208:209], off
	s_add_i32 m0, s51, 0x2000
	s_add_u32 s70, s40, 0x80000
	v_lshl_add_u64 v[210:211], s[40:41], 0, v[200:201]
	s_addc_u32 s71, s41, 0
	s_add_i32 s51, s78, s52
	global_load_lds_dwordx4 v[210:211], off
	v_lshl_add_u64 v[212:213], s[70:71], 0, v[196:197]
	s_mov_b32 m0, s51
	v_lshl_add_u64 v[214:215], s[42:43], 0, v[198:199]
	global_load_lds_dwordx4 v[212:213], off
	v_lshl_add_u64 v[212:213], s[70:71], 0, v[200:201]
	s_add_i32 m0, s51, 0x2000
	s_nop 0
	global_load_lds_dwordx4 v[212:213], off
	v_lshl_add_u64 v[212:213], s[42:43], 0, v[194:195]
	s_mov_b32 m0, s53
	s_nop 0
	global_load_lds_dwordx4 v[212:213], off
	s_mov_b32 m0, s54
	s_nop 0
	global_load_lds_dwordx4 v[214:215], off
	s_waitcnt vmcnt(8)
	s_waitcnt lgkmcnt(0)
	s_barrier
; #define PG8_STAGE(bufoff, gbase, voff) do { _Pragma("unroll") for (int _i = 0; _i < 2; ++_i) \
;         __builtin_amdgcn_global_load_lds((const unsigned*)((const char*)(gbase) + (voff)[_i]), (LAS unsigned*)(lds + (bufoff) + ldsw + _i * 8192), 16, 0, 0); } while (0)
; #define PG8_LDA(dst, b, h) do { _Pragma("unroll") for (int m = 0; m < 4; ++m) _Pragma("unroll") for (int k = 0; k < 2; ++k) dst[m][k] = *(const LAS bf16x8*)(lds + PG8_SA(b, h) + aoff + m * 2048 + k * 1024); } while (0)
; #define PG8_LDB(dst, b, h) do { _Pragma("unroll") for (int n = 0; n < 2; ++n) _Pragma("unroll") for (int k = 0; k < 2; ++k) dst[n][k] = *(const LAS bf16x8*)(lds + PG8_SB(b, h) + boff + n * 2048 + k * 1024); } while (0)
; #define PG8_MMA(ai, bj, At, Bt) do { __builtin_amdgcn_s_setprio(1); _Pragma("unroll") for (int m = 0; m < 4; ++m) _Pragma("unroll") for (int n = 0; n < 2; ++n) _Pragma("unroll") for (int k = 0; k < 2; ++k) \
;         acc[ai][bj][m][n] = __builtin_amdgcn_mfma_f32_16x16x32_bf16(Bt[n][k], At[m][k], acc[ai][bj][m][n], 0, 0, 0); __builtin_amdgcn_s_setprio(0); } while (0)
; #define PG8_WAIT_V(n) asm volatile("s_waitcnt vmcnt(" #n ")" ::: "memory")
; #define PG8_WAIT_L(n) asm volatile("s_waitcnt lgkmcnt(" #n ")" ::: "memory")
; #define PG8_BAR __builtin_amdgcn_s_barrier()
; #define PG8_SCHED __builtin_amdgcn_sched_barrier(0)
; template <class Epi, class Sched = StaticOrder, class EpiSub = NoSub, bool FAST = false>
; __device__ __forceinline__ void gemm_phase(LAS unsigned char* lds, const Gemm g, const Sched& S, const Epi& E, const EpiSub& ES = EpiSub()) {
;     ...
;             PG8_WAIT_V(8); PG8_WAIT_L(0); PG8_BAR; PG8_MMA(1, 0, At, B0); PG8_MMA(1, 1, At, B1); PG8_BAR; PG8_SCHED;
;             PG8_LDB(B0, 1, 0); PG8_LDB(B1, 1, 1); PG8_SCHED; PG8_LDA(At, 1, 0); PG8_STAGE(PG8_SA(0, 1), a2 + hstepA, voffA);
;             PG8_WAIT_V(8); PG8_WAIT_L(0); PG8_BAR; PG8_MMA(0, 0, At, B0); PG8_MMA(0, 1, At, B1); PG8_BAR; PG8_SCHED;
	v_mfma_f32_16x16x32_bf16 v[60:63], v[104:107], v[160:163], 0
	v_mfma_f32_16x16x32_bf16 v[56:59], v[120:123], v[160:163], 0
	v_mfma_f32_16x16x32_bf16 v[44:47], v[104:107], v[168:171], 0
	v_mfma_f32_16x16x32_bf16 v[40:43], v[120:123], v[168:171], 0
	v_mfma_f32_16x16x32_bf16 v[28:31], v[104:107], v[176:179], 0
	v_mfma_f32_16x16x32_bf16 v[24:27], v[120:123], v[176:179], 0
	v_mfma_f32_16x16x32_bf16 v[12:15], v[104:107], v[184:187], 0
	v_mfma_f32_16x16x32_bf16 v[8:11], v[120:123], v[184:187], 0
	v_mfma_f32_16x16x32_bf16 v[60:63], v[108:111], v[164:167], v[60:63]
	v_mfma_f32_16x16x32_bf16 v[56:59], v[124:127], v[164:167], v[56:59]
	v_mfma_f32_16x16x32_bf16 v[44:47], v[108:111], v[172:175], v[44:47]
	v_mfma_f32_16x16x32_bf16 v[40:43], v[124:127], v[172:175], v[40:43]
	v_mfma_f32_16x16x32_bf16 v[28:31], v[108:111], v[180:183], v[28:31]
	v_mfma_f32_16x16x32_bf16 v[24:27], v[124:127], v[180:183], v[24:27]
	v_mfma_f32_16x16x32_bf16 v[12:15], v[108:111], v[188:191], v[12:15]
	v_mfma_f32_16x16x32_bf16 v[8:11], v[124:127], v[188:191], v[8:11]
	v_mfma_f32_16x16x32_bf16 v[52:55], v[136:139], v[160:163], 0
	v_mfma_f32_16x16x32_bf16 v[48:51], v[152:155], v[160:163], 0
	v_mfma_f32_16x16x32_bf16 v[36:39], v[136:139], v[168:171], 0
	v_mfma_f32_16x16x32_bf16 v[32:35], v[152:155], v[168:171], 0
	v_mfma_f32_16x16x32_bf16 v[20:23], v[136:139], v[176:179], 0
	v_mfma_f32_16x16x32_bf16 v[16:19], v[152:155], v[176:179], 0
	v_mfma_f32_16x16x32_bf16 v[4:7], v[136:139], v[184:187], 0
	v_mfma_f32_16x16x32_bf16 v[0:3], v[152:155], v[184:187], 0
	v_mfma_f32_16x16x32_bf16 v[52:55], v[140:143], v[164:167], v[52:55]
	v_mfma_f32_16x16x32_bf16 v[48:51], v[156:159], v[164:167], v[48:51]
	v_mfma_f32_16x16x32_bf16 v[36:39], v[140:143], v[172:175], v[36:39]
	v_mfma_f32_16x16x32_bf16 v[32:35], v[156:159], v[172:175], v[32:35]
	v_mfma_f32_16x16x32_bf16 v[20:23], v[140:143], v[180:183], v[20:23]
	v_mfma_f32_16x16x32_bf16 v[16:19], v[156:159], v[180:183], v[16:19]
	v_mfma_f32_16x16x32_bf16 v[4:7], v[140:143], v[188:191], v[4:7]
	v_mfma_f32_16x16x32_bf16 v[0:3], v[156:159], v[188:191], v[0:3]
	s_barrier
	s_add_i32 s51, 0, 0x18000
	s_add_i32 s70, 0, 0x1c000
	v_add_u32_e32 v124, s51, v221
	v_add_u32_e32 v156, s70, v221
	ds_read_b128 v[104:107], v124
	ds_read_b128 v[108:111], v124 offset:1024
	ds_read_b128 v[120:123], v124 offset:2048
	ds_read_b128 v[124:127], v124 offset:3072
	ds_read_b128 v[136:139], v156
	ds_read_b128 v[140:143], v156 offset:1024
	ds_read_b128 v[152:155], v156 offset:2048
	ds_read_b128 v[156:159], v156 offset:3072
	s_add_u32 s42, s42, 0x80000
	s_addc_u32 s43, s43, 0
	s_mov_b32 m0, s55
	v_lshl_add_u64 v[216:217], s[42:43], 0, v[194:195]
	ds_read_b128 v[160:163], v226 offset:32768
	ds_read_b128 v[164:167], v226 offset:33792
	ds_read_b128 v[168:171], v226 offset:34816
	ds_read_b128 v[172:175], v226 offset:35840
	ds_read_b128 v[176:179], v226 offset:36864
	ds_read_b128 v[180:183], v226 offset:37888
	ds_read_b128 v[184:187], v226 offset:38912
	ds_read_b128 v[188:191], v226 offset:39936
	global_load_lds_dwordx4 v[216:217], off
	v_lshl_add_u64 v[216:217], s[42:43], 0, v[198:199]
	s_mov_b32 m0, s56
	s_nop 0
	global_load_lds_dwordx4 v[216:217], off
	s_waitcnt vmcnt(8)
	s_waitcnt lgkmcnt(0)
	s_barrier
	v_mfma_f32_16x16x32_bf16 v[148:151], v[104:107], v[160:163], v[148:151]
	v_mfma_f32_16x16x32_bf16 v[144:147], v[120:123], v[160:163], v[144:147]
	v_mfma_f32_16x16x32_bf16 v[116:119], v[104:107], v[168:171], v[116:119]
	v_mfma_f32_16x16x32_bf16 v[112:115], v[120:123], v[168:171], v[112:115]
	v_mfma_f32_16x16x32_bf16 v[92:95], v[104:107], v[176:179], v[92:95]
	v_mfma_f32_16x16x32_bf16 v[88:91], v[120:123], v[176:179], v[88:91]
	v_mfma_f32_16x16x32_bf16 v[76:79], v[104:107], v[184:187], v[76:79]
	v_mfma_f32_16x16x32_bf16 v[72:75], v[120:123], v[184:187], v[72:75]
	v_mfma_f32_16x16x32_bf16 v[148:151], v[108:111], v[164:167], v[148:151]
	v_mfma_f32_16x16x32_bf16 v[144:147], v[124:127], v[164:167], v[144:147]
	v_mfma_f32_16x16x32_bf16 v[116:119], v[108:111], v[172:175], v[116:119]
	v_mfma_f32_16x16x32_bf16 v[112:115], v[124:127], v[172:175], v[112:115]
	v_mfma_f32_16x16x32_bf16 v[92:95], v[108:111], v[180:183], v[92:95]
	v_mfma_f32_16x16x32_bf16 v[88:91], v[124:127], v[180:183], v[88:91]
	v_mfma_f32_16x16x32_bf16 v[76:79], v[108:111], v[188:191], v[76:79]
	v_mfma_f32_16x16x32_bf16 v[72:75], v[124:127], v[188:191], v[72:75]
	v_mfma_f32_16x16x32_bf16 v[132:135], v[136:139], v[160:163], v[132:135]
	v_mfma_f32_16x16x32_bf16 v[128:131], v[152:155], v[160:163], v[128:131]
	v_mfma_f32_16x16x32_bf16 v[100:103], v[136:139], v[168:171], v[100:103]
	v_mfma_f32_16x16x32_bf16 v[96:99], v[152:155], v[168:171], v[96:99]
	v_mfma_f32_16x16x32_bf16 v[84:87], v[136:139], v[176:179], v[84:87]
	v_mfma_f32_16x16x32_bf16 v[80:83], v[152:155], v[176:179], v[80:83]
	v_mfma_f32_16x16x32_bf16 v[68:71], v[136:139], v[184:187], v[68:71]
	v_mfma_f32_16x16x32_bf16 v[64:67], v[152:155], v[184:187], v[64:67]
	v_mfma_f32_16x16x32_bf16 v[132:135], v[140:143], v[164:167], v[132:135]
	v_mfma_f32_16x16x32_bf16 v[128:131], v[156:159], v[164:167], v[128:131]
	v_mfma_f32_16x16x32_bf16 v[100:103], v[140:143], v[172:175], v[100:103]
	v_mfma_f32_16x16x32_bf16 v[96:99], v[156:159], v[172:175], v[96:99]
	v_mfma_f32_16x16x32_bf16 v[84:87], v[140:143], v[180:183], v[84:87]
	v_mfma_f32_16x16x32_bf16 v[80:83], v[156:159], v[180:183], v[80:83]
	v_mfma_f32_16x16x32_bf16 v[68:71], v[140:143], v[188:191], v[68:71]
	v_mfma_f32_16x16x32_bf16 v[64:67], v[156:159], v[188:191], v[64:67]
	s_barrier
; #define PG8_STAGE(bufoff, gbase, voff) do { _Pragma("unroll") for (int _i = 0; _i < 2; ++_i) \
;         __builtin_amdgcn_global_load_lds((const unsigned*)((const char*)(gbase) + (voff)[_i]), (LAS unsigned*)(lds + (bufoff) + ldsw + _i * 8192), 16, 0, 0); } while (0)
; #define PG8_LDA(dst, b, h) do { _Pragma("unroll") for (int m = 0; m < 4; ++m) _Pragma("unroll") for (int k = 0; k < 2; ++k) dst[m][k] = *(const LAS bf16x8*)(lds + PG8_SA(b, h) + aoff + m * 2048 + k * 1024); } while (0)
; #define PG8_LDB(dst, b, h) do { _Pragma("unroll") for (int n = 0; n < 2; ++n) _Pragma("unroll") for (int k = 0; k < 2; ++k) dst[n][k] = *(const LAS bf16x8*)(lds + PG8_SB(b, h) + boff + n * 2048 + k * 1024); } while (0)
; template <class Epi, class Sched = StaticOrder, class EpiSub = NoSub, bool FAST = false>
; __device__ __forceinline__ void gemm_phase(LAS unsigned char* lds, const Gemm g, const Sched& S, const Epi& E, const EpiSub& ES = EpiSub()) {
;     ...
;         for (int t = 0; t < nt; t += 2) {
;             const bool last = (t == nt - 2);
;             const char* a1 = cA + (size_t)(t + 1) * kstep;
;             const char* a2 = last ? nA : cA + (size_t)(t + 2) * kstep; const char* b2 = last ? nB : cB + (size_t)(t + 2) * kstep;
;             const char* a3 = a2 + kstep; const char* b3 = b2 + kstep;
;             if constexpr (FAST && PG8_SP2) {
;             PG8_LDB(B0, 0, 0); PG8_LDB(B1, 0, 1); PG8_SCHED; PG8_LDA(At, 0, 0); PG8_STAGE(PG8_SA(1, 1), a1 + hstepA, voffA);
;             PG8_WAIT_V(8); PG8_WAIT_L(0); PG8_BAR; PG8_MMA(0, 0, At, B0); PG8_MMA(0, 1, At, B1); PG8_BAR; PG8_SCHED;
;             PG8_LDA(At, 0, 1); PG8_STAGE(PG8_SB(0, 0), b2, voffB); PG8_STAGE(PG8_SB(0, 1), b2 + hstepB, voffB); PG8_STAGE(PG8_SA(0, 0), a2, voffA);
;             PG8_WAIT_V(8); PG8_WAIT_L(0); PG8_BAR; PG8_MMA(1, 0, At, B0); PG8_MMA(1, 1, At, B1); PG8_BAR; PG8_SCHED;
;             PG8_LDB(B0, 1, 0); PG8_LDB(B1, 1, 1); PG8_SCHED; PG8_LDA(At, 1, 0); PG8_STAGE(PG8_SA(0, 1), a2 + hstepA, voffA);
;             PG8_WAIT_V(8); PG8_WAIT_L(0); PG8_BAR; PG8_MMA(0, 0, At, B0); PG8_MMA(0, 1, At, B1); PG8_BAR; PG8_SCHED;
;             PG8_LDA(At, 1, 1); PG8_STAGE(PG8_SB(1, 0), b3, voffB); PG8_STAGE(PG8_SB(1, 1), b3 + hstepB, voffB); PG8_STAGE(PG8_SA(1, 0), a3, voffA);
;             PG8_WAIT_V(8); PG8_WAIT_L(0); PG8_BAR; PG8_MMA(1, 0, At, B0); PG8_MMA(1, 1, At, B1); PG8_BAR; PG8_SCHED;
	s_add_i32 s42, s51, s52
	v_lshl_add_u64 v[208:209], v[208:209], 0, s[12:13]
	s_mov_b32 m0, s42
	ds_read_b128 v[160:163], v226 offset:49152
	ds_read_b128 v[164:167], v226 offset:50176
	ds_read_b128 v[168:171], v226 offset:51200
	ds_read_b128 v[172:175], v226 offset:52224
	ds_read_b128 v[176:179], v226 offset:53248
	ds_read_b128 v[180:183], v226 offset:54272
	ds_read_b128 v[184:187], v226 offset:55296
	ds_read_b128 v[188:191], v226 offset:56320
	global_load_lds_dwordx4 v[208:209], off
	s_add_i32 m0, s42, 0x2000
	s_add_u32 s40, s40, 0x80080
	v_lshl_add_u64 v[208:209], v[210:211], 0, s[12:13]
	s_addc_u32 s41, s41, 0
	s_add_i32 s42, s70, s52
	global_load_lds_dwordx4 v[208:209], off
	v_lshl_add_u64 v[208:209], s[40:41], 0, v[196:197]
	s_mov_b32 m0, s42
	s_nop 0
	global_load_lds_dwordx4 v[208:209], off
	v_lshl_add_u64 v[208:209], s[40:41], 0, v[200:201]
	s_add_i32 m0, s42, 0x2000
	s_nop 0
	global_load_lds_dwordx4 v[208:209], off
	v_lshl_add_u64 v[208:209], v[212:213], 0, s[12:13]
	s_mov_b32 m0, s69
	s_nop 0
	global_load_lds_dwordx4 v[208:209], off
	v_lshl_add_u64 v[208:209], v[214:215], 0, s[12:13]
	s_mov_b32 m0, s74
	s_nop 0
	global_load_lds_dwordx4 v[208:209], off
	s_waitcnt vmcnt(8)
	s_waitcnt lgkmcnt(0)
	s_barrier
	v_mfma_f32_16x16x32_bf16 v[60:63], v[104:107], v[160:163], v[60:63]
	v_mfma_f32_16x16x32_bf16 v[56:59], v[120:123], v[160:163], v[56:59]
	v_mfma_f32_16x16x32_bf16 v[44:47], v[104:107], v[168:171], v[44:47]
	v_mfma_f32_16x16x32_bf16 v[40:43], v[120:123], v[168:171], v[40:43]
	v_mfma_f32_16x16x32_bf16 v[28:31], v[104:107], v[176:179], v[28:31]
	v_mfma_f32_16x16x32_bf16 v[24:27], v[120:123], v[176:179], v[24:27]
	v_mfma_f32_16x16x32_bf16 v[12:15], v[104:107], v[184:187], v[12:15]
	v_mfma_f32_16x16x32_bf16 v[8:11], v[120:123], v[184:187], v[8:11]
	v_mfma_f32_16x16x32_bf16 v[60:63], v[108:111], v[164:167], v[60:63]
	v_mfma_f32_16x16x32_bf16 v[56:59], v[124:127], v[164:167], v[56:59]
	v_mfma_f32_16x16x32_bf16 v[44:47], v[108:111], v[172:175], v[44:47]
	v_mfma_f32_16x16x32_bf16 v[40:43], v[124:127], v[172:175], v[40:43]
	v_mfma_f32_16x16x32_bf16 v[28:31], v[108:111], v[180:183], v[28:31]
	v_mfma_f32_16x16x32_bf16 v[24:27], v[124:127], v[180:183], v[24:27]
	v_mfma_f32_16x16x32_bf16 v[12:15], v[108:111], v[188:191], v[12:15]
	v_mfma_f32_16x16x32_bf16 v[8:11], v[124:127], v[188:191], v[8:11]
	v_mfma_f32_16x16x32_bf16 v[52:55], v[136:139], v[160:163], v[52:55]
	v_mfma_f32_16x16x32_bf16 v[48:51], v[152:155], v[160:163], v[48:51]
	v_mfma_f32_16x16x32_bf16 v[36:39], v[136:139], v[168:171], v[36:39]
	v_mfma_f32_16x16x32_bf16 v[32:35], v[152:155], v[168:171], v[32:35]
	v_mfma_f32_16x16x32_bf16 v[20:23], v[136:139], v[176:179], v[20:23]
	v_mfma_f32_16x16x32_bf16 v[16:19], v[152:155], v[176:179], v[16:19]
	v_mfma_f32_16x16x32_bf16 v[4:7], v[136:139], v[184:187], v[4:7]
	v_mfma_f32_16x16x32_bf16 v[0:3], v[152:155], v[184:187], v[0:3]
	v_mfma_f32_16x16x32_bf16 v[52:55], v[140:143], v[164:167], v[52:55]
	v_mfma_f32_16x16x32_bf16 v[48:51], v[156:159], v[164:167], v[48:51]
	v_mfma_f32_16x16x32_bf16 v[36:39], v[140:143], v[172:175], v[36:39]
	v_mfma_f32_16x16x32_bf16 v[32:35], v[156:159], v[172:175], v[32:35]
	v_mfma_f32_16x16x32_bf16 v[20:23], v[140:143], v[180:183], v[20:23]
	v_mfma_f32_16x16x32_bf16 v[16:19], v[156:159], v[180:183], v[16:19]
	v_mfma_f32_16x16x32_bf16 v[4:7], v[140:143], v[188:191], v[4:7]
	v_mfma_f32_16x16x32_bf16 v[0:3], v[156:159], v[188:191], v[0:3]
	s_barrier
	s_add_u32 s38, s38, 0x100
	s_addc_u32 s39, s39, 0
	s_add_u32 s48, s48, 0x100
	s_addc_u32 s49, s49, 0
	s_cmp_ge_u32 s50, s31
	s_mov_b32 s42, s50
	s_cbranch_scc1 .Lkpeel_632_exit
.LBB0_632:
	ds_read_b128 v[104:107], v224
	ds_read_b128 v[108:111], v224 offset:1024
	ds_read_b128 v[120:123], v224 offset:2048
	ds_read_b128 v[124:127], v224 offset:3072
	ds_read_b128 v[136:139], v225
	ds_read_b128 v[140:143], v225 offset:1024
	ds_read_b128 v[152:155], v225 offset:2048
	ds_read_b128 v[156:159], v225 offset:3072
	s_add_i32 s50, s42, 2
	s_add_u32 s40, s38, 0xfff80080
	s_addc_u32 s41, s39, -1
	s_cmp_eq_u32 s33, s42
	s_cselect_b32 s42, s5, s40
	s_cselect_b32 s43, s1, s41
	s_cselect_b32 s41, s21, s49
	s_cselect_b32 s40, s23, s48
	v_lshl_add_u64 v[208:209], s[38:39], 0, v[202:203]
	s_add_i32 m0, s53, 0xc000
	ds_read_b128 v[160:163], v226
	ds_read_b128 v[164:167], v226 offset:1024
	ds_read_b128 v[168:171], v226 offset:2048
	ds_read_b128 v[172:175], v226 offset:3072
	ds_read_b128 v[176:179], v226 offset:4096
	ds_read_b128 v[180:183], v226 offset:5120
	ds_read_b128 v[184:187], v226 offset:6144
	ds_read_b128 v[188:191], v226 offset:7168
	global_load_lds_dwordx4 v[208:209], off
	v_lshl_add_u64 v[208:209], s[38:39], 0, v[204:205]
	s_add_i32 m0, s53, 0xe000
	s_nop 0
	global_load_lds_dwordx4 v[208:209], off
	s_waitcnt vmcnt(8)
	s_waitcnt lgkmcnt(0)
	s_barrier
; #define PG8_STAGE(bufoff, gbase, voff) do { _Pragma("unroll") for (int _i = 0; _i < 2; ++_i) \
;         __builtin_amdgcn_global_load_lds((const unsigned*)((const char*)(gbase) + (voff)[_i]), (LAS unsigned*)(lds + (bufoff) + ldsw + _i * 8192), 16, 0, 0); } while (0)
; #define PG8_LDA(dst, b, h) do { _Pragma("unroll") for (int m = 0; m < 4; ++m) _Pragma("unroll") for (int k = 0; k < 2; ++k) dst[m][k] = *(const LAS bf16x8*)(lds + PG8_SA(b, h) + aoff + m * 2048 + k * 1024); } while (0)
; #define PG8_MMA(ai, bj, At, Bt) do { __builtin_amdgcn_s_setprio(1); _Pragma("unroll") for (int m = 0; m < 4; ++m) _Pragma("unroll") for (int n = 0; n < 2; ++n) _Pragma("unroll") for (int k = 0; k < 2; ++k) \
;         acc[ai][bj][m][n] = __builtin_amdgcn_mfma_f32_16x16x32_bf16(Bt[n][k], At[m][k], acc[ai][bj][m][n], 0, 0, 0); __builtin_amdgcn_s_setprio(0); } while (0)
; #define PG8_WAIT_V(n) asm volatile("s_waitcnt vmcnt(" #n ")" ::: "memory")
; #define PG8_WAIT_L(n) asm volatile("s_waitcnt lgkmcnt(" #n ")" ::: "memory")
; #define PG8_BAR __builtin_amdgcn_s_barrier()
; #define PG8_SCHED __builtin_amdgcn_sched_barrier(0)
; template <class Epi, class Sched = StaticOrder, class EpiSub = NoSub, bool FAST = false>
; __device__ __forceinline__ void gemm_phase(LAS unsigned char* lds, const Gemm g, const Sched& S, const Epi& E, const EpiSub& ES = EpiSub()) {
;     ...
;             PG8_WAIT_V(8); PG8_WAIT_L(0); PG8_BAR; PG8_MMA(0, 0, At, B0); PG8_MMA(0, 1, At, B1); PG8_BAR; PG8_SCHED;
;             PG8_LDA(At, 0, 1); PG8_STAGE(PG8_SB(0, 0), b2, voffB); PG8_STAGE(PG8_SB(0, 1), b2 + hstepB, voffB); PG8_STAGE(PG8_SA(0, 0), a2, voffA);
;             PG8_WAIT_V(8); PG8_WAIT_L(0); PG8_BAR; PG8_MMA(1, 0, At, B0); PG8_MMA(1, 1, At, B1); PG8_BAR; PG8_SCHED;
	v_mfma_f32_16x16x32_bf16 v[148:151], v[104:107], v[160:163], v[148:151]
	v_mfma_f32_16x16x32_bf16 v[144:147], v[120:123], v[160:163], v[144:147]
	v_mfma_f32_16x16x32_bf16 v[116:119], v[104:107], v[168:171], v[116:119]
	v_mfma_f32_16x16x32_bf16 v[112:115], v[120:123], v[168:171], v[112:115]
	v_mfma_f32_16x16x32_bf16 v[92:95], v[104:107], v[176:179], v[92:95]
	v_mfma_f32_16x16x32_bf16 v[88:91], v[120:123], v[176:179], v[88:91]
	v_mfma_f32_16x16x32_bf16 v[76:79], v[104:107], v[184:187], v[76:79]
	v_mfma_f32_16x16x32_bf16 v[72:75], v[120:123], v[184:187], v[72:75]
	v_mfma_f32_16x16x32_bf16 v[148:151], v[108:111], v[164:167], v[148:151]
	v_mfma_f32_16x16x32_bf16 v[144:147], v[124:127], v[164:167], v[144:147]
	v_mfma_f32_16x16x32_bf16 v[116:119], v[108:111], v[172:175], v[116:119]
	v_mfma_f32_16x16x32_bf16 v[112:115], v[124:127], v[172:175], v[112:115]
	v_mfma_f32_16x16x32_bf16 v[92:95], v[108:111], v[180:183], v[92:95]
	v_mfma_f32_16x16x32_bf16 v[88:91], v[124:127], v[180:183], v[88:91]
	v_mfma_f32_16x16x32_bf16 v[76:79], v[108:111], v[188:191], v[76:79]
	v_mfma_f32_16x16x32_bf16 v[72:75], v[124:127], v[188:191], v[72:75]
	v_mfma_f32_16x16x32_bf16 v[132:135], v[136:139], v[160:163], v[132:135]
	v_mfma_f32_16x16x32_bf16 v[128:131], v[152:155], v[160:163], v[128:131]
	v_mfma_f32_16x16x32_bf16 v[100:103], v[136:139], v[168:171], v[100:103]
	v_mfma_f32_16x16x32_bf16 v[96:99], v[152:155], v[168:171], v[96:99]
	v_mfma_f32_16x16x32_bf16 v[84:87], v[136:139], v[176:179], v[84:87]
	v_mfma_f32_16x16x32_bf16 v[80:83], v[152:155], v[176:179], v[80:83]
	v_mfma_f32_16x16x32_bf16 v[68:71], v[136:139], v[184:187], v[68:71]
	v_mfma_f32_16x16x32_bf16 v[64:67], v[152:155], v[184:187], v[64:67]
	v_mfma_f32_16x16x32_bf16 v[132:135], v[140:143], v[164:167], v[132:135]
	v_mfma_f32_16x16x32_bf16 v[128:131], v[156:159], v[164:167], v[128:131]
	v_mfma_f32_16x16x32_bf16 v[100:103], v[140:143], v[172:175], v[100:103]
	v_mfma_f32_16x16x32_bf16 v[96:99], v[156:159], v[172:175], v[96:99]
	v_mfma_f32_16x16x32_bf16 v[84:87], v[140:143], v[180:183], v[84:87]
	v_mfma_f32_16x16x32_bf16 v[80:83], v[156:159], v[180:183], v[80:83]
	v_mfma_f32_16x16x32_bf16 v[68:71], v[140:143], v[188:191], v[68:71]
	v_mfma_f32_16x16x32_bf16 v[64:67], v[156:159], v[188:191], v[64:67]
	s_barrier
	s_add_i32 s51, s75, s52
	v_lshl_add_u64 v[208:209], s[40:41], 0, v[196:197]
	s_mov_b32 m0, s51
	ds_read_b128 v[160:163], v226 offset:16384
	ds_read_b128 v[164:167], v226 offset:17408
	ds_read_b128 v[168:171], v226 offset:18432
	ds_read_b128 v[172:175], v226 offset:19456
	ds_read_b128 v[176:179], v226 offset:20480
	ds_read_b128 v[180:183], v226 offset:21504
	ds_read_b128 v[184:187], v226 offset:22528
	ds_read_b128 v[188:191], v226 offset:23552
	global_load_lds_dwordx4 v[208:209], off
	s_add_i32 m0, s51, 0x2000
	s_add_u32 s70, s40, 0x80000
	v_lshl_add_u64 v[210:211], s[40:41], 0, v[200:201]
	s_addc_u32 s71, s41, 0
	s_add_i32 s51, s78, s52
	global_load_lds_dwordx4 v[210:211], off
	v_lshl_add_u64 v[212:213], s[70:71], 0, v[196:197]
	s_mov_b32 m0, s51
	v_lshl_add_u64 v[214:215], s[42:43], 0, v[198:199]
	global_load_lds_dwordx4 v[212:213], off
	v_lshl_add_u64 v[212:213], s[70:71], 0, v[200:201]
	s_add_i32 m0, s51, 0x2000
	s_nop 0
	global_load_lds_dwordx4 v[212:213], off
	v_lshl_add_u64 v[212:213], s[42:43], 0, v[194:195]
	s_mov_b32 m0, s53
	s_nop 0
	global_load_lds_dwordx4 v[212:213], off
	s_mov_b32 m0, s54
	s_nop 0
	global_load_lds_dwordx4 v[214:215], off
	s_waitcnt vmcnt(8)
	s_waitcnt lgkmcnt(0)
	s_barrier
	v_mfma_f32_16x16x32_bf16 v[60:63], v[104:107], v[160:163], v[60:63]
	v_mfma_f32_16x16x32_bf16 v[56:59], v[120:123], v[160:163], v[56:59]
	v_mfma_f32_16x16x32_bf16 v[44:47], v[104:107], v[168:171], v[44:47]
	v_mfma_f32_16x16x32_bf16 v[40:43], v[120:123], v[168:171], v[40:43]
	v_mfma_f32_16x16x32_bf16 v[28:31], v[104:107], v[176:179], v[28:31]
	v_mfma_f32_16x16x32_bf16 v[24:27], v[120:123], v[176:179], v[24:27]
	v_mfma_f32_16x16x32_bf16 v[12:15], v[104:107], v[184:187], v[12:15]
	v_mfma_f32_16x16x32_bf16 v[8:11], v[120:123], v[184:187], v[8:11]
	v_mfma_f32_16x16x32_bf16 v[60:63], v[108:111], v[164:167], v[60:63]
	v_mfma_f32_16x16x32_bf16 v[56:59], v[124:127], v[164:167], v[56:59]
	v_mfma_f32_16x16x32_bf16 v[44:47], v[108:111], v[172:175], v[44:47]
	v_mfma_f32_16x16x32_bf16 v[40:43], v[124:127], v[172:175], v[40:43]
	v_mfma_f32_16x16x32_bf16 v[28:31], v[108:111], v[180:183], v[28:31]
	v_mfma_f32_16x16x32_bf16 v[24:27], v[124:127], v[180:183], v[24:27]
	v_mfma_f32_16x16x32_bf16 v[12:15], v[108:111], v[188:191], v[12:15]
	v_mfma_f32_16x16x32_bf16 v[8:11], v[124:127], v[188:191], v[8:11]
	v_mfma_f32_16x16x32_bf16 v[52:55], v[136:139], v[160:163], v[52:55]
	v_mfma_f32_16x16x32_bf16 v[48:51], v[152:155], v[160:163], v[48:51]
	v_mfma_f32_16x16x32_bf16 v[36:39], v[136:139], v[168:171], v[36:39]
	v_mfma_f32_16x16x32_bf16 v[32:35], v[152:155], v[168:171], v[32:35]
	v_mfma_f32_16x16x32_bf16 v[20:23], v[136:139], v[176:179], v[20:23]
	v_mfma_f32_16x16x32_bf16 v[16:19], v[152:155], v[176:179], v[16:19]
	v_mfma_f32_16x16x32_bf16 v[4:7], v[136:139], v[184:187], v[4:7]
	v_mfma_f32_16x16x32_bf16 v[0:3], v[152:155], v[184:187], v[0:3]
	v_mfma_f32_16x16x32_bf16 v[52:55], v[140:143], v[164:167], v[52:55]
	v_mfma_f32_16x16x32_bf16 v[48:51], v[156:159], v[164:167], v[48:51]
	v_mfma_f32_16x16x32_bf16 v[36:39], v[140:143], v[172:175], v[36:39]
	v_mfma_f32_16x16x32_bf16 v[32:35], v[156:159], v[172:175], v[32:35]
	v_mfma_f32_16x16x32_bf16 v[20:23], v[140:143], v[180:183], v[20:23]
	v_mfma_f32_16x16x32_bf16 v[16:19], v[156:159], v[180:183], v[16:19]
	v_mfma_f32_16x16x32_bf16 v[4:7], v[140:143], v[188:191], v[4:7]
	v_mfma_f32_16x16x32_bf16 v[0:3], v[156:159], v[188:191], v[0:3]
	s_barrier
; #define PG8_STAGE(bufoff, gbase, voff) do { _Pragma("unroll") for (int _i = 0; _i < 2; ++_i) \
;         __builtin_amdgcn_global_load_lds((const unsigned*)((const char*)(gbase) + (voff)[_i]), (LAS unsigned*)(lds + (bufoff) + ldsw + _i * 8192), 16, 0, 0); } while (0)
; #define PG8_LDA(dst, b, h) do { _Pragma("unroll") for (int m = 0; m < 4; ++m) _Pragma("unroll") for (int k = 0; k < 2; ++k) dst[m][k] = *(const LAS bf16x8*)(lds + PG8_SA(b, h) + aoff + m * 2048 + k * 1024); } while (0)
; #define PG8_LDB(dst, b, h) do { _Pragma("unroll") for (int n = 0; n < 2; ++n) _Pragma("unroll") for (int k = 0; k < 2; ++k) dst[n][k] = *(const LAS bf16x8*)(lds + PG8_SB(b, h) + boff + n * 2048 + k * 1024); } while (0)
; #define PG8_MMA(ai, bj, At, Bt) do { __builtin_amdgcn_s_setprio(1); _Pragma("unroll") for (int m = 0; m < 4; ++m) _Pragma("unroll") for (int n = 0; n < 2; ++n) _Pragma("unroll") for (int k = 0; k < 2; ++k) \
;         acc[ai][bj][m][n] = __builtin_amdgcn_mfma_f32_16x16x32_bf16(Bt[n][k], At[m][k], acc[ai][bj][m][n], 0, 0, 0); __builtin_amdgcn_s_setprio(0); } while (0)
; #define PG8_WAIT_V(n) asm volatile("s_waitcnt vmcnt(" #n ")" ::: "memory")
; #define PG8_WAIT_L(n) asm volatile("s_waitcnt lgkmcnt(" #n ")" ::: "memory")
; #define PG8_BAR __builtin_amdgcn_s_barrier()
; #define PG8_SCHED __builtin_amdgcn_sched_barrier(0)
; template <class Epi, class Sched = StaticOrder, class EpiSub = NoSub, bool FAST = false>
; __device__ __forceinline__ void gemm_phase(LAS unsigned char* lds, const Gemm g, const Sched& S, const Epi& E, const EpiSub& ES = EpiSub()) {
;     ...
;             PG8_LDB(B0, 1, 0); PG8_LDB(B1, 1, 1); PG8_SCHED; PG8_LDA(At, 1, 0); PG8_STAGE(PG8_SA(0, 1), a2 + hstepA, voffA);
;             PG8_WAIT_V(8); PG8_WAIT_L(0); PG8_BAR; PG8_MMA(0, 0, At, B0); PG8_MMA(0, 1, At, B1); PG8_BAR; PG8_SCHED;
;             PG8_LDA(At, 1, 1); PG8_STAGE(PG8_SB(1, 0), b3, voffB); PG8_STAGE(PG8_SB(1, 1), b3 + hstepB, voffB); PG8_STAGE(PG8_SA(1, 0), a3, voffA);
;             PG8_WAIT_V(8); PG8_WAIT_L(0); PG8_BAR; PG8_MMA(1, 0, At, B0); PG8_MMA(1, 1, At, B1); PG8_BAR; PG8_SCHED;
	s_add_i32 s51, 0, 0x18000
	s_add_i32 s70, 0, 0x1c000
	v_add_u32_e32 v124, s51, v221
	v_add_u32_e32 v156, s70, v221
	ds_read_b128 v[104:107], v124
	ds_read_b128 v[108:111], v124 offset:1024
	ds_read_b128 v[120:123], v124 offset:2048
	ds_read_b128 v[124:127], v124 offset:3072
	ds_read_b128 v[136:139], v156
	ds_read_b128 v[140:143], v156 offset:1024
	ds_read_b128 v[152:155], v156 offset:2048
	ds_read_b128 v[156:159], v156 offset:3072
	s_add_u32 s42, s42, 0x80000
	s_addc_u32 s43, s43, 0
	s_mov_b32 m0, s55
	v_lshl_add_u64 v[216:217], s[42:43], 0, v[194:195]
	ds_read_b128 v[160:163], v226 offset:32768
	ds_read_b128 v[164:167], v226 offset:33792
	ds_read_b128 v[168:171], v226 offset:34816
	ds_read_b128 v[172:175], v226 offset:35840
	ds_read_b128 v[176:179], v226 offset:36864
	ds_read_b128 v[180:183], v226 offset:37888
	ds_read_b128 v[184:187], v226 offset:38912
	ds_read_b128 v[188:191], v226 offset:39936
	global_load_lds_dwordx4 v[216:217], off
	v_lshl_add_u64 v[216:217], s[42:43], 0, v[198:199]
	s_mov_b32 m0, s56
	s_nop 0
	global_load_lds_dwordx4 v[216:217], off
	s_waitcnt vmcnt(8)
	s_waitcnt lgkmcnt(0)
	s_barrier
	v_mfma_f32_16x16x32_bf16 v[148:151], v[104:107], v[160:163], v[148:151]
	v_mfma_f32_16x16x32_bf16 v[144:147], v[120:123], v[160:163], v[144:147]
	v_mfma_f32_16x16x32_bf16 v[116:119], v[104:107], v[168:171], v[116:119]
	v_mfma_f32_16x16x32_bf16 v[112:115], v[120:123], v[168:171], v[112:115]
	v_mfma_f32_16x16x32_bf16 v[92:95], v[104:107], v[176:179], v[92:95]
	v_mfma_f32_16x16x32_bf16 v[88:91], v[120:123], v[176:179], v[88:91]
	v_mfma_f32_16x16x32_bf16 v[76:79], v[104:107], v[184:187], v[76:79]
	v_mfma_f32_16x16x32_bf16 v[72:75], v[120:123], v[184:187], v[72:75]
	v_mfma_f32_16x16x32_bf16 v[148:151], v[108:111], v[164:167], v[148:151]
	v_mfma_f32_16x16x32_bf16 v[144:147], v[124:127], v[164:167], v[144:147]
	v_mfma_f32_16x16x32_bf16 v[116:119], v[108:111], v[172:175], v[116:119]
	v_mfma_f32_16x16x32_bf16 v[112:115], v[124:127], v[172:175], v[112:115]
	v_mfma_f32_16x16x32_bf16 v[92:95], v[108:111], v[180:183], v[92:95]
	v_mfma_f32_16x16x32_bf16 v[88:91], v[124:127], v[180:183], v[88:91]
	v_mfma_f32_16x16x32_bf16 v[76:79], v[108:111], v[188:191], v[76:79]
	v_mfma_f32_16x16x32_bf16 v[72:75], v[124:127], v[188:191], v[72:75]
	v_mfma_f32_16x16x32_bf16 v[132:135], v[136:139], v[160:163], v[132:135]
	v_mfma_f32_16x16x32_bf16 v[128:131], v[152:155], v[160:163], v[128:131]
	v_mfma_f32_16x16x32_bf16 v[100:103], v[136:139], v[168:171], v[100:103]
	v_mfma_f32_16x16x32_bf16 v[96:99], v[152:155], v[168:171], v[96:99]
	v_mfma_f32_16x16x32_bf16 v[84:87], v[136:139], v[176:179], v[84:87]
	v_mfma_f32_16x16x32_bf16 v[80:83], v[152:155], v[176:179], v[80:83]
	v_mfma_f32_16x16x32_bf16 v[68:71], v[136:139], v[184:187], v[68:71]
	v_mfma_f32_16x16x32_bf16 v[64:67], v[152:155], v[184:187], v[64:67]
	v_mfma_f32_16x16x32_bf16 v[132:135], v[140:143], v[164:167], v[132:135]
	v_mfma_f32_16x16x32_bf16 v[128:131], v[156:159], v[164:167], v[128:131]
	v_mfma_f32_16x16x32_bf16 v[100:103], v[140:143], v[172:175], v[100:103]
	v_mfma_f32_16x16x32_bf16 v[96:99], v[156:159], v[172:175], v[96:99]
	v_mfma_f32_16x16x32_bf16 v[84:87], v[140:143], v[180:183], v[84:87]
	v_mfma_f32_16x16x32_bf16 v[80:83], v[156:159], v[180:183], v[80:83]
	v_mfma_f32_16x16x32_bf16 v[68:71], v[140:143], v[188:191], v[68:71]
	v_mfma_f32_16x16x32_bf16 v[64:67], v[156:159], v[188:191], v[64:67]
	s_barrier
	s_add_i32 s42, s51, s52
	v_lshl_add_u64 v[208:209], v[208:209], 0, s[12:13]
	s_mov_b32 m0, s42
	ds_read_b128 v[160:163], v226 offset:49152
	ds_read_b128 v[164:167], v226 offset:50176
	ds_read_b128 v[168:171], v226 offset:51200
	ds_read_b128 v[172:175], v226 offset:52224
	ds_read_b128 v[176:179], v226 offset:53248
	ds_read_b128 v[180:183], v226 offset:54272
	ds_read_b128 v[184:187], v226 offset:55296
	ds_read_b128 v[188:191], v226 offset:56320
	global_load_lds_dwordx4 v[208:209], off
	s_add_i32 m0, s42, 0x2000
	s_add_u32 s40, s40, 0x80080
	v_lshl_add_u64 v[208:209], v[210:211], 0, s[12:13]
	s_addc_u32 s41, s41, 0
	s_add_i32 s42, s70, s52
	global_load_lds_dwordx4 v[208:209], off
	v_lshl_add_u64 v[208:209], s[40:41], 0, v[196:197]
	s_mov_b32 m0, s42
	s_nop 0
	global_load_lds_dwordx4 v[208:209], off
	v_lshl_add_u64 v[208:209], s[40:41], 0, v[200:201]
	s_add_i32 m0, s42, 0x2000
	s_nop 0
	global_load_lds_dwordx4 v[208:209], off
	v_lshl_add_u64 v[208:209], v[212:213], 0, s[12:13]
	s_mov_b32 m0, s69
	s_nop 0
	global_load_lds_dwordx4 v[208:209], off
	v_lshl_add_u64 v[208:209], v[214:215], 0, s[12:13]
	s_mov_b32 m0, s74
	s_nop 0
	global_load_lds_dwordx4 v[208:209], off
	s_waitcnt vmcnt(8)
	s_waitcnt lgkmcnt(0)
	s_barrier
	v_mfma_f32_16x16x32_bf16 v[60:63], v[104:107], v[160:163], v[60:63]
	v_mfma_f32_16x16x32_bf16 v[56:59], v[120:123], v[160:163], v[56:59]
	v_mfma_f32_16x16x32_bf16 v[44:47], v[104:107], v[168:171], v[44:47]
	v_mfma_f32_16x16x32_bf16 v[40:43], v[120:123], v[168:171], v[40:43]
	v_mfma_f32_16x16x32_bf16 v[28:31], v[104:107], v[176:179], v[28:31]
	v_mfma_f32_16x16x32_bf16 v[24:27], v[120:123], v[176:179], v[24:27]
	v_mfma_f32_16x16x32_bf16 v[12:15], v[104:107], v[184:187], v[12:15]
	v_mfma_f32_16x16x32_bf16 v[8:11], v[120:123], v[184:187], v[8:11]
	v_mfma_f32_16x16x32_bf16 v[60:63], v[108:111], v[164:167], v[60:63]
	v_mfma_f32_16x16x32_bf16 v[56:59], v[124:127], v[164:167], v[56:59]
	v_mfma_f32_16x16x32_bf16 v[44:47], v[108:111], v[172:175], v[44:47]
	v_mfma_f32_16x16x32_bf16 v[40:43], v[124:127], v[172:175], v[40:43]
	v_mfma_f32_16x16x32_bf16 v[28:31], v[108:111], v[180:183], v[28:31]
	v_mfma_f32_16x16x32_bf16 v[24:27], v[124:127], v[180:183], v[24:27]
	v_mfma_f32_16x16x32_bf16 v[12:15], v[108:111], v[188:191], v[12:15]
	v_mfma_f32_16x16x32_bf16 v[8:11], v[124:127], v[188:191], v[8:11]
	v_mfma_f32_16x16x32_bf16 v[52:55], v[136:139], v[160:163], v[52:55]
	v_mfma_f32_16x16x32_bf16 v[48:51], v[152:155], v[160:163], v[48:51]
	v_mfma_f32_16x16x32_bf16 v[36:39], v[136:139], v[168:171], v[36:39]
	v_mfma_f32_16x16x32_bf16 v[32:35], v[152:155], v[168:171], v[32:35]
	v_mfma_f32_16x16x32_bf16 v[20:23], v[136:139], v[176:179], v[20:23]
	v_mfma_f32_16x16x32_bf16 v[16:19], v[152:155], v[176:179], v[16:19]
	v_mfma_f32_16x16x32_bf16 v[4:7], v[136:139], v[184:187], v[4:7]
	v_mfma_f32_16x16x32_bf16 v[0:3], v[152:155], v[184:187], v[0:3]
	v_mfma_f32_16x16x32_bf16 v[52:55], v[140:143], v[164:167], v[52:55]
	v_mfma_f32_16x16x32_bf16 v[48:51], v[156:159], v[164:167], v[48:51]
	v_mfma_f32_16x16x32_bf16 v[36:39], v[140:143], v[172:175], v[36:39]
	v_mfma_f32_16x16x32_bf16 v[32:35], v[156:159], v[172:175], v[32:35]
	v_mfma_f32_16x16x32_bf16 v[20:23], v[140:143], v[180:183], v[20:23]
	v_mfma_f32_16x16x32_bf16 v[16:19], v[156:159], v[180:183], v[16:19]
	v_mfma_f32_16x16x32_bf16 v[4:7], v[140:143], v[188:191], v[4:7]
	v_mfma_f32_16x16x32_bf16 v[0:3], v[156:159], v[188:191], v[0:3]
	s_barrier
	s_add_u32 s38, s38, 0x100
	s_addc_u32 s39, s39, 0
	s_add_u32 s48, s48, 0x100
	s_addc_u32 s49, s49, 0
	s_cmp_ge_u32 s50, s31
	s_mov_b32 s42, s50
	s_cbranch_scc0 .LBB0_632

; #define PG8_STAGE(bufoff, gbase, voff) do { _Pragma("unroll") for (int _i = 0; _i < 2; ++_i) \
;         __builtin_amdgcn_global_load_lds((const unsigned*)((const char*)(gbase) + (voff)[_i]), (LAS unsigned*)(lds + (bufoff) + ldsw + _i * 8192), 16, 0, 0); } while (0)
; #define PG8_LDA(dst, b, h) do { _Pragma("unroll") for (int m = 0; m < 4; ++m) _Pragma("unroll") for (int k = 0; k < 2; ++k) dst[m][k] = *(const LAS bf16x8*)(lds + PG8_SA(b, h) + aoff + m * 2048 + k * 1024); } while (0)
; #define PG8_LDB(dst, b, h) do { _Pragma("unroll") for (int n = 0; n < 2; ++n) _Pragma("unroll") for (int k = 0; k < 2; ++k) dst[n][k] = *(const LAS bf16x8*)(lds + PG8_SB(b, h) + boff + n * 2048 + k * 1024); } while (0)
; #define PG8_WAIT_V(n) asm volatile("s_waitcnt vmcnt(" #n ")" ::: "memory")
; #define PG8_BAR __builtin_amdgcn_s_barrier()
; template <class Epi, class Sched = StaticOrder, class EpiSub = NoSub, bool FAST = false>
; __device__ __forceinline__ void gemm_phase(LAS unsigned char* lds, const Gemm g, const Sched& S, const Epi& E, const EpiSub& ES = EpiSub()) {
;     ...
;         const bool has_next = S.next(ui + 1, nxt);
;         const size_t nko = (has_next && nxt.kb >= 0) ? nxt.kb * ksubB : 0;
;         const char* nA = has_next ? (const char*)g.A + (size_t)nxt.pm * tstepA + (size_t)nxt.pn * g.acs + nko : cA; const char* nB = has_next ? (const char*)g.Bt + (size_t)nxt.pn * tstepB + nko : cB;
;         const int nt = cur.kb < 0 ? ntMain : ntSub;
;         for (int t = 0; t < nt; t += 2) {
;             const bool last = (t == nt - 2);
;             const char* a1 = cA + (size_t)(t + 1) * kstep;
;             const char* a2 = last ? nA : cA + (size_t)(t + 2) * kstep; const char* b2 = last ? nB : cB + (size_t)(t + 2) * kstep;
;             const char* a3 = a2 + kstep; const char* b3 = b2 + kstep;
;             if constexpr (FAST && PG8_SP2) {
;             PG8_LDB(B0, 0, 0); PG8_LDB(B1, 0, 1); PG8_SCHED; PG8_LDA(At, 0, 0); PG8_STAGE(PG8_SA(1, 1), a1 + hstepA, voffA);
;             PG8_WAIT_V(8); PG8_WAIT_L(0); PG8_BAR; PG8_MMA(0, 0, At, B0); PG8_MMA(0, 1, At, B1); PG8_BAR; PG8_SCHED;
;             PG8_LDA(At, 0, 1); PG8_STAGE(PG8_SB(0, 0), b2, voffB); PG8_STAGE(PG8_SB(0, 1), b2 + hstepB, voffB); PG8_STAGE(PG8_SA(0, 0), a2, voffA);
;             PG8_WAIT_V(8); PG8_WAIT_L(0); PG8_BAR; PG8_MMA(1, 0, At, B0); PG8_MMA(1, 1, At, B1); PG8_BAR; PG8_SCHED;
.LBB0_768:
	s_cmp_gt_i32 s6, -1
	s_cselect_b64 s[24:25], -1, 0
	s_and_b64 s[24:25], s[22:23], s[24:25]
	s_lshl_b64 s[26:27], s[6:7], 9
	s_and_b64 s[24:25], s[24:25], exec
	s_cselect_b32 s29, s27, 0
	s_cselect_b32 s30, s26, 0
	s_ashr_i32 s21, s20, 31
	s_lshl_b64 s[24:25], s[20:21], 20
	s_add_u32 s1, s84, s24
	s_addc_u32 s5, s85, s25
	s_add_u32 s24, s1, s30
	s_addc_u32 s25, s5, s29
	s_and_b64 s[26:27], s[22:23], exec
	s_cselect_b32 s1, s25, s39
	s_cselect_b32 s5, s24, s38
	s_ashr_i32 s19, s18, 31
	s_lshl_b64 s[26:27], s[18:19], 20
	s_add_u32 s19, s2, s26
	s_addc_u32 s21, s3, s27
	s_add_u32 s26, s19, s30
	s_addc_u32 s27, s21, s29
	s_and_b64 s[30:31], s[22:23], exec
	s_cselect_b32 s19, s27, s41
	s_cselect_b32 s21, s26, s40
	s_cmp_gt_i32 s4, -1
	s_cselect_b64 s[30:31], -1, 0
	s_cmp_lt_i32 s4, 0
	s_cselect_b32 s29, 32, 4
	s_add_i32 s33, s29, -2
	s_add_u32 s38, s38, 0x80080
	s_addc_u32 s39, s39, 0
	s_add_u32 s70, s40, 0x100
	s_mov_b32 s42, 0
	s_addc_u32 s71, s41, 0
	ds_read_b128 v[96:99], v215
	ds_read_b128 v[100:103], v215 offset:1024
	ds_read_b128 v[112:115], v215 offset:2048
	ds_read_b128 v[116:119], v215 offset:3072
	ds_read_b128 v[144:147], v216
	ds_read_b128 v[148:151], v216 offset:1024
	ds_read_b128 v[152:155], v216 offset:2048
	ds_read_b128 v[156:159], v216 offset:3072
	s_add_i32 s72, s42, 2
	s_add_u32 s40, s38, 0xfff80080
	s_addc_u32 s41, s39, -1
	s_cmp_eq_u32 s33, s42
	s_cselect_b32 s42, s5, s40
	s_cselect_b32 s43, s1, s41
	s_cselect_b32 s41, s19, s71
	s_cselect_b32 s40, s21, s70
	v_lshl_add_u64 v[208:209], s[38:39], 0, v[194:195]
	s_add_i32 m0, s48, 0xc000
	ds_read_b128 v[160:163], v217
	ds_read_b128 v[164:167], v217 offset:1024
	ds_read_b128 v[168:171], v217 offset:2048
	ds_read_b128 v[172:175], v217 offset:3072
	ds_read_b128 v[176:179], v217 offset:4096
	ds_read_b128 v[180:183], v217 offset:5120
	ds_read_b128 v[200:203], v217 offset:6144
	ds_read_b128 v[204:207], v217 offset:7168
	global_load_lds_dwordx4 v[208:209], off
	v_lshl_add_u64 v[208:209], s[38:39], 0, v[196:197]
	s_add_i32 m0, s48, 0xe000
	s_nop 0
	global_load_lds_dwordx4 v[208:209], off
	s_waitcnt vmcnt(8)
	s_waitcnt lgkmcnt(0)
	s_barrier
	v_mfma_f32_16x16x32_bf16 v[140:143], v[96:99], v[160:163], 0
	v_mfma_f32_16x16x32_bf16 v[136:139], v[112:115], v[160:163], 0
	v_mfma_f32_16x16x32_bf16 v[124:127], v[96:99], v[168:171], 0
	v_mfma_f32_16x16x32_bf16 v[120:123], v[112:115], v[168:171], 0
	v_mfma_f32_16x16x32_bf16 v[92:95], v[96:99], v[176:179], 0
	v_mfma_f32_16x16x32_bf16 v[88:91], v[112:115], v[176:179], 0
	v_mfma_f32_16x16x32_bf16 v[76:79], v[96:99], v[200:203], 0
	v_mfma_f32_16x16x32_bf16 v[72:75], v[112:115], v[200:203], 0
	v_mfma_f32_16x16x32_bf16 v[140:143], v[100:103], v[164:167], v[140:143]
	v_mfma_f32_16x16x32_bf16 v[136:139], v[116:119], v[164:167], v[136:139]
	v_mfma_f32_16x16x32_bf16 v[124:127], v[100:103], v[172:175], v[124:127]
	v_mfma_f32_16x16x32_bf16 v[120:123], v[116:119], v[172:175], v[120:123]
	v_mfma_f32_16x16x32_bf16 v[92:95], v[100:103], v[180:183], v[92:95]
	v_mfma_f32_16x16x32_bf16 v[88:91], v[116:119], v[180:183], v[88:91]
	v_mfma_f32_16x16x32_bf16 v[76:79], v[100:103], v[204:207], v[76:79]
	v_mfma_f32_16x16x32_bf16 v[72:75], v[116:119], v[204:207], v[72:75]
	v_mfma_f32_16x16x32_bf16 v[132:135], v[144:147], v[160:163], 0
	v_mfma_f32_16x16x32_bf16 v[128:131], v[152:155], v[160:163], 0
	v_mfma_f32_16x16x32_bf16 v[108:111], v[144:147], v[168:171], 0
	v_mfma_f32_16x16x32_bf16 v[104:107], v[152:155], v[168:171], 0
	v_mfma_f32_16x16x32_bf16 v[84:87], v[144:147], v[176:179], 0
	v_mfma_f32_16x16x32_bf16 v[80:83], v[152:155], v[176:179], 0
	v_mfma_f32_16x16x32_bf16 v[68:71], v[144:147], v[200:203], 0
	v_mfma_f32_16x16x32_bf16 v[64:67], v[152:155], v[200:203], 0
	v_mfma_f32_16x16x32_bf16 v[132:135], v[148:151], v[164:167], v[132:135]
	v_mfma_f32_16x16x32_bf16 v[128:131], v[156:159], v[164:167], v[128:131]
	v_mfma_f32_16x16x32_bf16 v[108:111], v[148:151], v[172:175], v[108:111]
	v_mfma_f32_16x16x32_bf16 v[104:107], v[156:159], v[172:175], v[104:107]
	v_mfma_f32_16x16x32_bf16 v[84:87], v[148:151], v[180:183], v[84:87]
	v_mfma_f32_16x16x32_bf16 v[80:83], v[156:159], v[180:183], v[80:83]
	v_mfma_f32_16x16x32_bf16 v[68:71], v[148:151], v[204:207], v[68:71]
	v_mfma_f32_16x16x32_bf16 v[64:67], v[156:159], v[204:207], v[64:67]
	s_barrier
	s_add_i32 s73, s58, s17
	v_lshl_add_u64 v[208:209], s[40:41], 0, v[186:187]
	s_mov_b32 m0, s73
	ds_read_b128 v[160:163], v217 offset:16384
	ds_read_b128 v[164:167], v217 offset:17408
	ds_read_b128 v[168:171], v217 offset:18432
	ds_read_b128 v[172:175], v217 offset:19456
	ds_read_b128 v[176:179], v217 offset:20480
	ds_read_b128 v[180:183], v217 offset:21504
	ds_read_b128 v[200:203], v217 offset:22528
	ds_read_b128 v[204:207], v217 offset:23552
	global_load_lds_dwordx4 v[208:209], off
	s_add_i32 m0, s73, 0x2000
	s_add_u32 s76, s40, 0x80000
	v_lshl_add_u64 v[210:211], s[40:41], 0, v[190:191]
	s_addc_u32 s77, s41, 0
	s_add_i32 s73, s59, s17
	global_load_lds_dwordx4 v[210:211], off
	v_lshl_add_u64 v[218:219], s[76:77], 0, v[186:187]
	s_mov_b32 m0, s73
	v_lshl_add_u64 v[220:221], s[42:43], 0, v[188:189]
	global_load_lds_dwordx4 v[218:219], off
	v_lshl_add_u64 v[218:219], s[76:77], 0, v[190:191]
	s_add_i32 m0, s73, 0x2000
	s_nop 0
	global_load_lds_dwordx4 v[218:219], off
	v_lshl_add_u64 v[218:219], s[42:43], 0, v[184:185]
	s_mov_b32 m0, s48
	s_nop 0
	global_load_lds_dwordx4 v[218:219], off
	s_mov_b32 m0, s49
	s_nop 0
	global_load_lds_dwordx4 v[220:221], off
	s_waitcnt vmcnt(8)
	s_waitcnt lgkmcnt(0)
	s_barrier
; #define PG8_STAGE(bufoff, gbase, voff) do { _Pragma("unroll") for (int _i = 0; _i < 2; ++_i) \
;         __builtin_amdgcn_global_load_lds((const unsigned*)((const char*)(gbase) + (voff)[_i]), (LAS unsigned*)(lds + (bufoff) + ldsw + _i * 8192), 16, 0, 0); } while (0)
; #define PG8_LDA(dst, b, h) do { _Pragma("unroll") for (int m = 0; m < 4; ++m) _Pragma("unroll") for (int k = 0; k < 2; ++k) dst[m][k] = *(const LAS bf16x8*)(lds + PG8_SA(b, h) + aoff + m * 2048 + k * 1024); } while (0)
; #define PG8_LDB(dst, b, h) do { _Pragma("unroll") for (int n = 0; n < 2; ++n) _Pragma("unroll") for (int k = 0; k < 2; ++k) dst[n][k] = *(const LAS bf16x8*)(lds + PG8_SB(b, h) + boff + n * 2048 + k * 1024); } while (0)
; #define PG8_MMA(ai, bj, At, Bt) do { __builtin_amdgcn_s_setprio(1); _Pragma("unroll") for (int m = 0; m < 4; ++m) _Pragma("unroll") for (int n = 0; n < 2; ++n) _Pragma("unroll") for (int k = 0; k < 2; ++k) \
;         acc[ai][bj][m][n] = __builtin_amdgcn_mfma_f32_16x16x32_bf16(Bt[n][k], At[m][k], acc[ai][bj][m][n], 0, 0, 0); __builtin_amdgcn_s_setprio(0); } while (0)
; #define PG8_WAIT_V(n) asm volatile("s_waitcnt vmcnt(" #n ")" ::: "memory")
; #define PG8_WAIT_L(n) asm volatile("s_waitcnt lgkmcnt(" #n ")" ::: "memory")
; #define PG8_BAR __builtin_amdgcn_s_barrier()
; #define PG8_SCHED __builtin_amdgcn_sched_barrier(0)
; template <class Epi, class Sched = StaticOrder, class EpiSub = NoSub, bool FAST = false>
; __device__ __forceinline__ void gemm_phase(LAS unsigned char* lds, const Gemm g, const Sched& S, const Epi& E, const EpiSub& ES = EpiSub()) {
;     ...
;             PG8_WAIT_V(8); PG8_WAIT_L(0); PG8_BAR; PG8_MMA(1, 0, At, B0); PG8_MMA(1, 1, At, B1); PG8_BAR; PG8_SCHED;
;             PG8_LDB(B0, 1, 0); PG8_LDB(B1, 1, 1); PG8_SCHED; PG8_LDA(At, 1, 0); PG8_STAGE(PG8_SA(0, 1), a2 + hstepA, voffA);
;             PG8_WAIT_V(8); PG8_WAIT_L(0); PG8_BAR; PG8_MMA(0, 0, At, B0); PG8_MMA(0, 1, At, B1); PG8_BAR; PG8_SCHED;
	v_mfma_f32_16x16x32_bf16 v[60:63], v[96:99], v[160:163], 0
	v_mfma_f32_16x16x32_bf16 v[56:59], v[112:115], v[160:163], 0
	v_mfma_f32_16x16x32_bf16 v[44:47], v[96:99], v[168:171], 0
	v_mfma_f32_16x16x32_bf16 v[40:43], v[112:115], v[168:171], 0
	v_mfma_f32_16x16x32_bf16 v[28:31], v[96:99], v[176:179], 0
	v_mfma_f32_16x16x32_bf16 v[24:27], v[112:115], v[176:179], 0
	v_mfma_f32_16x16x32_bf16 v[12:15], v[96:99], v[200:203], 0
	v_mfma_f32_16x16x32_bf16 v[8:11], v[112:115], v[200:203], 0
	v_mfma_f32_16x16x32_bf16 v[60:63], v[100:103], v[164:167], v[60:63]
	v_mfma_f32_16x16x32_bf16 v[56:59], v[116:119], v[164:167], v[56:59]
	v_mfma_f32_16x16x32_bf16 v[44:47], v[100:103], v[172:175], v[44:47]
	v_mfma_f32_16x16x32_bf16 v[40:43], v[116:119], v[172:175], v[40:43]
	v_mfma_f32_16x16x32_bf16 v[28:31], v[100:103], v[180:183], v[28:31]
	v_mfma_f32_16x16x32_bf16 v[24:27], v[116:119], v[180:183], v[24:27]
	v_mfma_f32_16x16x32_bf16 v[12:15], v[100:103], v[204:207], v[12:15]
	v_mfma_f32_16x16x32_bf16 v[8:11], v[116:119], v[204:207], v[8:11]
	v_mfma_f32_16x16x32_bf16 v[52:55], v[144:147], v[160:163], 0
	v_mfma_f32_16x16x32_bf16 v[48:51], v[152:155], v[160:163], 0
	v_mfma_f32_16x16x32_bf16 v[36:39], v[144:147], v[168:171], 0
	v_mfma_f32_16x16x32_bf16 v[32:35], v[152:155], v[168:171], 0
	v_mfma_f32_16x16x32_bf16 v[20:23], v[144:147], v[176:179], 0
	v_mfma_f32_16x16x32_bf16 v[16:19], v[152:155], v[176:179], 0
	v_mfma_f32_16x16x32_bf16 v[4:7], v[144:147], v[200:203], 0
	v_mfma_f32_16x16x32_bf16 v[0:3], v[152:155], v[200:203], 0
	v_mfma_f32_16x16x32_bf16 v[52:55], v[148:151], v[164:167], v[52:55]
	v_mfma_f32_16x16x32_bf16 v[48:51], v[156:159], v[164:167], v[48:51]
	v_mfma_f32_16x16x32_bf16 v[36:39], v[148:151], v[172:175], v[36:39]
	v_mfma_f32_16x16x32_bf16 v[32:35], v[156:159], v[172:175], v[32:35]
	v_mfma_f32_16x16x32_bf16 v[20:23], v[148:151], v[180:183], v[20:23]
	v_mfma_f32_16x16x32_bf16 v[16:19], v[156:159], v[180:183], v[16:19]
	v_mfma_f32_16x16x32_bf16 v[4:7], v[148:151], v[204:207], v[4:7]
	v_mfma_f32_16x16x32_bf16 v[0:3], v[156:159], v[204:207], v[0:3]
	s_barrier
	s_add_i32 s73, 0, 0x18000
	s_add_i32 s76, 0, 0x1c000
	v_add_u32_e32 v116, s73, v212
	v_add_u32_e32 v156, s76, v212
	ds_read_b128 v[96:99], v116
	ds_read_b128 v[100:103], v116 offset:1024
	ds_read_b128 v[112:115], v116 offset:2048
	ds_read_b128 v[116:119], v116 offset:3072
	ds_read_b128 v[144:147], v156
	ds_read_b128 v[148:151], v156 offset:1024
	ds_read_b128 v[152:155], v156 offset:2048
	ds_read_b128 v[156:159], v156 offset:3072
	s_add_u32 s42, s42, 0x80000
	s_addc_u32 s43, s43, 0
	s_mov_b32 m0, s50
	v_lshl_add_u64 v[222:223], s[42:43], 0, v[184:185]
	ds_read_b128 v[160:163], v217 offset:32768
	ds_read_b128 v[164:167], v217 offset:33792
	ds_read_b128 v[168:171], v217 offset:34816
	ds_read_b128 v[172:175], v217 offset:35840
	ds_read_b128 v[176:179], v217 offset:36864
	ds_read_b128 v[180:183], v217 offset:37888
	ds_read_b128 v[200:203], v217 offset:38912
	ds_read_b128 v[204:207], v217 offset:39936
	global_load_lds_dwordx4 v[222:223], off
	v_lshl_add_u64 v[222:223], s[42:43], 0, v[188:189]
	s_mov_b32 m0, s51
	s_nop 0
	global_load_lds_dwordx4 v[222:223], off
	s_waitcnt vmcnt(8)
	s_waitcnt lgkmcnt(0)
	s_barrier
	v_mfma_f32_16x16x32_bf16 v[140:143], v[96:99], v[160:163], v[140:143]
	v_mfma_f32_16x16x32_bf16 v[136:139], v[112:115], v[160:163], v[136:139]
	v_mfma_f32_16x16x32_bf16 v[124:127], v[96:99], v[168:171], v[124:127]
	v_mfma_f32_16x16x32_bf16 v[120:123], v[112:115], v[168:171], v[120:123]
	v_mfma_f32_16x16x32_bf16 v[92:95], v[96:99], v[176:179], v[92:95]
	v_mfma_f32_16x16x32_bf16 v[88:91], v[112:115], v[176:179], v[88:91]
	v_mfma_f32_16x16x32_bf16 v[76:79], v[96:99], v[200:203], v[76:79]
	v_mfma_f32_16x16x32_bf16 v[72:75], v[112:115], v[200:203], v[72:75]
	v_mfma_f32_16x16x32_bf16 v[140:143], v[100:103], v[164:167], v[140:143]
	v_mfma_f32_16x16x32_bf16 v[136:139], v[116:119], v[164:167], v[136:139]
	v_mfma_f32_16x16x32_bf16 v[124:127], v[100:103], v[172:175], v[124:127]
	v_mfma_f32_16x16x32_bf16 v[120:123], v[116:119], v[172:175], v[120:123]
	v_mfma_f32_16x16x32_bf16 v[92:95], v[100:103], v[180:183], v[92:95]
	v_mfma_f32_16x16x32_bf16 v[88:91], v[116:119], v[180:183], v[88:91]
	v_mfma_f32_16x16x32_bf16 v[76:79], v[100:103], v[204:207], v[76:79]
	v_mfma_f32_16x16x32_bf16 v[72:75], v[116:119], v[204:207], v[72:75]
	v_mfma_f32_16x16x32_bf16 v[132:135], v[144:147], v[160:163], v[132:135]
	v_mfma_f32_16x16x32_bf16 v[128:131], v[152:155], v[160:163], v[128:131]
	v_mfma_f32_16x16x32_bf16 v[108:111], v[144:147], v[168:171], v[108:111]
	v_mfma_f32_16x16x32_bf16 v[104:107], v[152:155], v[168:171], v[104:107]
	v_mfma_f32_16x16x32_bf16 v[84:87], v[144:147], v[176:179], v[84:87]
	v_mfma_f32_16x16x32_bf16 v[80:83], v[152:155], v[176:179], v[80:83]
	v_mfma_f32_16x16x32_bf16 v[68:71], v[144:147], v[200:203], v[68:71]
	v_mfma_f32_16x16x32_bf16 v[64:67], v[152:155], v[200:203], v[64:67]
	v_mfma_f32_16x16x32_bf16 v[132:135], v[148:151], v[164:167], v[132:135]
	v_mfma_f32_16x16x32_bf16 v[128:131], v[156:159], v[164:167], v[128:131]
	v_mfma_f32_16x16x32_bf16 v[108:111], v[148:151], v[172:175], v[108:111]
	v_mfma_f32_16x16x32_bf16 v[104:107], v[156:159], v[172:175], v[104:107]
	v_mfma_f32_16x16x32_bf16 v[84:87], v[148:151], v[180:183], v[84:87]
	v_mfma_f32_16x16x32_bf16 v[80:83], v[156:159], v[180:183], v[80:83]
	v_mfma_f32_16x16x32_bf16 v[68:71], v[148:151], v[204:207], v[68:71]
	v_mfma_f32_16x16x32_bf16 v[64:67], v[156:159], v[204:207], v[64:67]
	s_barrier
; #define PG8_STAGE(bufoff, gbase, voff) do { _Pragma("unroll") for (int _i = 0; _i < 2; ++_i) \
;         __builtin_amdgcn_global_load_lds((const unsigned*)((const char*)(gbase) + (voff)[_i]), (LAS unsigned*)(lds + (bufoff) + ldsw + _i * 8192), 16, 0, 0); } while (0)
; #define PG8_LDA(dst, b, h) do { _Pragma("unroll") for (int m = 0; m < 4; ++m) _Pragma("unroll") for (int k = 0; k < 2; ++k) dst[m][k] = *(const LAS bf16x8*)(lds + PG8_SA(b, h) + aoff + m * 2048 + k * 1024); } while (0)
; #define PG8_LDB(dst, b, h) do { _Pragma("unroll") for (int n = 0; n < 2; ++n) _Pragma("unroll") for (int k = 0; k < 2; ++k) dst[n][k] = *(const LAS bf16x8*)(lds + PG8_SB(b, h) + boff + n * 2048 + k * 1024); } while (0)
; template <class Epi, class Sched = StaticOrder, class EpiSub = NoSub, bool FAST = false>
; __device__ __forceinline__ void gemm_phase(LAS unsigned char* lds, const Gemm g, const Sched& S, const Epi& E, const EpiSub& ES = EpiSub()) {
;     ...
;         for (int t = 0; t < nt; t += 2) {
;             const bool last = (t == nt - 2);
;             const char* a1 = cA + (size_t)(t + 1) * kstep;
;             const char* a2 = last ? nA : cA + (size_t)(t + 2) * kstep; const char* b2 = last ? nB : cB + (size_t)(t + 2) * kstep;
;             const char* a3 = a2 + kstep; const char* b3 = b2 + kstep;
;             if constexpr (FAST && PG8_SP2) {
;             PG8_LDB(B0, 0, 0); PG8_LDB(B1, 0, 1); PG8_SCHED; PG8_LDA(At, 0, 0); PG8_STAGE(PG8_SA(1, 1), a1 + hstepA, voffA);
;             PG8_WAIT_V(8); PG8_WAIT_L(0); PG8_BAR; PG8_MMA(0, 0, At, B0); PG8_MMA(0, 1, At, B1); PG8_BAR; PG8_SCHED;
;             PG8_LDA(At, 0, 1); PG8_STAGE(PG8_SB(0, 0), b2, voffB); PG8_STAGE(PG8_SB(0, 1), b2 + hstepB, voffB); PG8_STAGE(PG8_SA(0, 0), a2, voffA);
;             PG8_WAIT_V(8); PG8_WAIT_L(0); PG8_BAR; PG8_MMA(1, 0, At, B0); PG8_MMA(1, 1, At, B1); PG8_BAR; PG8_SCHED;
;             PG8_LDB(B0, 1, 0); PG8_LDB(B1, 1, 1); PG8_SCHED; PG8_LDA(At, 1, 0); PG8_STAGE(PG8_SA(0, 1), a2 + hstepA, voffA);
;             PG8_WAIT_V(8); PG8_WAIT_L(0); PG8_BAR; PG8_MMA(0, 0, At, B0); PG8_MMA(0, 1, At, B1); PG8_BAR; PG8_SCHED;
;             PG8_LDA(At, 1, 1); PG8_STAGE(PG8_SB(1, 0), b3, voffB); PG8_STAGE(PG8_SB(1, 1), b3 + hstepB, voffB); PG8_STAGE(PG8_SA(1, 0), a3, voffA);
;             PG8_WAIT_V(8); PG8_WAIT_L(0); PG8_BAR; PG8_MMA(1, 0, At, B0); PG8_MMA(1, 1, At, B1); PG8_BAR; PG8_SCHED;
	s_add_i32 s42, s73, s17
	v_lshl_add_u64 v[208:209], v[208:209], 0, s[12:13]
	s_mov_b32 m0, s42
	ds_read_b128 v[160:163], v217 offset:49152
	ds_read_b128 v[164:167], v217 offset:50176
	ds_read_b128 v[168:171], v217 offset:51200
	ds_read_b128 v[172:175], v217 offset:52224
	ds_read_b128 v[176:179], v217 offset:53248
	ds_read_b128 v[180:183], v217 offset:54272
	ds_read_b128 v[200:203], v217 offset:55296
	ds_read_b128 v[204:207], v217 offset:56320
	global_load_lds_dwordx4 v[208:209], off
	s_add_i32 m0, s42, 0x2000
	s_add_u32 s40, s40, 0x80080
	v_lshl_add_u64 v[208:209], v[210:211], 0, s[12:13]
	s_addc_u32 s41, s41, 0
	s_add_i32 s42, s76, s17
	global_load_lds_dwordx4 v[208:209], off
	v_lshl_add_u64 v[208:209], s[40:41], 0, v[186:187]
	s_mov_b32 m0, s42
	s_nop 0
	global_load_lds_dwordx4 v[208:209], off
	v_lshl_add_u64 v[208:209], s[40:41], 0, v[190:191]
	s_add_i32 m0, s42, 0x2000
	s_nop 0
	global_load_lds_dwordx4 v[208:209], off
	v_lshl_add_u64 v[208:209], v[218:219], 0, s[12:13]
	s_mov_b32 m0, s55
	s_nop 0
	global_load_lds_dwordx4 v[208:209], off
	v_lshl_add_u64 v[208:209], v[220:221], 0, s[12:13]
	s_mov_b32 m0, s56
	s_nop 0
	global_load_lds_dwordx4 v[208:209], off
	s_waitcnt vmcnt(8)
	s_waitcnt lgkmcnt(0)
	s_barrier
	v_mfma_f32_16x16x32_bf16 v[60:63], v[96:99], v[160:163], v[60:63]
	v_mfma_f32_16x16x32_bf16 v[56:59], v[112:115], v[160:163], v[56:59]
	v_mfma_f32_16x16x32_bf16 v[44:47], v[96:99], v[168:171], v[44:47]
	v_mfma_f32_16x16x32_bf16 v[40:43], v[112:115], v[168:171], v[40:43]
	v_mfma_f32_16x16x32_bf16 v[28:31], v[96:99], v[176:179], v[28:31]
	v_mfma_f32_16x16x32_bf16 v[24:27], v[112:115], v[176:179], v[24:27]
	v_mfma_f32_16x16x32_bf16 v[12:15], v[96:99], v[200:203], v[12:15]
	v_mfma_f32_16x16x32_bf16 v[8:11], v[112:115], v[200:203], v[8:11]
	v_mfma_f32_16x16x32_bf16 v[60:63], v[100:103], v[164:167], v[60:63]
	v_mfma_f32_16x16x32_bf16 v[56:59], v[116:119], v[164:167], v[56:59]
	v_mfma_f32_16x16x32_bf16 v[44:47], v[100:103], v[172:175], v[44:47]
	v_mfma_f32_16x16x32_bf16 v[40:43], v[116:119], v[172:175], v[40:43]
	v_mfma_f32_16x16x32_bf16 v[28:31], v[100:103], v[180:183], v[28:31]
	v_mfma_f32_16x16x32_bf16 v[24:27], v[116:119], v[180:183], v[24:27]
	v_mfma_f32_16x16x32_bf16 v[12:15], v[100:103], v[204:207], v[12:15]
	v_mfma_f32_16x16x32_bf16 v[8:11], v[116:119], v[204:207], v[8:11]
	v_mfma_f32_16x16x32_bf16 v[52:55], v[144:147], v[160:163], v[52:55]
	v_mfma_f32_16x16x32_bf16 v[48:51], v[152:155], v[160:163], v[48:51]
	v_mfma_f32_16x16x32_bf16 v[36:39], v[144:147], v[168:171], v[36:39]
	v_mfma_f32_16x16x32_bf16 v[32:35], v[152:155], v[168:171], v[32:35]
	v_mfma_f32_16x16x32_bf16 v[20:23], v[144:147], v[176:179], v[20:23]
	v_mfma_f32_16x16x32_bf16 v[16:19], v[152:155], v[176:179], v[16:19]
	v_mfma_f32_16x16x32_bf16 v[4:7], v[144:147], v[200:203], v[4:7]
	v_mfma_f32_16x16x32_bf16 v[0:3], v[152:155], v[200:203], v[0:3]
	v_mfma_f32_16x16x32_bf16 v[52:55], v[148:151], v[164:167], v[52:55]
	v_mfma_f32_16x16x32_bf16 v[48:51], v[156:159], v[164:167], v[48:51]
	v_mfma_f32_16x16x32_bf16 v[36:39], v[148:151], v[172:175], v[36:39]
	v_mfma_f32_16x16x32_bf16 v[32:35], v[156:159], v[172:175], v[32:35]
	v_mfma_f32_16x16x32_bf16 v[20:23], v[148:151], v[180:183], v[20:23]
	v_mfma_f32_16x16x32_bf16 v[16:19], v[156:159], v[180:183], v[16:19]
	v_mfma_f32_16x16x32_bf16 v[4:7], v[148:151], v[204:207], v[4:7]
	v_mfma_f32_16x16x32_bf16 v[0:3], v[156:159], v[204:207], v[0:3]
	s_barrier
	s_add_u32 s38, s38, 0x100
	s_addc_u32 s39, s39, 0
	s_add_u32 s70, s70, 0x100
	s_addc_u32 s71, s71, 0
	s_cmp_ge_u32 s72, s29
	s_mov_b32 s42, s72
	s_cbranch_scc1 .Lkpeel_769_exit
.LBB0_769:
	ds_read_b128 v[96:99], v215
	ds_read_b128 v[100:103], v215 offset:1024
	ds_read_b128 v[112:115], v215 offset:2048
	ds_read_b128 v[116:119], v215 offset:3072
	ds_read_b128 v[144:147], v216
	ds_read_b128 v[148:151], v216 offset:1024
	ds_read_b128 v[152:155], v216 offset:2048
	ds_read_b128 v[156:159], v216 offset:3072
	s_add_i32 s72, s42, 2
	s_add_u32 s40, s38, 0xfff80080
	s_addc_u32 s41, s39, -1
	s_cmp_eq_u32 s33, s42
	s_cselect_b32 s42, s5, s40
	s_cselect_b32 s43, s1, s41
	s_cselect_b32 s41, s19, s71
	s_cselect_b32 s40, s21, s70
	v_lshl_add_u64 v[208:209], s[38:39], 0, v[194:195]
	s_add_i32 m0, s48, 0xc000
	ds_read_b128 v[160:163], v217
	ds_read_b128 v[164:167], v217 offset:1024
	ds_read_b128 v[168:171], v217 offset:2048
	ds_read_b128 v[172:175], v217 offset:3072
	ds_read_b128 v[176:179], v217 offset:4096
	ds_read_b128 v[180:183], v217 offset:5120
	ds_read_b128 v[200:203], v217 offset:6144
	ds_read_b128 v[204:207], v217 offset:7168
	global_load_lds_dwordx4 v[208:209], off
	v_lshl_add_u64 v[208:209], s[38:39], 0, v[196:197]
	s_add_i32 m0, s48, 0xe000
	s_nop 0
	global_load_lds_dwordx4 v[208:209], off
	s_waitcnt vmcnt(8)
	s_waitcnt lgkmcnt(0)
	s_barrier
; #define PG8_STAGE(bufoff, gbase, voff) do { _Pragma("unroll") for (int _i = 0; _i < 2; ++_i) \
;         __builtin_amdgcn_global_load_lds((const unsigned*)((const char*)(gbase) + (voff)[_i]), (LAS unsigned*)(lds + (bufoff) + ldsw + _i * 8192), 16, 0, 0); } while (0)
; #define PG8_LDA(dst, b, h) do { _Pragma("unroll") for (int m = 0; m < 4; ++m) _Pragma("unroll") for (int k = 0; k < 2; ++k) dst[m][k] = *(const LAS bf16x8*)(lds + PG8_SA(b, h) + aoff + m * 2048 + k * 1024); } while (0)
; #define PG8_MMA(ai, bj, At, Bt) do { __builtin_amdgcn_s_setprio(1); _Pragma("unroll") for (int m = 0; m < 4; ++m) _Pragma("unroll") for (int n = 0; n < 2; ++n) _Pragma("unroll") for (int k = 0; k < 2; ++k) \
;         acc[ai][bj][m][n] = __builtin_amdgcn_mfma_f32_16x16x32_bf16(Bt[n][k], At[m][k], acc[ai][bj][m][n], 0, 0, 0); __builtin_amdgcn_s_setprio(0); } while (0)
; #define PG8_WAIT_V(n) asm volatile("s_waitcnt vmcnt(" #n ")" ::: "memory")
; #define PG8_WAIT_L(n) asm volatile("s_waitcnt lgkmcnt(" #n ")" ::: "memory")
; #define PG8_BAR __builtin_amdgcn_s_barrier()
; #define PG8_SCHED __builtin_amdgcn_sched_barrier(0)
; template <class Epi, class Sched = StaticOrder, class EpiSub = NoSub, bool FAST = false>
; __device__ __forceinline__ void gemm_phase(LAS unsigned char* lds, const Gemm g, const Sched& S, const Epi& E, const EpiSub& ES = EpiSub()) {
;     ...
;             PG8_WAIT_V(8); PG8_WAIT_L(0); PG8_BAR; PG8_MMA(0, 0, At, B0); PG8_MMA(0, 1, At, B1); PG8_BAR; PG8_SCHED;
;             PG8_LDA(At, 0, 1); PG8_STAGE(PG8_SB(0, 0), b2, voffB); PG8_STAGE(PG8_SB(0, 1), b2 + hstepB, voffB); PG8_STAGE(PG8_SA(0, 0), a2, voffA);
;             PG8_WAIT_V(8); PG8_WAIT_L(0); PG8_BAR; PG8_MMA(1, 0, At, B0); PG8_MMA(1, 1, At, B1); PG8_BAR; PG8_SCHED;
	v_mfma_f32_16x16x32_bf16 v[140:143], v[96:99], v[160:163], v[140:143]
	v_mfma_f32_16x16x32_bf16 v[136:139], v[112:115], v[160:163], v[136:139]
	v_mfma_f32_16x16x32_bf16 v[124:127], v[96:99], v[168:171], v[124:127]
	v_mfma_f32_16x16x32_bf16 v[120:123], v[112:115], v[168:171], v[120:123]
	v_mfma_f32_16x16x32_bf16 v[92:95], v[96:99], v[176:179], v[92:95]
	v_mfma_f32_16x16x32_bf16 v[88:91], v[112:115], v[176:179], v[88:91]
	v_mfma_f32_16x16x32_bf16 v[76:79], v[96:99], v[200:203], v[76:79]
	v_mfma_f32_16x16x32_bf16 v[72:75], v[112:115], v[200:203], v[72:75]
	v_mfma_f32_16x16x32_bf16 v[140:143], v[100:103], v[164:167], v[140:143]
	v_mfma_f32_16x16x32_bf16 v[136:139], v[116:119], v[164:167], v[136:139]
	v_mfma_f32_16x16x32_bf16 v[124:127], v[100:103], v[172:175], v[124:127]
	v_mfma_f32_16x16x32_bf16 v[120:123], v[116:119], v[172:175], v[120:123]
	v_mfma_f32_16x16x32_bf16 v[92:95], v[100:103], v[180:183], v[92:95]
	v_mfma_f32_16x16x32_bf16 v[88:91], v[116:119], v[180:183], v[88:91]
	v_mfma_f32_16x16x32_bf16 v[76:79], v[100:103], v[204:207], v[76:79]
	v_mfma_f32_16x16x32_bf16 v[72:75], v[116:119], v[204:207], v[72:75]
	v_mfma_f32_16x16x32_bf16 v[132:135], v[144:147], v[160:163], v[132:135]
	v_mfma_f32_16x16x32_bf16 v[128:131], v[152:155], v[160:163], v[128:131]
	v_mfma_f32_16x16x32_bf16 v[108:111], v[144:147], v[168:171], v[108:111]
	v_mfma_f32_16x16x32_bf16 v[104:107], v[152:155], v[168:171], v[104:107]
	v_mfma_f32_16x16x32_bf16 v[84:87], v[144:147], v[176:179], v[84:87]
	v_mfma_f32_16x16x32_bf16 v[80:83], v[152:155], v[176:179], v[80:83]
	v_mfma_f32_16x16x32_bf16 v[68:71], v[144:147], v[200:203], v[68:71]
	v_mfma_f32_16x16x32_bf16 v[64:67], v[152:155], v[200:203], v[64:67]
	v_mfma_f32_16x16x32_bf16 v[132:135], v[148:151], v[164:167], v[132:135]
	v_mfma_f32_16x16x32_bf16 v[128:131], v[156:159], v[164:167], v[128:131]
	v_mfma_f32_16x16x32_bf16 v[108:111], v[148:151], v[172:175], v[108:111]
	v_mfma_f32_16x16x32_bf16 v[104:107], v[156:159], v[172:175], v[104:107]
	v_mfma_f32_16x16x32_bf16 v[84:87], v[148:151], v[180:183], v[84:87]
	v_mfma_f32_16x16x32_bf16 v[80:83], v[156:159], v[180:183], v[80:83]
	v_mfma_f32_16x16x32_bf16 v[68:71], v[148:151], v[204:207], v[68:71]
	v_mfma_f32_16x16x32_bf16 v[64:67], v[156:159], v[204:207], v[64:67]
	s_barrier
	s_add_i32 s73, s58, s17
	v_lshl_add_u64 v[208:209], s[40:41], 0, v[186:187]
	s_mov_b32 m0, s73
	ds_read_b128 v[160:163], v217 offset:16384
	ds_read_b128 v[164:167], v217 offset:17408
	ds_read_b128 v[168:171], v217 offset:18432
	ds_read_b128 v[172:175], v217 offset:19456
	ds_read_b128 v[176:179], v217 offset:20480
	ds_read_b128 v[180:183], v217 offset:21504
	ds_read_b128 v[200:203], v217 offset:22528
	ds_read_b128 v[204:207], v217 offset:23552
	global_load_lds_dwordx4 v[208:209], off
	s_add_i32 m0, s73, 0x2000
	s_add_u32 s76, s40, 0x80000
	v_lshl_add_u64 v[210:211], s[40:41], 0, v[190:191]
	s_addc_u32 s77, s41, 0
	s_add_i32 s73, s59, s17
	global_load_lds_dwordx4 v[210:211], off
	v_lshl_add_u64 v[218:219], s[76:77], 0, v[186:187]
	s_mov_b32 m0, s73
	v_lshl_add_u64 v[220:221], s[42:43], 0, v[188:189]
	global_load_lds_dwordx4 v[218:219], off
	v_lshl_add_u64 v[218:219], s[76:77], 0, v[190:191]
	s_add_i32 m0, s73, 0x2000
	s_nop 0
	global_load_lds_dwordx4 v[218:219], off
	v_lshl_add_u64 v[218:219], s[42:43], 0, v[184:185]
	s_mov_b32 m0, s48
	s_nop 0
	global_load_lds_dwordx4 v[218:219], off
	s_mov_b32 m0, s49
	s_nop 0
	global_load_lds_dwordx4 v[220:221], off
	s_waitcnt vmcnt(8)
	s_waitcnt lgkmcnt(0)
	s_barrier
	v_mfma_f32_16x16x32_bf16 v[60:63], v[96:99], v[160:163], v[60:63]
	v_mfma_f32_16x16x32_bf16 v[56:59], v[112:115], v[160:163], v[56:59]
	v_mfma_f32_16x16x32_bf16 v[44:47], v[96:99], v[168:171], v[44:47]
	v_mfma_f32_16x16x32_bf16 v[40:43], v[112:115], v[168:171], v[40:43]
	v_mfma_f32_16x16x32_bf16 v[28:31], v[96:99], v[176:179], v[28:31]
	v_mfma_f32_16x16x32_bf16 v[24:27], v[112:115], v[176:179], v[24:27]
	v_mfma_f32_16x16x32_bf16 v[12:15], v[96:99], v[200:203], v[12:15]
	v_mfma_f32_16x16x32_bf16 v[8:11], v[112:115], v[200:203], v[8:11]
	v_mfma_f32_16x16x32_bf16 v[60:63], v[100:103], v[164:167], v[60:63]
	v_mfma_f32_16x16x32_bf16 v[56:59], v[116:119], v[164:167], v[56:59]
	v_mfma_f32_16x16x32_bf16 v[44:47], v[100:103], v[172:175], v[44:47]
	v_mfma_f32_16x16x32_bf16 v[40:43], v[116:119], v[172:175], v[40:43]
	v_mfma_f32_16x16x32_bf16 v[28:31], v[100:103], v[180:183], v[28:31]
	v_mfma_f32_16x16x32_bf16 v[24:27], v[116:119], v[180:183], v[24:27]
	v_mfma_f32_16x16x32_bf16 v[12:15], v[100:103], v[204:207], v[12:15]
	v_mfma_f32_16x16x32_bf16 v[8:11], v[116:119], v[204:207], v[8:11]
	v_mfma_f32_16x16x32_bf16 v[52:55], v[144:147], v[160:163], v[52:55]
	v_mfma_f32_16x16x32_bf16 v[48:51], v[152:155], v[160:163], v[48:51]
	v_mfma_f32_16x16x32_bf16 v[36:39], v[144:147], v[168:171], v[36:39]
	v_mfma_f32_16x16x32_bf16 v[32:35], v[152:155], v[168:171], v[32:35]
	v_mfma_f32_16x16x32_bf16 v[20:23], v[144:147], v[176:179], v[20:23]
	v_mfma_f32_16x16x32_bf16 v[16:19], v[152:155], v[176:179], v[16:19]
	v_mfma_f32_16x16x32_bf16 v[4:7], v[144:147], v[200:203], v[4:7]
	v_mfma_f32_16x16x32_bf16 v[0:3], v[152:155], v[200:203], v[0:3]
	v_mfma_f32_16x16x32_bf16 v[52:55], v[148:151], v[164:167], v[52:55]
	v_mfma_f32_16x16x32_bf16 v[48:51], v[156:159], v[164:167], v[48:51]
	v_mfma_f32_16x16x32_bf16 v[36:39], v[148:151], v[172:175], v[36:39]
	v_mfma_f32_16x16x32_bf16 v[32:35], v[156:159], v[172:175], v[32:35]
	v_mfma_f32_16x16x32_bf16 v[20:23], v[148:151], v[180:183], v[20:23]
	v_mfma_f32_16x16x32_bf16 v[16:19], v[156:159], v[180:183], v[16:19]
	v_mfma_f32_16x16x32_bf16 v[4:7], v[148:151], v[204:207], v[4:7]
	v_mfma_f32_16x16x32_bf16 v[0:3], v[156:159], v[204:207], v[0:3]
	s_barrier
; #define PG8_STAGE(bufoff, gbase, voff) do { _Pragma("unroll") for (int _i = 0; _i < 2; ++_i) \
;         __builtin_amdgcn_global_load_lds((const unsigned*)((const char*)(gbase) + (voff)[_i]), (LAS unsigned*)(lds + (bufoff) + ldsw + _i * 8192), 16, 0, 0); } while (0)
; #define PG8_LDA(dst, b, h) do { _Pragma("unroll") for (int m = 0; m < 4; ++m) _Pragma("unroll") for (int k = 0; k < 2; ++k) dst[m][k] = *(const LAS bf16x8*)(lds + PG8_SA(b, h) + aoff + m * 2048 + k * 1024); } while (0)
; #define PG8_LDB(dst, b, h) do { _Pragma("unroll") for (int n = 0; n < 2; ++n) _Pragma("unroll") for (int k = 0; k < 2; ++k) dst[n][k] = *(const LAS bf16x8*)(lds + PG8_SB(b, h) + boff + n * 2048 + k * 1024); } while (0)
; #define PG8_MMA(ai, bj, At, Bt) do { __builtin_amdgcn_s_setprio(1); _Pragma("unroll") for (int m = 0; m < 4; ++m) _Pragma("unroll") for (int n = 0; n < 2; ++n) _Pragma("unroll") for (int k = 0; k < 2; ++k) \
;         acc[ai][bj][m][n] = __builtin_amdgcn_mfma_f32_16x16x32_bf16(Bt[n][k], At[m][k], acc[ai][bj][m][n], 0, 0, 0); __builtin_amdgcn_s_setprio(0); } while (0)
; #define PG8_WAIT_V(n) asm volatile("s_waitcnt vmcnt(" #n ")" ::: "memory")
; #define PG8_WAIT_L(n) asm volatile("s_waitcnt lgkmcnt(" #n ")" ::: "memory")
; #define PG8_BAR __builtin_amdgcn_s_barrier()
; #define PG8_SCHED __builtin_amdgcn_sched_barrier(0)
; template <class Epi, class Sched = StaticOrder, class EpiSub = NoSub, bool FAST = false>
; __device__ __forceinline__ void gemm_phase(LAS unsigned char* lds, const Gemm g, const Sched& S, const Epi& E, const EpiSub& ES = EpiSub()) {
;     ...
;             PG8_LDB(B0, 1, 0); PG8_LDB(B1, 1, 1); PG8_SCHED; PG8_LDA(At, 1, 0); PG8_STAGE(PG8_SA(0, 1), a2 + hstepA, voffA);
;             PG8_WAIT_V(8); PG8_WAIT_L(0); PG8_BAR; PG8_MMA(0, 0, At, B0); PG8_MMA(0, 1, At, B1); PG8_BAR; PG8_SCHED;
;             PG8_LDA(At, 1, 1); PG8_STAGE(PG8_SB(1, 0), b3, voffB); PG8_STAGE(PG8_SB(1, 1), b3 + hstepB, voffB); PG8_STAGE(PG8_SA(1, 0), a3, voffA);
;             PG8_WAIT_V(8); PG8_WAIT_L(0); PG8_BAR; PG8_MMA(1, 0, At, B0); PG8_MMA(1, 1, At, B1); PG8_BAR; PG8_SCHED;
	s_add_i32 s73, 0, 0x18000
	s_add_i32 s76, 0, 0x1c000
	v_add_u32_e32 v116, s73, v212
	v_add_u32_e32 v156, s76, v212
	ds_read_b128 v[96:99], v116
	ds_read_b128 v[100:103], v116 offset:1024
	ds_read_b128 v[112:115], v116 offset:2048
	ds_read_b128 v[116:119], v116 offset:3072
	ds_read_b128 v[144:147], v156
	ds_read_b128 v[148:151], v156 offset:1024
	ds_read_b128 v[152:155], v156 offset:2048
	ds_read_b128 v[156:159], v156 offset:3072
	s_add_u32 s42, s42, 0x80000
	s_addc_u32 s43, s43, 0
	s_mov_b32 m0, s50
	v_lshl_add_u64 v[222:223], s[42:43], 0, v[184:185]
	ds_read_b128 v[160:163], v217 offset:32768
	ds_read_b128 v[164:167], v217 offset:33792
	ds_read_b128 v[168:171], v217 offset:34816
	ds_read_b128 v[172:175], v217 offset:35840
	ds_read_b128 v[176:179], v217 offset:36864
	ds_read_b128 v[180:183], v217 offset:37888
	ds_read_b128 v[200:203], v217 offset:38912
	ds_read_b128 v[204:207], v217 offset:39936
	global_load_lds_dwordx4 v[222:223], off
	v_lshl_add_u64 v[222:223], s[42:43], 0, v[188:189]
	s_mov_b32 m0, s51
	s_nop 0
	global_load_lds_dwordx4 v[222:223], off
	s_waitcnt vmcnt(8)
	s_waitcnt lgkmcnt(0)
	s_barrier
	v_mfma_f32_16x16x32_bf16 v[140:143], v[96:99], v[160:163], v[140:143]
	v_mfma_f32_16x16x32_bf16 v[136:139], v[112:115], v[160:163], v[136:139]
	v_mfma_f32_16x16x32_bf16 v[124:127], v[96:99], v[168:171], v[124:127]
	v_mfma_f32_16x16x32_bf16 v[120:123], v[112:115], v[168:171], v[120:123]
	v_mfma_f32_16x16x32_bf16 v[92:95], v[96:99], v[176:179], v[92:95]
	v_mfma_f32_16x16x32_bf16 v[88:91], v[112:115], v[176:179], v[88:91]
	v_mfma_f32_16x16x32_bf16 v[76:79], v[96:99], v[200:203], v[76:79]
	v_mfma_f32_16x16x32_bf16 v[72:75], v[112:115], v[200:203], v[72:75]
	v_mfma_f32_16x16x32_bf16 v[140:143], v[100:103], v[164:167], v[140:143]
	v_mfma_f32_16x16x32_bf16 v[136:139], v[116:119], v[164:167], v[136:139]
	v_mfma_f32_16x16x32_bf16 v[124:127], v[100:103], v[172:175], v[124:127]
	v_mfma_f32_16x16x32_bf16 v[120:123], v[116:119], v[172:175], v[120:123]
	v_mfma_f32_16x16x32_bf16 v[92:95], v[100:103], v[180:183], v[92:95]
	v_mfma_f32_16x16x32_bf16 v[88:91], v[116:119], v[180:183], v[88:91]
	v_mfma_f32_16x16x32_bf16 v[76:79], v[100:103], v[204:207], v[76:79]
	v_mfma_f32_16x16x32_bf16 v[72:75], v[116:119], v[204:207], v[72:75]
	v_mfma_f32_16x16x32_bf16 v[132:135], v[144:147], v[160:163], v[132:135]
	v_mfma_f32_16x16x32_bf16 v[128:131], v[152:155], v[160:163], v[128:131]
	v_mfma_f32_16x16x32_bf16 v[108:111], v[144:147], v[168:171], v[108:111]
	v_mfma_f32_16x16x32_bf16 v[104:107], v[152:155], v[168:171], v[104:107]
	v_mfma_f32_16x16x32_bf16 v[84:87], v[144:147], v[176:179], v[84:87]
	v_mfma_f32_16x16x32_bf16 v[80:83], v[152:155], v[176:179], v[80:83]
	v_mfma_f32_16x16x32_bf16 v[68:71], v[144:147], v[200:203], v[68:71]
	v_mfma_f32_16x16x32_bf16 v[64:67], v[152:155], v[200:203], v[64:67]
	v_mfma_f32_16x16x32_bf16 v[132:135], v[148:151], v[164:167], v[132:135]
	v_mfma_f32_16x16x32_bf16 v[128:131], v[156:159], v[164:167], v[128:131]
	v_mfma_f32_16x16x32_bf16 v[108:111], v[148:151], v[172:175], v[108:111]
	v_mfma_f32_16x16x32_bf16 v[104:107], v[156:159], v[172:175], v[104:107]
	v_mfma_f32_16x16x32_bf16 v[84:87], v[148:151], v[180:183], v[84:87]
	v_mfma_f32_16x16x32_bf16 v[80:83], v[156:159], v[180:183], v[80:83]
	v_mfma_f32_16x16x32_bf16 v[68:71], v[148:151], v[204:207], v[68:71]
	v_mfma_f32_16x16x32_bf16 v[64:67], v[156:159], v[204:207], v[64:67]
	s_barrier
	s_add_i32 s42, s73, s17
	v_lshl_add_u64 v[208:209], v[208:209], 0, s[12:13]
	s_mov_b32 m0, s42
	ds_read_b128 v[160:163], v217 offset:49152
	ds_read_b128 v[164:167], v217 offset:50176
	ds_read_b128 v[168:171], v217 offset:51200
	ds_read_b128 v[172:175], v217 offset:52224
	ds_read_b128 v[176:179], v217 offset:53248
	ds_read_b128 v[180:183], v217 offset:54272
	ds_read_b128 v[200:203], v217 offset:55296
	ds_read_b128 v[204:207], v217 offset:56320
	global_load_lds_dwordx4 v[208:209], off
	s_add_i32 m0, s42, 0x2000
	s_add_u32 s40, s40, 0x80080
	v_lshl_add_u64 v[208:209], v[210:211], 0, s[12:13]
	s_addc_u32 s41, s41, 0
	s_add_i32 s42, s76, s17
	global_load_lds_dwordx4 v[208:209], off
	v_lshl_add_u64 v[208:209], s[40:41], 0, v[186:187]
	s_mov_b32 m0, s42
	s_nop 0
	global_load_lds_dwordx4 v[208:209], off
	v_lshl_add_u64 v[208:209], s[40:41], 0, v[190:191]
	s_add_i32 m0, s42, 0x2000
	s_nop 0
	global_load_lds_dwordx4 v[208:209], off
	v_lshl_add_u64 v[208:209], v[218:219], 0, s[12:13]
	s_mov_b32 m0, s55
	s_nop 0
	global_load_lds_dwordx4 v[208:209], off
	v_lshl_add_u64 v[208:209], v[220:221], 0, s[12:13]
	s_mov_b32 m0, s56
	s_nop 0
	global_load_lds_dwordx4 v[208:209], off
	s_waitcnt vmcnt(8)
	s_waitcnt lgkmcnt(0)
	s_barrier
	v_mfma_f32_16x16x32_bf16 v[60:63], v[96:99], v[160:163], v[60:63]
	v_mfma_f32_16x16x32_bf16 v[56:59], v[112:115], v[160:163], v[56:59]
	v_mfma_f32_16x16x32_bf16 v[44:47], v[96:99], v[168:171], v[44:47]
	v_mfma_f32_16x16x32_bf16 v[40:43], v[112:115], v[168:171], v[40:43]
	v_mfma_f32_16x16x32_bf16 v[28:31], v[96:99], v[176:179], v[28:31]
	v_mfma_f32_16x16x32_bf16 v[24:27], v[112:115], v[176:179], v[24:27]
	v_mfma_f32_16x16x32_bf16 v[12:15], v[96:99], v[200:203], v[12:15]
	v_mfma_f32_16x16x32_bf16 v[8:11], v[112:115], v[200:203], v[8:11]
	v_mfma_f32_16x16x32_bf16 v[60:63], v[100:103], v[164:167], v[60:63]
	v_mfma_f32_16x16x32_bf16 v[56:59], v[116:119], v[164:167], v[56:59]
	v_mfma_f32_16x16x32_bf16 v[44:47], v[100:103], v[172:175], v[44:47]
	v_mfma_f32_16x16x32_bf16 v[40:43], v[116:119], v[172:175], v[40:43]
	v_mfma_f32_16x16x32_bf16 v[28:31], v[100:103], v[180:183], v[28:31]
	v_mfma_f32_16x16x32_bf16 v[24:27], v[116:119], v[180:183], v[24:27]
	v_mfma_f32_16x16x32_bf16 v[12:15], v[100:103], v[204:207], v[12:15]
	v_mfma_f32_16x16x32_bf16 v[8:11], v[116:119], v[204:207], v[8:11]
	v_mfma_f32_16x16x32_bf16 v[52:55], v[144:147], v[160:163], v[52:55]
	v_mfma_f32_16x16x32_bf16 v[48:51], v[152:155], v[160:163], v[48:51]
	v_mfma_f32_16x16x32_bf16 v[36:39], v[144:147], v[168:171], v[36:39]
	v_mfma_f32_16x16x32_bf16 v[32:35], v[152:155], v[168:171], v[32:35]
	v_mfma_f32_16x16x32_bf16 v[20:23], v[144:147], v[176:179], v[20:23]
	v_mfma_f32_16x16x32_bf16 v[16:19], v[152:155], v[176:179], v[16:19]
	v_mfma_f32_16x16x32_bf16 v[4:7], v[144:147], v[200:203], v[4:7]
	v_mfma_f32_16x16x32_bf16 v[0:3], v[152:155], v[200:203], v[0:3]
	v_mfma_f32_16x16x32_bf16 v[52:55], v[148:151], v[164:167], v[52:55]
	v_mfma_f32_16x16x32_bf16 v[48:51], v[156:159], v[164:167], v[48:51]
	v_mfma_f32_16x16x32_bf16 v[36:39], v[148:151], v[172:175], v[36:39]
	v_mfma_f32_16x16x32_bf16 v[32:35], v[156:159], v[172:175], v[32:35]
	v_mfma_f32_16x16x32_bf16 v[20:23], v[148:151], v[180:183], v[20:23]
	v_mfma_f32_16x16x32_bf16 v[16:19], v[156:159], v[180:183], v[16:19]
	v_mfma_f32_16x16x32_bf16 v[4:7], v[148:151], v[204:207], v[4:7]
	v_mfma_f32_16x16x32_bf16 v[0:3], v[156:159], v[204:207], v[0:3]
	s_barrier
	s_add_u32 s38, s38, 0x100
	s_addc_u32 s39, s39, 0
	s_add_u32 s70, s70, 0x100
	s_addc_u32 s71, s71, 0
	s_cmp_ge_u32 s72, s29
	s_mov_b32 s42, s72
	s_cbranch_scc0 .LBB0_769

; #define PG8_STAGE(bufoff, gbase, voff) do { _Pragma("unroll") for (int _i = 0; _i < 2; ++_i) \
;         __builtin_amdgcn_global_load_lds((const unsigned*)((const char*)(gbase) + (voff)[_i]), (LAS unsigned*)(lds + (bufoff) + ldsw + _i * 8192), 16, 0, 0); } while (0)
; #define PG8_LDA(dst, b, h) do { _Pragma("unroll") for (int m = 0; m < 4; ++m) _Pragma("unroll") for (int k = 0; k < 2; ++k) dst[m][k] = *(const LAS bf16x8*)(lds + PG8_SA(b, h) + aoff + m * 2048 + k * 1024); } while (0)
; #define PG8_LDB(dst, b, h) do { _Pragma("unroll") for (int n = 0; n < 2; ++n) _Pragma("unroll") for (int k = 0; k < 2; ++k) dst[n][k] = *(const LAS bf16x8*)(lds + PG8_SB(b, h) + boff + n * 2048 + k * 1024); } while (0)
; #define PG8_WAIT_V(n) asm volatile("s_waitcnt vmcnt(" #n ")" ::: "memory")
; #define PG8_BAR __builtin_amdgcn_s_barrier()
; template <class Epi, class Sched = StaticOrder, class EpiSub = NoSub, bool FAST = false>
; __device__ __forceinline__ void gemm_phase(LAS unsigned char* lds, const Gemm g, const Sched& S, const Epi& E, const EpiSub& ES = EpiSub()) {
;     ...
;         const bool has_next = S.next(ui + 1, nxt);
;         const size_t nko = (has_next && nxt.kb >= 0) ? nxt.kb * ksubB : 0;
;         const char* nA = has_next ? (const char*)g.A + (size_t)nxt.pm * tstepA + (size_t)nxt.pn * g.acs + nko : cA; const char* nB = has_next ? (const char*)g.Bt + (size_t)nxt.pn * tstepB + nko : cB;
;         const int nt = cur.kb < 0 ? ntMain : ntSub;
;         for (int t = 0; t < nt; t += 2) {
;             const bool last = (t == nt - 2);
;             const char* a1 = cA + (size_t)(t + 1) * kstep;
;             const char* a2 = last ? nA : cA + (size_t)(t + 2) * kstep; const char* b2 = last ? nB : cB + (size_t)(t + 2) * kstep;
;             const char* a3 = a2 + kstep; const char* b3 = b2 + kstep;
;             if constexpr (FAST && PG8_SP2) {
;             PG8_LDB(B0, 0, 0); PG8_LDB(B1, 0, 1); PG8_SCHED; PG8_LDA(At, 0, 0); PG8_STAGE(PG8_SA(1, 1), a1 + hstepA, voffA);
;             PG8_WAIT_V(8); PG8_WAIT_L(0); PG8_BAR; PG8_MMA(0, 0, At, B0); PG8_MMA(0, 1, At, B1); PG8_BAR; PG8_SCHED;
;             PG8_LDA(At, 0, 1); PG8_STAGE(PG8_SB(0, 0), b2, voffB); PG8_STAGE(PG8_SB(0, 1), b2 + hstepB, voffB); PG8_STAGE(PG8_SA(0, 0), a2, voffA);
;             PG8_WAIT_V(8); PG8_WAIT_L(0); PG8_BAR; PG8_MMA(1, 0, At, B0); PG8_MMA(1, 1, At, B1); PG8_BAR; PG8_SCHED;
.LBB0_984:
	s_ashr_i32 s15, s14, 31
	s_lshl_b64 s[16:17], s[14:15], 20
	v_readlane_b32 s18, v254, 36
	v_readlane_b32 s19, v254, 37
	s_add_u32 s16, s18, s16
	s_addc_u32 s17, s19, s17
	s_and_b64 s[18:19], s[0:1], exec
	s_cselect_b32 s15, s17, s23
	s_cselect_b32 s45, s16, s22
	s_ashr_i32 s13, s12, 31
	s_lshl_b64 s[18:19], s[12:13], 20
	s_add_u32 s18, s2, s18
	s_addc_u32 s19, s3, s19
	s_and_b64 s[26:27], s[0:1], exec
	s_cselect_b32 s13, s19, s25
	s_cselect_b32 s46, s18, s24
	s_add_u32 s22, s22, 0x80080
	s_addc_u32 s23, s23, 0
	s_add_u32 s47, s24, 0x100
	s_addc_u32 s48, s25, 0
	s_mov_b32 s49, -2
	ds_read_b128 v[150:153], v147
	ds_read_b128 v[154:157], v147 offset:1024
	ds_read_b128 v[158:161], v147 offset:2048
	ds_read_b128 v[162:165], v147 offset:3072
	ds_read_b128 v[166:169], v148
	ds_read_b128 v[170:173], v148 offset:1024
	ds_read_b128 v[174:177], v148 offset:2048
	ds_read_b128 v[178:181], v148 offset:3072
	s_add_u32 s24, s22, 0xfff80080
	s_addc_u32 s25, s23, -1
	s_cmp_eq_u32 s49, 28
	s_cselect_b32 s27, s15, s25
	s_cselect_b32 s26, s45, s24
	s_cselect_b32 s25, s13, s48
	s_cselect_b32 s24, s46, s47
	v_lshl_add_u64 v[190:191], s[22:23], 0, v[136:137]
	s_add_i32 m0, s21, 0xc000
	ds_read_b128 v[182:185], v149
	ds_read_b128 v[186:189], v149 offset:1024
	ds_read_b128 v[194:197], v149 offset:2048
	ds_read_b128 v[198:201], v149 offset:3072
	ds_read_b128 v[202:205], v149 offset:4096
	ds_read_b128 v[206:209], v149 offset:5120
	ds_read_b128 v[210:213], v149 offset:6144
	ds_read_b128 v[214:217], v149 offset:7168
	global_load_lds_dwordx4 v[190:191], off
	v_lshl_add_u64 v[190:191], s[22:23], 0, v[138:139]
	s_add_i32 m0, s21, 0xe000
	s_nop 0
	global_load_lds_dwordx4 v[190:191], off
	s_waitcnt vmcnt(8)
	s_waitcnt lgkmcnt(0)
	s_barrier
	v_mfma_f32_16x16x32_bf16 v[124:127], v[150:153], v[182:185], 0
	v_mfma_f32_16x16x32_bf16 v[116:119], v[158:161], v[182:185], 0
	v_mfma_f32_16x16x32_bf16 v[108:111], v[150:153], v[194:197], 0
	v_mfma_f32_16x16x32_bf16 v[100:103], v[158:161], v[194:197], 0
	v_mfma_f32_16x16x32_bf16 v[92:95], v[150:153], v[202:205], 0
	v_mfma_f32_16x16x32_bf16 v[84:87], v[158:161], v[202:205], 0
	v_mfma_f32_16x16x32_bf16 v[76:79], v[150:153], v[210:213], 0
	v_mfma_f32_16x16x32_bf16 v[68:71], v[158:161], v[210:213], 0
	v_mfma_f32_16x16x32_bf16 v[124:127], v[154:157], v[186:189], v[124:127]
	v_mfma_f32_16x16x32_bf16 v[116:119], v[162:165], v[186:189], v[116:119]
	v_mfma_f32_16x16x32_bf16 v[108:111], v[154:157], v[198:201], v[108:111]
	v_mfma_f32_16x16x32_bf16 v[100:103], v[162:165], v[198:201], v[100:103]
	v_mfma_f32_16x16x32_bf16 v[92:95], v[154:157], v[206:209], v[92:95]
	v_mfma_f32_16x16x32_bf16 v[84:87], v[162:165], v[206:209], v[84:87]
	v_mfma_f32_16x16x32_bf16 v[76:79], v[154:157], v[214:217], v[76:79]
	v_mfma_f32_16x16x32_bf16 v[68:71], v[162:165], v[214:217], v[68:71]
	v_mfma_f32_16x16x32_bf16 v[120:123], v[166:169], v[182:185], 0
	v_mfma_f32_16x16x32_bf16 v[112:115], v[174:177], v[182:185], 0
	v_mfma_f32_16x16x32_bf16 v[104:107], v[166:169], v[194:197], 0
	v_mfma_f32_16x16x32_bf16 v[96:99], v[174:177], v[194:197], 0
	v_mfma_f32_16x16x32_bf16 v[88:91], v[166:169], v[202:205], 0
	v_mfma_f32_16x16x32_bf16 v[80:83], v[174:177], v[202:205], 0
	v_mfma_f32_16x16x32_bf16 v[72:75], v[166:169], v[210:213], 0
	v_mfma_f32_16x16x32_bf16 v[64:67], v[174:177], v[210:213], 0
	v_mfma_f32_16x16x32_bf16 v[120:123], v[170:173], v[186:189], v[120:123]
	v_mfma_f32_16x16x32_bf16 v[112:115], v[178:181], v[186:189], v[112:115]
	v_mfma_f32_16x16x32_bf16 v[104:107], v[170:173], v[198:201], v[104:107]
	v_mfma_f32_16x16x32_bf16 v[96:99], v[178:181], v[198:201], v[96:99]
	v_mfma_f32_16x16x32_bf16 v[88:91], v[170:173], v[206:209], v[88:91]
	v_mfma_f32_16x16x32_bf16 v[80:83], v[178:181], v[206:209], v[80:83]
	v_mfma_f32_16x16x32_bf16 v[72:75], v[170:173], v[214:217], v[72:75]
	v_mfma_f32_16x16x32_bf16 v[64:67], v[178:181], v[214:217], v[64:67]
	s_barrier
	s_add_i32 s50, s42, s28
	v_lshl_add_u64 v[190:191], s[24:25], 0, v[130:131]
	s_mov_b32 m0, s50
	ds_read_b128 v[182:185], v149 offset:16384
	ds_read_b128 v[186:189], v149 offset:17408
	ds_read_b128 v[194:197], v149 offset:18432
	ds_read_b128 v[198:201], v149 offset:19456
	ds_read_b128 v[202:205], v149 offset:20480
	ds_read_b128 v[206:209], v149 offset:21504
	ds_read_b128 v[210:213], v149 offset:22528
	ds_read_b128 v[214:217], v149 offset:23552
	global_load_lds_dwordx4 v[190:191], off
	s_add_i32 m0, s50, 0x2000
	s_add_u32 s50, s24, 0x80000
	v_lshl_add_u64 v[218:219], s[24:25], 0, v[134:135]
	s_addc_u32 s51, s25, 0
	s_add_i32 s52, s43, s28
	global_load_lds_dwordx4 v[218:219], off
	v_lshl_add_u64 v[220:221], s[50:51], 0, v[130:131]
	s_mov_b32 m0, s52
	v_lshl_add_u64 v[222:223], s[26:27], 0, v[132:133]
	global_load_lds_dwordx4 v[220:221], off
	v_lshl_add_u64 v[220:221], s[50:51], 0, v[134:135]
	s_add_i32 m0, s52, 0x2000
	s_nop 0
	global_load_lds_dwordx4 v[220:221], off
	v_lshl_add_u64 v[220:221], s[26:27], 0, v[128:129]
	s_mov_b32 m0, s21
	s_nop 0
	global_load_lds_dwordx4 v[220:221], off
	s_mov_b32 m0, s31
	s_nop 0
	global_load_lds_dwordx4 v[222:223], off
	s_waitcnt vmcnt(8)
	s_waitcnt lgkmcnt(0)
	s_barrier
; #define PG8_STAGE(bufoff, gbase, voff) do { _Pragma("unroll") for (int _i = 0; _i < 2; ++_i) \
;         __builtin_amdgcn_global_load_lds((const unsigned*)((const char*)(gbase) + (voff)[_i]), (LAS unsigned*)(lds + (bufoff) + ldsw + _i * 8192), 16, 0, 0); } while (0)
; #define PG8_LDA(dst, b, h) do { _Pragma("unroll") for (int m = 0; m < 4; ++m) _Pragma("unroll") for (int k = 0; k < 2; ++k) dst[m][k] = *(const LAS bf16x8*)(lds + PG8_SA(b, h) + aoff + m * 2048 + k * 1024); } while (0)
; #define PG8_LDB(dst, b, h) do { _Pragma("unroll") for (int n = 0; n < 2; ++n) _Pragma("unroll") for (int k = 0; k < 2; ++k) dst[n][k] = *(const LAS bf16x8*)(lds + PG8_SB(b, h) + boff + n * 2048 + k * 1024); } while (0)
; #define PG8_MMA(ai, bj, At, Bt) do { __builtin_amdgcn_s_setprio(1); _Pragma("unroll") for (int m = 0; m < 4; ++m) _Pragma("unroll") for (int n = 0; n < 2; ++n) _Pragma("unroll") for (int k = 0; k < 2; ++k) \
;         acc[ai][bj][m][n] = __builtin_amdgcn_mfma_f32_16x16x32_bf16(Bt[n][k], At[m][k], acc[ai][bj][m][n], 0, 0, 0); __builtin_amdgcn_s_setprio(0); } while (0)
; #define PG8_WAIT_V(n) asm volatile("s_waitcnt vmcnt(" #n ")" ::: "memory")
; #define PG8_WAIT_L(n) asm volatile("s_waitcnt lgkmcnt(" #n ")" ::: "memory")
; #define PG8_BAR __builtin_amdgcn_s_barrier()
; #define PG8_SCHED __builtin_amdgcn_sched_barrier(0)
; template <class Epi, class Sched = StaticOrder, class EpiSub = NoSub, bool FAST = false>
; __device__ __forceinline__ void gemm_phase(LAS unsigned char* lds, const Gemm g, const Sched& S, const Epi& E, const EpiSub& ES = EpiSub()) {
;     ...
;             PG8_WAIT_V(8); PG8_WAIT_L(0); PG8_BAR; PG8_MMA(1, 0, At, B0); PG8_MMA(1, 1, At, B1); PG8_BAR; PG8_SCHED;
;             PG8_LDB(B0, 1, 0); PG8_LDB(B1, 1, 1); PG8_SCHED; PG8_LDA(At, 1, 0); PG8_STAGE(PG8_SA(0, 1), a2 + hstepA, voffA);
;             PG8_WAIT_V(8); PG8_WAIT_L(0); PG8_BAR; PG8_MMA(0, 0, At, B0); PG8_MMA(0, 1, At, B1); PG8_BAR; PG8_SCHED;
	v_mfma_f32_16x16x32_bf16 v[60:63], v[150:153], v[182:185], 0
	v_mfma_f32_16x16x32_bf16 v[52:55], v[158:161], v[182:185], 0
	v_mfma_f32_16x16x32_bf16 v[44:47], v[150:153], v[194:197], 0
	v_mfma_f32_16x16x32_bf16 v[36:39], v[158:161], v[194:197], 0
	v_mfma_f32_16x16x32_bf16 v[28:31], v[150:153], v[202:205], 0
	v_mfma_f32_16x16x32_bf16 v[20:23], v[158:161], v[202:205], 0
	v_mfma_f32_16x16x32_bf16 v[12:15], v[150:153], v[210:213], 0
	v_mfma_f32_16x16x32_bf16 v[4:7], v[158:161], v[210:213], 0
	v_mfma_f32_16x16x32_bf16 v[60:63], v[154:157], v[186:189], v[60:63]
	v_mfma_f32_16x16x32_bf16 v[52:55], v[162:165], v[186:189], v[52:55]
	v_mfma_f32_16x16x32_bf16 v[44:47], v[154:157], v[198:201], v[44:47]
	v_mfma_f32_16x16x32_bf16 v[36:39], v[162:165], v[198:201], v[36:39]
	v_mfma_f32_16x16x32_bf16 v[28:31], v[154:157], v[206:209], v[28:31]
	v_mfma_f32_16x16x32_bf16 v[20:23], v[162:165], v[206:209], v[20:23]
	v_mfma_f32_16x16x32_bf16 v[12:15], v[154:157], v[214:217], v[12:15]
	v_mfma_f32_16x16x32_bf16 v[4:7], v[162:165], v[214:217], v[4:7]
	v_mfma_f32_16x16x32_bf16 v[56:59], v[166:169], v[182:185], 0
	v_mfma_f32_16x16x32_bf16 v[48:51], v[174:177], v[182:185], 0
	v_mfma_f32_16x16x32_bf16 v[40:43], v[166:169], v[194:197], 0
	v_mfma_f32_16x16x32_bf16 v[32:35], v[174:177], v[194:197], 0
	v_mfma_f32_16x16x32_bf16 v[24:27], v[166:169], v[202:205], 0
	v_mfma_f32_16x16x32_bf16 v[16:19], v[174:177], v[202:205], 0
	v_mfma_f32_16x16x32_bf16 v[8:11], v[166:169], v[210:213], 0
	v_mfma_f32_16x16x32_bf16 v[0:3], v[174:177], v[210:213], 0
	v_mfma_f32_16x16x32_bf16 v[56:59], v[170:173], v[186:189], v[56:59]
	v_mfma_f32_16x16x32_bf16 v[48:51], v[178:181], v[186:189], v[48:51]
	v_mfma_f32_16x16x32_bf16 v[40:43], v[170:173], v[198:201], v[40:43]
	v_mfma_f32_16x16x32_bf16 v[32:35], v[178:181], v[198:201], v[32:35]
	v_mfma_f32_16x16x32_bf16 v[24:27], v[170:173], v[206:209], v[24:27]
	v_mfma_f32_16x16x32_bf16 v[16:19], v[178:181], v[206:209], v[16:19]
	v_mfma_f32_16x16x32_bf16 v[8:11], v[170:173], v[214:217], v[8:11]
	v_mfma_f32_16x16x32_bf16 v[0:3], v[178:181], v[214:217], v[0:3]
	s_barrier
	s_add_i32 s50, 0, 0x18000
	s_add_i32 s51, 0, 0x1c000
	v_add_u32_e32 v162, s50, v145
	v_add_u32_e32 v178, s51, v145
	ds_read_b128 v[150:153], v162
	ds_read_b128 v[154:157], v162 offset:1024
	ds_read_b128 v[158:161], v162 offset:2048
	ds_read_b128 v[162:165], v162 offset:3072
	ds_read_b128 v[166:169], v178
	ds_read_b128 v[170:173], v178 offset:1024
	ds_read_b128 v[174:177], v178 offset:2048
	ds_read_b128 v[178:181], v178 offset:3072
	s_add_u32 s26, s26, 0x80000
	s_addc_u32 s27, s27, 0
	s_mov_b32 m0, s36
	v_lshl_add_u64 v[224:225], s[26:27], 0, v[128:129]
	ds_read_b128 v[182:185], v149 offset:32768
	ds_read_b128 v[186:189], v149 offset:33792
	ds_read_b128 v[194:197], v149 offset:34816
	ds_read_b128 v[198:201], v149 offset:35840
	ds_read_b128 v[202:205], v149 offset:36864
	ds_read_b128 v[206:209], v149 offset:37888
	ds_read_b128 v[210:213], v149 offset:38912
	ds_read_b128 v[214:217], v149 offset:39936
	global_load_lds_dwordx4 v[224:225], off
	v_lshl_add_u64 v[224:225], s[26:27], 0, v[132:133]
	s_mov_b32 m0, s37
	s_nop 0
	global_load_lds_dwordx4 v[224:225], off
	s_waitcnt vmcnt(8)
	s_waitcnt lgkmcnt(0)
	s_barrier
	v_mfma_f32_16x16x32_bf16 v[124:127], v[150:153], v[182:185], v[124:127]
	v_mfma_f32_16x16x32_bf16 v[116:119], v[158:161], v[182:185], v[116:119]
	v_mfma_f32_16x16x32_bf16 v[108:111], v[150:153], v[194:197], v[108:111]
	v_mfma_f32_16x16x32_bf16 v[100:103], v[158:161], v[194:197], v[100:103]
	v_mfma_f32_16x16x32_bf16 v[92:95], v[150:153], v[202:205], v[92:95]
	v_mfma_f32_16x16x32_bf16 v[84:87], v[158:161], v[202:205], v[84:87]
	v_mfma_f32_16x16x32_bf16 v[76:79], v[150:153], v[210:213], v[76:79]
	v_mfma_f32_16x16x32_bf16 v[68:71], v[158:161], v[210:213], v[68:71]
	v_mfma_f32_16x16x32_bf16 v[124:127], v[154:157], v[186:189], v[124:127]
	v_mfma_f32_16x16x32_bf16 v[116:119], v[162:165], v[186:189], v[116:119]
	v_mfma_f32_16x16x32_bf16 v[108:111], v[154:157], v[198:201], v[108:111]
	v_mfma_f32_16x16x32_bf16 v[100:103], v[162:165], v[198:201], v[100:103]
	v_mfma_f32_16x16x32_bf16 v[92:95], v[154:157], v[206:209], v[92:95]
	v_mfma_f32_16x16x32_bf16 v[84:87], v[162:165], v[206:209], v[84:87]
	v_mfma_f32_16x16x32_bf16 v[76:79], v[154:157], v[214:217], v[76:79]
	v_mfma_f32_16x16x32_bf16 v[68:71], v[162:165], v[214:217], v[68:71]
	v_mfma_f32_16x16x32_bf16 v[120:123], v[166:169], v[182:185], v[120:123]
	v_mfma_f32_16x16x32_bf16 v[112:115], v[174:177], v[182:185], v[112:115]
	v_mfma_f32_16x16x32_bf16 v[104:107], v[166:169], v[194:197], v[104:107]
	v_mfma_f32_16x16x32_bf16 v[96:99], v[174:177], v[194:197], v[96:99]
	v_mfma_f32_16x16x32_bf16 v[88:91], v[166:169], v[202:205], v[88:91]
	v_mfma_f32_16x16x32_bf16 v[80:83], v[174:177], v[202:205], v[80:83]
	v_mfma_f32_16x16x32_bf16 v[72:75], v[166:169], v[210:213], v[72:75]
	v_mfma_f32_16x16x32_bf16 v[64:67], v[174:177], v[210:213], v[64:67]
	v_mfma_f32_16x16x32_bf16 v[120:123], v[170:173], v[186:189], v[120:123]
	v_mfma_f32_16x16x32_bf16 v[112:115], v[178:181], v[186:189], v[112:115]
	v_mfma_f32_16x16x32_bf16 v[104:107], v[170:173], v[198:201], v[104:107]
	v_mfma_f32_16x16x32_bf16 v[96:99], v[178:181], v[198:201], v[96:99]
	v_mfma_f32_16x16x32_bf16 v[88:91], v[170:173], v[206:209], v[88:91]
	v_mfma_f32_16x16x32_bf16 v[80:83], v[178:181], v[206:209], v[80:83]
	v_mfma_f32_16x16x32_bf16 v[72:75], v[170:173], v[214:217], v[72:75]
	v_mfma_f32_16x16x32_bf16 v[64:67], v[178:181], v[214:217], v[64:67]
	s_barrier
; #define PG8_STAGE(bufoff, gbase, voff) do { _Pragma("unroll") for (int _i = 0; _i < 2; ++_i) \
;         __builtin_amdgcn_global_load_lds((const unsigned*)((const char*)(gbase) + (voff)[_i]), (LAS unsigned*)(lds + (bufoff) + ldsw + _i * 8192), 16, 0, 0); } while (0)
; #define PG8_LDA(dst, b, h) do { _Pragma("unroll") for (int m = 0; m < 4; ++m) _Pragma("unroll") for (int k = 0; k < 2; ++k) dst[m][k] = *(const LAS bf16x8*)(lds + PG8_SA(b, h) + aoff + m * 2048 + k * 1024); } while (0)
; #define PG8_LDB(dst, b, h) do { _Pragma("unroll") for (int n = 0; n < 2; ++n) _Pragma("unroll") for (int k = 0; k < 2; ++k) dst[n][k] = *(const LAS bf16x8*)(lds + PG8_SB(b, h) + boff + n * 2048 + k * 1024); } while (0)
; #define PG8_MMA(ai, bj, At, Bt) do { __builtin_amdgcn_s_setprio(1); _Pragma("unroll") for (int m = 0; m < 4; ++m) _Pragma("unroll") for (int n = 0; n < 2; ++n) _Pragma("unroll") for (int k = 0; k < 2; ++k) \
;         acc[ai][bj][m][n] = __builtin_amdgcn_mfma_f32_16x16x32_bf16(Bt[n][k], At[m][k], acc[ai][bj][m][n], 0, 0, 0); __builtin_amdgcn_s_setprio(0); } while (0)
; #define PG8_BAR __builtin_amdgcn_s_barrier()
; template <class Epi, class Sched = StaticOrder, class EpiSub = NoSub, bool FAST = false>
; __device__ __forceinline__ void gemm_phase(LAS unsigned char* lds, const Gemm g, const Sched& S, const Epi& E, const EpiSub& ES = EpiSub()) {
;     ...
;             PG8_LDB(B0, 0, 0); PG8_LDB(B1, 0, 1); PG8_SCHED; PG8_LDA(At, 0, 0); PG8_STAGE(PG8_SA(1, 1), a1 + hstepA, voffA);
;             PG8_WAIT_V(8); PG8_WAIT_L(0); PG8_BAR; PG8_MMA(0, 0, At, B0); PG8_MMA(0, 1, At, B1); PG8_BAR; PG8_SCHED;
;             PG8_LDA(At, 0, 1); PG8_STAGE(PG8_SB(0, 0), b2, voffB); PG8_STAGE(PG8_SB(0, 1), b2 + hstepB, voffB); PG8_STAGE(PG8_SA(0, 0), a2, voffA);
;             PG8_WAIT_V(8); PG8_WAIT_L(0); PG8_BAR; PG8_MMA(1, 0, At, B0); PG8_MMA(1, 1, At, B1); PG8_BAR; PG8_SCHED;
;             PG8_LDB(B0, 1, 0); PG8_LDB(B1, 1, 1); PG8_SCHED; PG8_LDA(At, 1, 0); PG8_STAGE(PG8_SA(0, 1), a2 + hstepA, voffA);
;             PG8_WAIT_V(8); PG8_WAIT_L(0); PG8_BAR; PG8_MMA(0, 0, At, B0); PG8_MMA(0, 1, At, B1); PG8_BAR; PG8_SCHED;
;             PG8_LDA(At, 1, 1); PG8_STAGE(PG8_SB(1, 0), b3, voffB); PG8_STAGE(PG8_SB(1, 1), b3 + hstepB, voffB); PG8_STAGE(PG8_SA(1, 0), a3, voffA);
;             PG8_WAIT_V(8); PG8_WAIT_L(0); PG8_BAR; PG8_MMA(1, 0, At, B0); PG8_MMA(1, 1, At, B1); PG8_BAR; PG8_SCHED;
	s_add_i32 s26, s50, s28
	v_lshl_add_u64 v[190:191], v[190:191], 0, s[8:9]
	s_mov_b32 m0, s26
	ds_read_b128 v[182:185], v149 offset:49152
	ds_read_b128 v[186:189], v149 offset:50176
	ds_read_b128 v[194:197], v149 offset:51200
	ds_read_b128 v[198:201], v149 offset:52224
	ds_read_b128 v[202:205], v149 offset:53248
	ds_read_b128 v[206:209], v149 offset:54272
	ds_read_b128 v[210:213], v149 offset:55296
	ds_read_b128 v[214:217], v149 offset:56320
	global_load_lds_dwordx4 v[190:191], off
	s_add_i32 m0, s26, 0x2000
	s_add_u32 s24, s24, 0x80080
	v_lshl_add_u64 v[190:191], v[218:219], 0, s[8:9]
	s_addc_u32 s25, s25, 0
	s_add_i32 s26, s51, s28
	global_load_lds_dwordx4 v[190:191], off
	v_lshl_add_u64 v[190:191], s[24:25], 0, v[130:131]
	s_mov_b32 m0, s26
	s_nop 0
	global_load_lds_dwordx4 v[190:191], off
	v_lshl_add_u64 v[190:191], s[24:25], 0, v[134:135]
	s_add_i32 m0, s26, 0x2000
	s_nop 0
	global_load_lds_dwordx4 v[190:191], off
	v_lshl_add_u64 v[190:191], v[220:221], 0, s[8:9]
	s_mov_b32 m0, s40
	s_nop 0
	global_load_lds_dwordx4 v[190:191], off
	v_lshl_add_u64 v[190:191], v[222:223], 0, s[8:9]
	s_mov_b32 m0, s41
	s_nop 0
	global_load_lds_dwordx4 v[190:191], off
	s_waitcnt vmcnt(8)
	s_waitcnt lgkmcnt(0)
	s_barrier
	v_mfma_f32_16x16x32_bf16 v[60:63], v[150:153], v[182:185], v[60:63]
	v_mfma_f32_16x16x32_bf16 v[52:55], v[158:161], v[182:185], v[52:55]
	v_mfma_f32_16x16x32_bf16 v[44:47], v[150:153], v[194:197], v[44:47]
	v_mfma_f32_16x16x32_bf16 v[36:39], v[158:161], v[194:197], v[36:39]
	v_mfma_f32_16x16x32_bf16 v[28:31], v[150:153], v[202:205], v[28:31]
	v_mfma_f32_16x16x32_bf16 v[20:23], v[158:161], v[202:205], v[20:23]
	v_mfma_f32_16x16x32_bf16 v[12:15], v[150:153], v[210:213], v[12:15]
	v_mfma_f32_16x16x32_bf16 v[4:7], v[158:161], v[210:213], v[4:7]
	v_mfma_f32_16x16x32_bf16 v[60:63], v[154:157], v[186:189], v[60:63]
	v_mfma_f32_16x16x32_bf16 v[52:55], v[162:165], v[186:189], v[52:55]
	v_mfma_f32_16x16x32_bf16 v[44:47], v[154:157], v[198:201], v[44:47]
	v_mfma_f32_16x16x32_bf16 v[36:39], v[162:165], v[198:201], v[36:39]
	v_mfma_f32_16x16x32_bf16 v[28:31], v[154:157], v[206:209], v[28:31]
	v_mfma_f32_16x16x32_bf16 v[20:23], v[162:165], v[206:209], v[20:23]
	v_mfma_f32_16x16x32_bf16 v[12:15], v[154:157], v[214:217], v[12:15]
	v_mfma_f32_16x16x32_bf16 v[4:7], v[162:165], v[214:217], v[4:7]
	v_mfma_f32_16x16x32_bf16 v[56:59], v[166:169], v[182:185], v[56:59]
	v_mfma_f32_16x16x32_bf16 v[48:51], v[174:177], v[182:185], v[48:51]
	v_mfma_f32_16x16x32_bf16 v[40:43], v[166:169], v[194:197], v[40:43]
	v_mfma_f32_16x16x32_bf16 v[32:35], v[174:177], v[194:197], v[32:35]
	v_mfma_f32_16x16x32_bf16 v[24:27], v[166:169], v[202:205], v[24:27]
	v_mfma_f32_16x16x32_bf16 v[16:19], v[174:177], v[202:205], v[16:19]
	v_mfma_f32_16x16x32_bf16 v[8:11], v[166:169], v[210:213], v[8:11]
	v_mfma_f32_16x16x32_bf16 v[0:3], v[174:177], v[210:213], v[0:3]
	v_mfma_f32_16x16x32_bf16 v[56:59], v[170:173], v[186:189], v[56:59]
	v_mfma_f32_16x16x32_bf16 v[48:51], v[178:181], v[186:189], v[48:51]
	v_mfma_f32_16x16x32_bf16 v[40:43], v[170:173], v[198:201], v[40:43]
	v_mfma_f32_16x16x32_bf16 v[32:35], v[178:181], v[198:201], v[32:35]
	v_mfma_f32_16x16x32_bf16 v[24:27], v[170:173], v[206:209], v[24:27]
	v_mfma_f32_16x16x32_bf16 v[16:19], v[178:181], v[206:209], v[16:19]
	v_mfma_f32_16x16x32_bf16 v[8:11], v[170:173], v[214:217], v[8:11]
	v_mfma_f32_16x16x32_bf16 v[0:3], v[178:181], v[214:217], v[0:3]
	s_barrier
	s_add_i32 s49, s49, 2
	s_add_u32 s22, s22, 0x100
	s_addc_u32 s23, s23, 0
	s_add_u32 s47, s47, 0x100
	s_addc_u32 s48, s48, 0
	s_cmp_gt_u32 s49, 29
	s_cbranch_scc1 .Lkpeel_985_exit
.LBB0_985:
	ds_read_b128 v[150:153], v147
	ds_read_b128 v[154:157], v147 offset:1024
	ds_read_b128 v[158:161], v147 offset:2048
	ds_read_b128 v[162:165], v147 offset:3072
	ds_read_b128 v[166:169], v148
	ds_read_b128 v[170:173], v148 offset:1024
	ds_read_b128 v[174:177], v148 offset:2048
	ds_read_b128 v[178:181], v148 offset:3072
	s_add_u32 s24, s22, 0xfff80080
	s_addc_u32 s25, s23, -1
	s_cmp_eq_u32 s49, 28
	s_cselect_b32 s27, s15, s25
	s_cselect_b32 s26, s45, s24
	s_cselect_b32 s25, s13, s48
	s_cselect_b32 s24, s46, s47
	v_lshl_add_u64 v[190:191], s[22:23], 0, v[136:137]
	s_add_i32 m0, s21, 0xc000
	ds_read_b128 v[182:185], v149
	ds_read_b128 v[186:189], v149 offset:1024
	ds_read_b128 v[194:197], v149 offset:2048
	ds_read_b128 v[198:201], v149 offset:3072
	ds_read_b128 v[202:205], v149 offset:4096
	ds_read_b128 v[206:209], v149 offset:5120
	ds_read_b128 v[210:213], v149 offset:6144
	ds_read_b128 v[214:217], v149 offset:7168
	global_load_lds_dwordx4 v[190:191], off
	v_lshl_add_u64 v[190:191], s[22:23], 0, v[138:139]
	s_add_i32 m0, s21, 0xe000
	s_nop 0
	global_load_lds_dwordx4 v[190:191], off
	s_waitcnt vmcnt(8)
	s_waitcnt lgkmcnt(0)
	s_barrier
; #define PG8_STAGE(bufoff, gbase, voff) do { _Pragma("unroll") for (int _i = 0; _i < 2; ++_i) \
;         __builtin_amdgcn_global_load_lds((const unsigned*)((const char*)(gbase) + (voff)[_i]), (LAS unsigned*)(lds + (bufoff) + ldsw + _i * 8192), 16, 0, 0); } while (0)
; #define PG8_LDA(dst, b, h) do { _Pragma("unroll") for (int m = 0; m < 4; ++m) _Pragma("unroll") for (int k = 0; k < 2; ++k) dst[m][k] = *(const LAS bf16x8*)(lds + PG8_SA(b, h) + aoff + m * 2048 + k * 1024); } while (0)
; #define PG8_LDB(dst, b, h) do { _Pragma("unroll") for (int n = 0; n < 2; ++n) _Pragma("unroll") for (int k = 0; k < 2; ++k) dst[n][k] = *(const LAS bf16x8*)(lds + PG8_SB(b, h) + boff + n * 2048 + k * 1024); } while (0)
; #define PG8_MMA(ai, bj, At, Bt) do { __builtin_amdgcn_s_setprio(1); _Pragma("unroll") for (int m = 0; m < 4; ++m) _Pragma("unroll") for (int n = 0; n < 2; ++n) _Pragma("unroll") for (int k = 0; k < 2; ++k) \
;         acc[ai][bj][m][n] = __builtin_amdgcn_mfma_f32_16x16x32_bf16(Bt[n][k], At[m][k], acc[ai][bj][m][n], 0, 0, 0); __builtin_amdgcn_s_setprio(0); } while (0)
; #define PG8_WAIT_V(n) asm volatile("s_waitcnt vmcnt(" #n ")" ::: "memory")
; #define PG8_WAIT_L(n) asm volatile("s_waitcnt lgkmcnt(" #n ")" ::: "memory")
; #define PG8_BAR __builtin_amdgcn_s_barrier()
; #define PG8_SCHED __builtin_amdgcn_sched_barrier(0)
; template <class Epi, class Sched = StaticOrder, class EpiSub = NoSub, bool FAST = false>
; __device__ __forceinline__ void gemm_phase(LAS unsigned char* lds, const Gemm g, const Sched& S, const Epi& E, const EpiSub& ES = EpiSub()) {
;     ...
;             PG8_LDB(B0, 0, 0); PG8_LDB(B1, 0, 1); PG8_SCHED; PG8_LDA(At, 0, 0); PG8_STAGE(PG8_SA(1, 1), a1 + hstepA, voffA);
;             PG8_WAIT_V(8); PG8_WAIT_L(0); PG8_BAR; PG8_MMA(0, 0, At, B0); PG8_MMA(0, 1, At, B1); PG8_BAR; PG8_SCHED;
;             PG8_LDA(At, 0, 1); PG8_STAGE(PG8_SB(0, 0), b2, voffB); PG8_STAGE(PG8_SB(0, 1), b2 + hstepB, voffB); PG8_STAGE(PG8_SA(0, 0), a2, voffA);
;             PG8_WAIT_V(8); PG8_WAIT_L(0); PG8_BAR; PG8_MMA(1, 0, At, B0); PG8_MMA(1, 1, At, B1); PG8_BAR; PG8_SCHED;
;             PG8_LDB(B0, 1, 0); PG8_LDB(B1, 1, 1); PG8_SCHED; PG8_LDA(At, 1, 0); PG8_STAGE(PG8_SA(0, 1), a2 + hstepA, voffA);
;             PG8_WAIT_V(8); PG8_WAIT_L(0); PG8_BAR; PG8_MMA(0, 0, At, B0); PG8_MMA(0, 1, At, B1); PG8_BAR; PG8_SCHED;
	v_mfma_f32_16x16x32_bf16 v[124:127], v[150:153], v[182:185], v[124:127]
	v_mfma_f32_16x16x32_bf16 v[116:119], v[158:161], v[182:185], v[116:119]
	v_mfma_f32_16x16x32_bf16 v[108:111], v[150:153], v[194:197], v[108:111]
	v_mfma_f32_16x16x32_bf16 v[100:103], v[158:161], v[194:197], v[100:103]
	v_mfma_f32_16x16x32_bf16 v[92:95], v[150:153], v[202:205], v[92:95]
	v_mfma_f32_16x16x32_bf16 v[84:87], v[158:161], v[202:205], v[84:87]
	v_mfma_f32_16x16x32_bf16 v[76:79], v[150:153], v[210:213], v[76:79]
	v_mfma_f32_16x16x32_bf16 v[68:71], v[158:161], v[210:213], v[68:71]
	v_mfma_f32_16x16x32_bf16 v[124:127], v[154:157], v[186:189], v[124:127]
	v_mfma_f32_16x16x32_bf16 v[116:119], v[162:165], v[186:189], v[116:119]
	v_mfma_f32_16x16x32_bf16 v[108:111], v[154:157], v[198:201], v[108:111]
	v_mfma_f32_16x16x32_bf16 v[100:103], v[162:165], v[198:201], v[100:103]
	v_mfma_f32_16x16x32_bf16 v[92:95], v[154:157], v[206:209], v[92:95]
	v_mfma_f32_16x16x32_bf16 v[84:87], v[162:165], v[206:209], v[84:87]
	v_mfma_f32_16x16x32_bf16 v[76:79], v[154:157], v[214:217], v[76:79]
	v_mfma_f32_16x16x32_bf16 v[68:71], v[162:165], v[214:217], v[68:71]
	v_mfma_f32_16x16x32_bf16 v[120:123], v[166:169], v[182:185], v[120:123]
	v_mfma_f32_16x16x32_bf16 v[112:115], v[174:177], v[182:185], v[112:115]
	v_mfma_f32_16x16x32_bf16 v[104:107], v[166:169], v[194:197], v[104:107]
	v_mfma_f32_16x16x32_bf16 v[96:99], v[174:177], v[194:197], v[96:99]
	v_mfma_f32_16x16x32_bf16 v[88:91], v[166:169], v[202:205], v[88:91]
	v_mfma_f32_16x16x32_bf16 v[80:83], v[174:177], v[202:205], v[80:83]
	v_mfma_f32_16x16x32_bf16 v[72:75], v[166:169], v[210:213], v[72:75]
	v_mfma_f32_16x16x32_bf16 v[64:67], v[174:177], v[210:213], v[64:67]
	v_mfma_f32_16x16x32_bf16 v[120:123], v[170:173], v[186:189], v[120:123]
	v_mfma_f32_16x16x32_bf16 v[112:115], v[178:181], v[186:189], v[112:115]
	v_mfma_f32_16x16x32_bf16 v[104:107], v[170:173], v[198:201], v[104:107]
	v_mfma_f32_16x16x32_bf16 v[96:99], v[178:181], v[198:201], v[96:99]
	v_mfma_f32_16x16x32_bf16 v[88:91], v[170:173], v[206:209], v[88:91]
	v_mfma_f32_16x16x32_bf16 v[80:83], v[178:181], v[206:209], v[80:83]
	v_mfma_f32_16x16x32_bf16 v[72:75], v[170:173], v[214:217], v[72:75]
	v_mfma_f32_16x16x32_bf16 v[64:67], v[178:181], v[214:217], v[64:67]
	s_barrier
	s_add_i32 s50, s42, s28
	v_lshl_add_u64 v[190:191], s[24:25], 0, v[130:131]
	s_mov_b32 m0, s50
	ds_read_b128 v[182:185], v149 offset:16384
	ds_read_b128 v[186:189], v149 offset:17408
	ds_read_b128 v[194:197], v149 offset:18432
	ds_read_b128 v[198:201], v149 offset:19456
	ds_read_b128 v[202:205], v149 offset:20480
	ds_read_b128 v[206:209], v149 offset:21504
	ds_read_b128 v[210:213], v149 offset:22528
	ds_read_b128 v[214:217], v149 offset:23552
	global_load_lds_dwordx4 v[190:191], off
	s_add_i32 m0, s50, 0x2000
	s_add_u32 s50, s24, 0x80000
	v_lshl_add_u64 v[218:219], s[24:25], 0, v[134:135]
	s_addc_u32 s51, s25, 0
	s_add_i32 s52, s43, s28
	global_load_lds_dwordx4 v[218:219], off
	v_lshl_add_u64 v[220:221], s[50:51], 0, v[130:131]
	s_mov_b32 m0, s52
	v_lshl_add_u64 v[222:223], s[26:27], 0, v[132:133]
	global_load_lds_dwordx4 v[220:221], off
	v_lshl_add_u64 v[220:221], s[50:51], 0, v[134:135]
	s_add_i32 m0, s52, 0x2000
	s_nop 0
	global_load_lds_dwordx4 v[220:221], off
	v_lshl_add_u64 v[220:221], s[26:27], 0, v[128:129]
	s_mov_b32 m0, s21
	s_nop 0
	global_load_lds_dwordx4 v[220:221], off
	s_mov_b32 m0, s31
	s_nop 0
	global_load_lds_dwordx4 v[222:223], off
	s_waitcnt vmcnt(8)
	s_waitcnt lgkmcnt(0)
	s_barrier
	v_mfma_f32_16x16x32_bf16 v[60:63], v[150:153], v[182:185], v[60:63]
	v_mfma_f32_16x16x32_bf16 v[52:55], v[158:161], v[182:185], v[52:55]
	v_mfma_f32_16x16x32_bf16 v[44:47], v[150:153], v[194:197], v[44:47]
	v_mfma_f32_16x16x32_bf16 v[36:39], v[158:161], v[194:197], v[36:39]
	v_mfma_f32_16x16x32_bf16 v[28:31], v[150:153], v[202:205], v[28:31]
	v_mfma_f32_16x16x32_bf16 v[20:23], v[158:161], v[202:205], v[20:23]
	v_mfma_f32_16x16x32_bf16 v[12:15], v[150:153], v[210:213], v[12:15]
	v_mfma_f32_16x16x32_bf16 v[4:7], v[158:161], v[210:213], v[4:7]
	v_mfma_f32_16x16x32_bf16 v[60:63], v[154:157], v[186:189], v[60:63]
	v_mfma_f32_16x16x32_bf16 v[52:55], v[162:165], v[186:189], v[52:55]
	v_mfma_f32_16x16x32_bf16 v[44:47], v[154:157], v[198:201], v[44:47]
	v_mfma_f32_16x16x32_bf16 v[36:39], v[162:165], v[198:201], v[36:39]
	v_mfma_f32_16x16x32_bf16 v[28:31], v[154:157], v[206:209], v[28:31]
	v_mfma_f32_16x16x32_bf16 v[20:23], v[162:165], v[206:209], v[20:23]
	v_mfma_f32_16x16x32_bf16 v[12:15], v[154:157], v[214:217], v[12:15]
	v_mfma_f32_16x16x32_bf16 v[4:7], v[162:165], v[214:217], v[4:7]
	v_mfma_f32_16x16x32_bf16 v[56:59], v[166:169], v[182:185], v[56:59]
	v_mfma_f32_16x16x32_bf16 v[48:51], v[174:177], v[182:185], v[48:51]
	v_mfma_f32_16x16x32_bf16 v[40:43], v[166:169], v[194:197], v[40:43]
	v_mfma_f32_16x16x32_bf16 v[32:35], v[174:177], v[194:197], v[32:35]
	v_mfma_f32_16x16x32_bf16 v[24:27], v[166:169], v[202:205], v[24:27]
	v_mfma_f32_16x16x32_bf16 v[16:19], v[174:177], v[202:205], v[16:19]
	v_mfma_f32_16x16x32_bf16 v[8:11], v[166:169], v[210:213], v[8:11]
	v_mfma_f32_16x16x32_bf16 v[0:3], v[174:177], v[210:213], v[0:3]
	v_mfma_f32_16x16x32_bf16 v[56:59], v[170:173], v[186:189], v[56:59]
	v_mfma_f32_16x16x32_bf16 v[48:51], v[178:181], v[186:189], v[48:51]
	v_mfma_f32_16x16x32_bf16 v[40:43], v[170:173], v[198:201], v[40:43]
	v_mfma_f32_16x16x32_bf16 v[32:35], v[178:181], v[198:201], v[32:35]
	v_mfma_f32_16x16x32_bf16 v[24:27], v[170:173], v[206:209], v[24:27]
	v_mfma_f32_16x16x32_bf16 v[16:19], v[178:181], v[206:209], v[16:19]
	v_mfma_f32_16x16x32_bf16 v[8:11], v[170:173], v[214:217], v[8:11]
	v_mfma_f32_16x16x32_bf16 v[0:3], v[178:181], v[214:217], v[0:3]
	s_barrier
; #define PG8_STAGE(bufoff, gbase, voff) do { _Pragma("unroll") for (int _i = 0; _i < 2; ++_i) \
;         __builtin_amdgcn_global_load_lds((const unsigned*)((const char*)(gbase) + (voff)[_i]), (LAS unsigned*)(lds + (bufoff) + ldsw + _i * 8192), 16, 0, 0); } while (0)
; #define PG8_LDA(dst, b, h) do { _Pragma("unroll") for (int m = 0; m < 4; ++m) _Pragma("unroll") for (int k = 0; k < 2; ++k) dst[m][k] = *(const LAS bf16x8*)(lds + PG8_SA(b, h) + aoff + m * 2048 + k * 1024); } while (0)
; #define PG8_LDB(dst, b, h) do { _Pragma("unroll") for (int n = 0; n < 2; ++n) _Pragma("unroll") for (int k = 0; k < 2; ++k) dst[n][k] = *(const LAS bf16x8*)(lds + PG8_SB(b, h) + boff + n * 2048 + k * 1024); } while (0)
; #define PG8_MMA(ai, bj, At, Bt) do { __builtin_amdgcn_s_setprio(1); _Pragma("unroll") for (int m = 0; m < 4; ++m) _Pragma("unroll") for (int n = 0; n < 2; ++n) _Pragma("unroll") for (int k = 0; k < 2; ++k) \
;         acc[ai][bj][m][n] = __builtin_amdgcn_mfma_f32_16x16x32_bf16(Bt[n][k], At[m][k], acc[ai][bj][m][n], 0, 0, 0); __builtin_amdgcn_s_setprio(0); } while (0)
; #define PG8_WAIT_V(n) asm volatile("s_waitcnt vmcnt(" #n ")" ::: "memory")
; #define PG8_WAIT_L(n) asm volatile("s_waitcnt lgkmcnt(" #n ")" ::: "memory")
; #define PG8_BAR __builtin_amdgcn_s_barrier()
; #define PG8_SCHED __builtin_amdgcn_sched_barrier(0)
; template <class Epi, class Sched = StaticOrder, class EpiSub = NoSub, bool FAST = false>
; __device__ __forceinline__ void gemm_phase(LAS unsigned char* lds, const Gemm g, const Sched& S, const Epi& E, const EpiSub& ES = EpiSub()) {
;     ...
;         for (int t = 0; t < nt; t += 2) {
;     ...
;             PG8_LDB(B0, 1, 0); PG8_LDB(B1, 1, 1); PG8_SCHED; PG8_LDA(At, 1, 0); PG8_STAGE(PG8_SA(0, 1), a2 + hstepA, voffA);
;             PG8_WAIT_V(8); PG8_WAIT_L(0); PG8_BAR; PG8_MMA(0, 0, At, B0); PG8_MMA(0, 1, At, B1); PG8_BAR; PG8_SCHED;
;             PG8_LDA(At, 1, 1); PG8_STAGE(PG8_SB(1, 0), b3, voffB); PG8_STAGE(PG8_SB(1, 1), b3 + hstepB, voffB); PG8_STAGE(PG8_SA(1, 0), a3, voffA);
;             PG8_WAIT_V(8); PG8_WAIT_L(0); PG8_BAR; PG8_MMA(1, 0, At, B0); PG8_MMA(1, 1, At, B1); PG8_BAR; PG8_SCHED;
	s_add_i32 s50, 0, 0x18000
	s_add_i32 s51, 0, 0x1c000
	v_add_u32_e32 v162, s50, v145
	v_add_u32_e32 v178, s51, v145
	ds_read_b128 v[150:153], v162
	ds_read_b128 v[154:157], v162 offset:1024
	ds_read_b128 v[158:161], v162 offset:2048
	ds_read_b128 v[162:165], v162 offset:3072
	ds_read_b128 v[166:169], v178
	ds_read_b128 v[170:173], v178 offset:1024
	ds_read_b128 v[174:177], v178 offset:2048
	ds_read_b128 v[178:181], v178 offset:3072
	s_add_u32 s26, s26, 0x80000
	s_addc_u32 s27, s27, 0
	s_mov_b32 m0, s36
	v_lshl_add_u64 v[224:225], s[26:27], 0, v[128:129]
	ds_read_b128 v[182:185], v149 offset:32768
	ds_read_b128 v[186:189], v149 offset:33792
	ds_read_b128 v[194:197], v149 offset:34816
	ds_read_b128 v[198:201], v149 offset:35840
	ds_read_b128 v[202:205], v149 offset:36864
	ds_read_b128 v[206:209], v149 offset:37888
	ds_read_b128 v[210:213], v149 offset:38912
	ds_read_b128 v[214:217], v149 offset:39936
	global_load_lds_dwordx4 v[224:225], off
	v_lshl_add_u64 v[224:225], s[26:27], 0, v[132:133]
	s_mov_b32 m0, s37
	s_nop 0
	global_load_lds_dwordx4 v[224:225], off
	s_waitcnt vmcnt(8)
	s_waitcnt lgkmcnt(0)
	s_barrier
	v_mfma_f32_16x16x32_bf16 v[124:127], v[150:153], v[182:185], v[124:127]
	v_mfma_f32_16x16x32_bf16 v[116:119], v[158:161], v[182:185], v[116:119]
	v_mfma_f32_16x16x32_bf16 v[108:111], v[150:153], v[194:197], v[108:111]
	v_mfma_f32_16x16x32_bf16 v[100:103], v[158:161], v[194:197], v[100:103]
	v_mfma_f32_16x16x32_bf16 v[92:95], v[150:153], v[202:205], v[92:95]
	v_mfma_f32_16x16x32_bf16 v[84:87], v[158:161], v[202:205], v[84:87]
	v_mfma_f32_16x16x32_bf16 v[76:79], v[150:153], v[210:213], v[76:79]
	v_mfma_f32_16x16x32_bf16 v[68:71], v[158:161], v[210:213], v[68:71]
	v_mfma_f32_16x16x32_bf16 v[124:127], v[154:157], v[186:189], v[124:127]
	v_mfma_f32_16x16x32_bf16 v[116:119], v[162:165], v[186:189], v[116:119]
	v_mfma_f32_16x16x32_bf16 v[108:111], v[154:157], v[198:201], v[108:111]
	v_mfma_f32_16x16x32_bf16 v[100:103], v[162:165], v[198:201], v[100:103]
	v_mfma_f32_16x16x32_bf16 v[92:95], v[154:157], v[206:209], v[92:95]
	v_mfma_f32_16x16x32_bf16 v[84:87], v[162:165], v[206:209], v[84:87]
	v_mfma_f32_16x16x32_bf16 v[76:79], v[154:157], v[214:217], v[76:79]
	v_mfma_f32_16x16x32_bf16 v[68:71], v[162:165], v[214:217], v[68:71]
	v_mfma_f32_16x16x32_bf16 v[120:123], v[166:169], v[182:185], v[120:123]
	v_mfma_f32_16x16x32_bf16 v[112:115], v[174:177], v[182:185], v[112:115]
	v_mfma_f32_16x16x32_bf16 v[104:107], v[166:169], v[194:197], v[104:107]
	v_mfma_f32_16x16x32_bf16 v[96:99], v[174:177], v[194:197], v[96:99]
	v_mfma_f32_16x16x32_bf16 v[88:91], v[166:169], v[202:205], v[88:91]
	v_mfma_f32_16x16x32_bf16 v[80:83], v[174:177], v[202:205], v[80:83]
	v_mfma_f32_16x16x32_bf16 v[72:75], v[166:169], v[210:213], v[72:75]
	v_mfma_f32_16x16x32_bf16 v[64:67], v[174:177], v[210:213], v[64:67]
	v_mfma_f32_16x16x32_bf16 v[120:123], v[170:173], v[186:189], v[120:123]
	v_mfma_f32_16x16x32_bf16 v[112:115], v[178:181], v[186:189], v[112:115]
	v_mfma_f32_16x16x32_bf16 v[104:107], v[170:173], v[198:201], v[104:107]
	v_mfma_f32_16x16x32_bf16 v[96:99], v[178:181], v[198:201], v[96:99]
	v_mfma_f32_16x16x32_bf16 v[88:91], v[170:173], v[206:209], v[88:91]
	v_mfma_f32_16x16x32_bf16 v[80:83], v[178:181], v[206:209], v[80:83]
	v_mfma_f32_16x16x32_bf16 v[72:75], v[170:173], v[214:217], v[72:75]
	v_mfma_f32_16x16x32_bf16 v[64:67], v[178:181], v[214:217], v[64:67]
	s_barrier
	s_add_i32 s26, s50, s28
	v_lshl_add_u64 v[190:191], v[190:191], 0, s[8:9]
	s_mov_b32 m0, s26
	ds_read_b128 v[182:185], v149 offset:49152
	ds_read_b128 v[186:189], v149 offset:50176
	ds_read_b128 v[194:197], v149 offset:51200
	ds_read_b128 v[198:201], v149 offset:52224
	ds_read_b128 v[202:205], v149 offset:53248
	ds_read_b128 v[206:209], v149 offset:54272
	ds_read_b128 v[210:213], v149 offset:55296
	ds_read_b128 v[214:217], v149 offset:56320
	global_load_lds_dwordx4 v[190:191], off
	s_add_i32 m0, s26, 0x2000
	s_add_u32 s24, s24, 0x80080
	v_lshl_add_u64 v[190:191], v[218:219], 0, s[8:9]
	s_addc_u32 s25, s25, 0
	s_add_i32 s26, s51, s28
	global_load_lds_dwordx4 v[190:191], off
	v_lshl_add_u64 v[190:191], s[24:25], 0, v[130:131]
	s_mov_b32 m0, s26
	s_nop 0
	global_load_lds_dwordx4 v[190:191], off
	v_lshl_add_u64 v[190:191], s[24:25], 0, v[134:135]
	s_add_i32 m0, s26, 0x2000
	s_nop 0
	global_load_lds_dwordx4 v[190:191], off
	v_lshl_add_u64 v[190:191], v[220:221], 0, s[8:9]
	s_mov_b32 m0, s40
	s_nop 0
	global_load_lds_dwordx4 v[190:191], off
	v_lshl_add_u64 v[190:191], v[222:223], 0, s[8:9]
	s_mov_b32 m0, s41
	s_nop 0
	global_load_lds_dwordx4 v[190:191], off
	s_waitcnt vmcnt(8)
	s_waitcnt lgkmcnt(0)
	s_barrier
	v_mfma_f32_16x16x32_bf16 v[60:63], v[150:153], v[182:185], v[60:63]
	v_mfma_f32_16x16x32_bf16 v[52:55], v[158:161], v[182:185], v[52:55]
	v_mfma_f32_16x16x32_bf16 v[44:47], v[150:153], v[194:197], v[44:47]
	v_mfma_f32_16x16x32_bf16 v[36:39], v[158:161], v[194:197], v[36:39]
	v_mfma_f32_16x16x32_bf16 v[28:31], v[150:153], v[202:205], v[28:31]
	v_mfma_f32_16x16x32_bf16 v[20:23], v[158:161], v[202:205], v[20:23]
	v_mfma_f32_16x16x32_bf16 v[12:15], v[150:153], v[210:213], v[12:15]
	v_mfma_f32_16x16x32_bf16 v[4:7], v[158:161], v[210:213], v[4:7]
	v_mfma_f32_16x16x32_bf16 v[60:63], v[154:157], v[186:189], v[60:63]
	v_mfma_f32_16x16x32_bf16 v[52:55], v[162:165], v[186:189], v[52:55]
	v_mfma_f32_16x16x32_bf16 v[44:47], v[154:157], v[198:201], v[44:47]
	v_mfma_f32_16x16x32_bf16 v[36:39], v[162:165], v[198:201], v[36:39]
	v_mfma_f32_16x16x32_bf16 v[28:31], v[154:157], v[206:209], v[28:31]
	v_mfma_f32_16x16x32_bf16 v[20:23], v[162:165], v[206:209], v[20:23]
	v_mfma_f32_16x16x32_bf16 v[12:15], v[154:157], v[214:217], v[12:15]
	v_mfma_f32_16x16x32_bf16 v[4:7], v[162:165], v[214:217], v[4:7]
	v_mfma_f32_16x16x32_bf16 v[56:59], v[166:169], v[182:185], v[56:59]
	v_mfma_f32_16x16x32_bf16 v[48:51], v[174:177], v[182:185], v[48:51]
	v_mfma_f32_16x16x32_bf16 v[40:43], v[166:169], v[194:197], v[40:43]
	v_mfma_f32_16x16x32_bf16 v[32:35], v[174:177], v[194:197], v[32:35]
	v_mfma_f32_16x16x32_bf16 v[24:27], v[166:169], v[202:205], v[24:27]
	v_mfma_f32_16x16x32_bf16 v[16:19], v[174:177], v[202:205], v[16:19]
	v_mfma_f32_16x16x32_bf16 v[8:11], v[166:169], v[210:213], v[8:11]
	v_mfma_f32_16x16x32_bf16 v[0:3], v[174:177], v[210:213], v[0:3]
	v_mfma_f32_16x16x32_bf16 v[56:59], v[170:173], v[186:189], v[56:59]
	v_mfma_f32_16x16x32_bf16 v[48:51], v[178:181], v[186:189], v[48:51]
	v_mfma_f32_16x16x32_bf16 v[40:43], v[170:173], v[198:201], v[40:43]
	v_mfma_f32_16x16x32_bf16 v[32:35], v[178:181], v[198:201], v[32:35]
	v_mfma_f32_16x16x32_bf16 v[24:27], v[170:173], v[206:209], v[24:27]
	v_mfma_f32_16x16x32_bf16 v[16:19], v[178:181], v[206:209], v[16:19]
	v_mfma_f32_16x16x32_bf16 v[8:11], v[170:173], v[214:217], v[8:11]
	v_mfma_f32_16x16x32_bf16 v[0:3], v[178:181], v[214:217], v[0:3]
	s_barrier
	s_add_i32 s49, s49, 2
	s_add_u32 s22, s22, 0x100
	s_addc_u32 s23, s23, 0
	s_add_u32 s47, s47, 0x100
	s_addc_u32 s48, s48, 0
	s_cmp_gt_u32 s49, 29
	s_cbranch_scc0 .LBB0_985

; #define PG8_STAGE(bufoff, gbase, voff) do { _Pragma("unroll") for (int _i = 0; _i < 2; ++_i) \
;         __builtin_amdgcn_global_load_lds((const unsigned*)((const char*)(gbase) + (voff)[_i]), (LAS unsigned*)(lds + (bufoff) + ldsw + _i * 8192), 16, 0, 0); } while (0)
; #define PG8_LDA(dst, b, h) do { _Pragma("unroll") for (int m = 0; m < 4; ++m) _Pragma("unroll") for (int k = 0; k < 2; ++k) dst[m][k] = *(const LAS bf16x8*)(lds + PG8_SA(b, h) + aoff + m * 2048 + k * 1024); } while (0)
; #define PG8_LDB(dst, b, h) do { _Pragma("unroll") for (int n = 0; n < 2; ++n) _Pragma("unroll") for (int k = 0; k < 2; ++k) dst[n][k] = *(const LAS bf16x8*)(lds + PG8_SB(b, h) + boff + n * 2048 + k * 1024); } while (0)
; #define PG8_WAIT_V(n) asm volatile("s_waitcnt vmcnt(" #n ")" ::: "memory")
; #define PG8_WAIT_L(n) asm volatile("s_waitcnt lgkmcnt(" #n ")" ::: "memory")
; #define PG8_BAR __builtin_amdgcn_s_barrier()
; template <class Epi, class Sched = StaticOrder, class EpiSub = NoSub, bool FAST = false>
; __device__ __forceinline__ void gemm_phase(LAS unsigned char* lds, const Gemm g, const Sched& S, const Epi& E, const EpiSub& ES = EpiSub()) {
;     ...
;         const size_t nko = (has_next && nxt.kb >= 0) ? nxt.kb * ksubB : 0;
;         const char* nA = has_next ? (const char*)g.A + (size_t)nxt.pm * tstepA + (size_t)nxt.pn * g.acs + nko : cA; const char* nB = has_next ? (const char*)g.Bt + (size_t)nxt.pn * tstepB + nko : cB;
;         const int nt = cur.kb < 0 ? ntMain : ntSub;
;         for (int t = 0; t < nt; t += 2) {
;             const bool last = (t == nt - 2);
;             const char* a1 = cA + (size_t)(t + 1) * kstep;
;             const char* a2 = last ? nA : cA + (size_t)(t + 2) * kstep; const char* b2 = last ? nB : cB + (size_t)(t + 2) * kstep;
;             const char* a3 = a2 + kstep; const char* b3 = b2 + kstep;
;             if constexpr (FAST && PG8_SP2) {
;             PG8_LDB(B0, 0, 0); PG8_LDB(B1, 0, 1); PG8_SCHED; PG8_LDA(At, 0, 0); PG8_STAGE(PG8_SA(1, 1), a1 + hstepA, voffA);
;             PG8_WAIT_V(8); PG8_WAIT_L(0); PG8_BAR; PG8_MMA(0, 0, At, B0); PG8_MMA(0, 1, At, B1); PG8_BAR; PG8_SCHED;
;             PG8_LDA(At, 0, 1); PG8_STAGE(PG8_SB(0, 0), b2, voffB); PG8_STAGE(PG8_SB(0, 1), b2 + hstepB, voffB); PG8_STAGE(PG8_SA(0, 0), a2, voffA);
;             PG8_WAIT_V(8); PG8_WAIT_L(0); PG8_BAR; PG8_MMA(1, 0, At, B0); PG8_MMA(1, 1, At, B1); PG8_BAR; PG8_SCHED;
.LBB0_1078:
	s_cmp_gt_i32 s8, -1
	s_cselect_b64 s[4:5], -1, 0
	s_cmp_lt_i32 s8, 0
	s_cselect_b32 s70, 0x58, 22
	s_add_i32 s71, s70, -2
	s_add_u32 s42, s42, 0x160080
	s_addc_u32 s43, s43, 0
	s_add_u32 s83, s44, 0x100
	s_mov_b32 s46, 0
	s_addc_u32 s84, s45, 0
	ds_read_b128 v[96:99], v201
	ds_read_b128 v[100:103], v201 offset:1024
	ds_read_b128 v[108:111], v201 offset:2048
	ds_read_b128 v[116:119], v201 offset:3072
	ds_read_b128 v[144:147], v202
	ds_read_b128 v[148:151], v202 offset:1024
	ds_read_b128 v[152:155], v202 offset:2048
	ds_read_b128 v[156:159], v202 offset:3072
	s_add_i32 s85, s46, 2
	s_add_u32 s44, s42, 0xffea0080
	s_addc_u32 s45, s43, -1
	s_cmp_eq_u32 s71, s46
	s_cselect_b32 s46, s38, s44
	s_cselect_b32 s47, s39, s45
	s_cselect_b32 s45, s41, s84
	s_cselect_b32 s44, s40, s83
	v_lshl_add_u64 v[190:191], s[42:43], 0, v[176:177]
	s_add_i32 m0, s48, 0xc000
	ds_read_b128 v[160:163], v203
	ds_read_b128 v[164:167], v203 offset:1024
	ds_read_b128 v[182:185], v203 offset:2048
	ds_read_b128 v[186:189], v203 offset:3072
	ds_read_b128 v[194:197], v203 offset:4096
	ds_read_b128 v[204:207], v203 offset:5120
	ds_read_b128 v[208:211], v203 offset:6144
	ds_read_b128 v[212:215], v203 offset:7168
	global_load_lds_dwordx4 v[190:191], off
	v_lshl_add_u64 v[190:191], s[42:43], 0, v[178:179]
	s_add_i32 m0, s48, 0xe000
	s_nop 0
	global_load_lds_dwordx4 v[190:191], off
	s_waitcnt vmcnt(8)
	s_waitcnt lgkmcnt(0)
	s_barrier
	v_mfma_f32_16x16x32_bf16 v[140:143], v[96:99], v[160:163], 0
	v_mfma_f32_16x16x32_bf16 v[136:139], v[108:111], v[160:163], 0
	v_mfma_f32_16x16x32_bf16 v[124:127], v[96:99], v[182:185], 0
	v_mfma_f32_16x16x32_bf16 v[120:123], v[108:111], v[182:185], 0
	v_mfma_f32_16x16x32_bf16 v[92:95], v[96:99], v[194:197], 0
	v_mfma_f32_16x16x32_bf16 v[88:91], v[108:111], v[194:197], 0
	v_mfma_f32_16x16x32_bf16 v[76:79], v[96:99], v[208:211], 0
	v_mfma_f32_16x16x32_bf16 v[72:75], v[108:111], v[208:211], 0
	v_mfma_f32_16x16x32_bf16 v[140:143], v[100:103], v[164:167], v[140:143]
	v_mfma_f32_16x16x32_bf16 v[136:139], v[116:119], v[164:167], v[136:139]
	v_mfma_f32_16x16x32_bf16 v[124:127], v[100:103], v[186:189], v[124:127]
	v_mfma_f32_16x16x32_bf16 v[120:123], v[116:119], v[186:189], v[120:123]
	v_mfma_f32_16x16x32_bf16 v[92:95], v[100:103], v[204:207], v[92:95]
	v_mfma_f32_16x16x32_bf16 v[88:91], v[116:119], v[204:207], v[88:91]
	v_mfma_f32_16x16x32_bf16 v[76:79], v[100:103], v[212:215], v[76:79]
	v_mfma_f32_16x16x32_bf16 v[72:75], v[116:119], v[212:215], v[72:75]
	v_mfma_f32_16x16x32_bf16 v[132:135], v[144:147], v[160:163], 0
	v_mfma_f32_16x16x32_bf16 v[128:131], v[152:155], v[160:163], 0
	v_mfma_f32_16x16x32_bf16 v[112:115], v[144:147], v[182:185], 0
	v_mfma_f32_16x16x32_bf16 v[104:107], v[152:155], v[182:185], 0
	v_mfma_f32_16x16x32_bf16 v[84:87], v[144:147], v[194:197], 0
	v_mfma_f32_16x16x32_bf16 v[80:83], v[152:155], v[194:197], 0
	v_mfma_f32_16x16x32_bf16 v[68:71], v[144:147], v[208:211], 0
	v_mfma_f32_16x16x32_bf16 v[64:67], v[152:155], v[208:211], 0
	v_mfma_f32_16x16x32_bf16 v[132:135], v[148:151], v[164:167], v[132:135]
	v_mfma_f32_16x16x32_bf16 v[128:131], v[156:159], v[164:167], v[128:131]
	v_mfma_f32_16x16x32_bf16 v[112:115], v[148:151], v[186:189], v[112:115]
	v_mfma_f32_16x16x32_bf16 v[104:107], v[156:159], v[186:189], v[104:107]
	v_mfma_f32_16x16x32_bf16 v[84:87], v[148:151], v[204:207], v[84:87]
	v_mfma_f32_16x16x32_bf16 v[80:83], v[156:159], v[204:207], v[80:83]
	v_mfma_f32_16x16x32_bf16 v[68:71], v[148:151], v[212:215], v[68:71]
	v_mfma_f32_16x16x32_bf16 v[64:67], v[156:159], v[212:215], v[64:67]
	s_barrier
	s_add_i32 s86, s58, s27
	v_lshl_add_u64 v[190:191], s[44:45], 0, v[170:171]
	s_mov_b32 m0, s86
	ds_read_b128 v[160:163], v203 offset:16384
	ds_read_b128 v[164:167], v203 offset:17408
	ds_read_b128 v[182:185], v203 offset:18432
	ds_read_b128 v[186:189], v203 offset:19456
	ds_read_b128 v[194:197], v203 offset:20480
	ds_read_b128 v[204:207], v203 offset:21504
	ds_read_b128 v[208:211], v203 offset:22528
	ds_read_b128 v[212:215], v203 offset:23552
	global_load_lds_dwordx4 v[190:191], off
	s_add_i32 m0, s86, 0x2000
	s_add_u32 s86, s44, 0x160000
	v_lshl_add_u64 v[216:217], s[44:45], 0, v[174:175]
	s_addc_u32 s87, s45, 0
	s_add_i32 s88, s59, s27
	global_load_lds_dwordx4 v[216:217], off
	v_lshl_add_u64 v[218:219], s[86:87], 0, v[170:171]
	s_mov_b32 m0, s88
	v_lshl_add_u64 v[220:221], s[46:47], 0, v[172:173]
	global_load_lds_dwordx4 v[218:219], off
	v_lshl_add_u64 v[218:219], s[86:87], 0, v[174:175]
	s_add_i32 m0, s88, 0x2000
	s_nop 0
	global_load_lds_dwordx4 v[218:219], off
	v_lshl_add_u64 v[218:219], s[46:47], 0, v[168:169]
	s_mov_b32 m0, s48
	s_nop 0
	global_load_lds_dwordx4 v[218:219], off
	s_mov_b32 m0, s49
	s_nop 0
	global_load_lds_dwordx4 v[220:221], off
	s_waitcnt vmcnt(8)
	s_waitcnt lgkmcnt(0)
	s_barrier
; #define PG8_STAGE(bufoff, gbase, voff) do { _Pragma("unroll") for (int _i = 0; _i < 2; ++_i) \
;         __builtin_amdgcn_global_load_lds((const unsigned*)((const char*)(gbase) + (voff)[_i]), (LAS unsigned*)(lds + (bufoff) + ldsw + _i * 8192), 16, 0, 0); } while (0)
; #define PG8_LDA(dst, b, h) do { _Pragma("unroll") for (int m = 0; m < 4; ++m) _Pragma("unroll") for (int k = 0; k < 2; ++k) dst[m][k] = *(const LAS bf16x8*)(lds + PG8_SA(b, h) + aoff + m * 2048 + k * 1024); } while (0)
; #define PG8_LDB(dst, b, h) do { _Pragma("unroll") for (int n = 0; n < 2; ++n) _Pragma("unroll") for (int k = 0; k < 2; ++k) dst[n][k] = *(const LAS bf16x8*)(lds + PG8_SB(b, h) + boff + n * 2048 + k * 1024); } while (0)
; #define PG8_MMA(ai, bj, At, Bt) do { __builtin_amdgcn_s_setprio(1); _Pragma("unroll") for (int m = 0; m < 4; ++m) _Pragma("unroll") for (int n = 0; n < 2; ++n) _Pragma("unroll") for (int k = 0; k < 2; ++k) \
;         acc[ai][bj][m][n] = __builtin_amdgcn_mfma_f32_16x16x32_bf16(Bt[n][k], At[m][k], acc[ai][bj][m][n], 0, 0, 0); __builtin_amdgcn_s_setprio(0); } while (0)
; #define PG8_WAIT_V(n) asm volatile("s_waitcnt vmcnt(" #n ")" ::: "memory")
; #define PG8_WAIT_L(n) asm volatile("s_waitcnt lgkmcnt(" #n ")" ::: "memory")
; #define PG8_BAR __builtin_amdgcn_s_barrier()
; #define PG8_SCHED __builtin_amdgcn_sched_barrier(0)
; template <class Epi, class Sched = StaticOrder, class EpiSub = NoSub, bool FAST = false>
; __device__ __forceinline__ void gemm_phase(LAS unsigned char* lds, const Gemm g, const Sched& S, const Epi& E, const EpiSub& ES = EpiSub()) {
;     ...
;             PG8_WAIT_V(8); PG8_WAIT_L(0); PG8_BAR; PG8_MMA(1, 0, At, B0); PG8_MMA(1, 1, At, B1); PG8_BAR; PG8_SCHED;
;             PG8_LDB(B0, 1, 0); PG8_LDB(B1, 1, 1); PG8_SCHED; PG8_LDA(At, 1, 0); PG8_STAGE(PG8_SA(0, 1), a2 + hstepA, voffA);
;             PG8_WAIT_V(8); PG8_WAIT_L(0); PG8_BAR; PG8_MMA(0, 0, At, B0); PG8_MMA(0, 1, At, B1); PG8_BAR; PG8_SCHED;
	v_mfma_f32_16x16x32_bf16 v[60:63], v[96:99], v[160:163], 0
	v_mfma_f32_16x16x32_bf16 v[56:59], v[108:111], v[160:163], 0
	v_mfma_f32_16x16x32_bf16 v[44:47], v[96:99], v[182:185], 0
	v_mfma_f32_16x16x32_bf16 v[40:43], v[108:111], v[182:185], 0
	v_mfma_f32_16x16x32_bf16 v[28:31], v[96:99], v[194:197], 0
	v_mfma_f32_16x16x32_bf16 v[24:27], v[108:111], v[194:197], 0
	v_mfma_f32_16x16x32_bf16 v[12:15], v[96:99], v[208:211], 0
	v_mfma_f32_16x16x32_bf16 v[8:11], v[108:111], v[208:211], 0
	v_mfma_f32_16x16x32_bf16 v[60:63], v[100:103], v[164:167], v[60:63]
	v_mfma_f32_16x16x32_bf16 v[56:59], v[116:119], v[164:167], v[56:59]
	v_mfma_f32_16x16x32_bf16 v[44:47], v[100:103], v[186:189], v[44:47]
	v_mfma_f32_16x16x32_bf16 v[40:43], v[116:119], v[186:189], v[40:43]
	v_mfma_f32_16x16x32_bf16 v[28:31], v[100:103], v[204:207], v[28:31]
	v_mfma_f32_16x16x32_bf16 v[24:27], v[116:119], v[204:207], v[24:27]
	v_mfma_f32_16x16x32_bf16 v[12:15], v[100:103], v[212:215], v[12:15]
	v_mfma_f32_16x16x32_bf16 v[8:11], v[116:119], v[212:215], v[8:11]
	v_mfma_f32_16x16x32_bf16 v[52:55], v[144:147], v[160:163], 0
	v_mfma_f32_16x16x32_bf16 v[48:51], v[152:155], v[160:163], 0
	v_mfma_f32_16x16x32_bf16 v[36:39], v[144:147], v[182:185], 0
	v_mfma_f32_16x16x32_bf16 v[32:35], v[152:155], v[182:185], 0
	v_mfma_f32_16x16x32_bf16 v[20:23], v[144:147], v[194:197], 0
	v_mfma_f32_16x16x32_bf16 v[16:19], v[152:155], v[194:197], 0
	v_mfma_f32_16x16x32_bf16 v[4:7], v[144:147], v[208:211], 0
	v_mfma_f32_16x16x32_bf16 v[0:3], v[152:155], v[208:211], 0
	v_mfma_f32_16x16x32_bf16 v[52:55], v[148:151], v[164:167], v[52:55]
	v_mfma_f32_16x16x32_bf16 v[48:51], v[156:159], v[164:167], v[48:51]
	v_mfma_f32_16x16x32_bf16 v[36:39], v[148:151], v[186:189], v[36:39]
	v_mfma_f32_16x16x32_bf16 v[32:35], v[156:159], v[186:189], v[32:35]
	v_mfma_f32_16x16x32_bf16 v[20:23], v[148:151], v[204:207], v[20:23]
	v_mfma_f32_16x16x32_bf16 v[16:19], v[156:159], v[204:207], v[16:19]
	v_mfma_f32_16x16x32_bf16 v[4:7], v[148:151], v[212:215], v[4:7]
	v_mfma_f32_16x16x32_bf16 v[0:3], v[156:159], v[212:215], v[0:3]
	s_barrier
	s_add_i32 s86, 0, 0x18000
	s_add_i32 s87, 0, 0x1c000
	v_add_u32_e32 v116, s86, v198
	v_add_u32_e32 v156, s87, v198
	ds_read_b128 v[96:99], v116
	ds_read_b128 v[100:103], v116 offset:1024
	ds_read_b128 v[108:111], v116 offset:2048
	ds_read_b128 v[116:119], v116 offset:3072
	ds_read_b128 v[144:147], v156
	ds_read_b128 v[148:151], v156 offset:1024
	ds_read_b128 v[152:155], v156 offset:2048
	ds_read_b128 v[156:159], v156 offset:3072
	s_add_u32 s46, s46, 0x160000
	s_addc_u32 s47, s47, 0
	s_mov_b32 m0, s50
	v_lshl_add_u64 v[222:223], s[46:47], 0, v[168:169]
	ds_read_b128 v[160:163], v203 offset:32768
	ds_read_b128 v[164:167], v203 offset:33792
	ds_read_b128 v[182:185], v203 offset:34816
	ds_read_b128 v[186:189], v203 offset:35840
	ds_read_b128 v[194:197], v203 offset:36864
	ds_read_b128 v[204:207], v203 offset:37888
	ds_read_b128 v[208:211], v203 offset:38912
	ds_read_b128 v[212:215], v203 offset:39936
	global_load_lds_dwordx4 v[222:223], off
	v_lshl_add_u64 v[222:223], s[46:47], 0, v[172:173]
	s_mov_b32 m0, s51
	s_nop 0
	global_load_lds_dwordx4 v[222:223], off
	s_waitcnt vmcnt(8)
	s_waitcnt lgkmcnt(0)
	s_barrier
	v_mfma_f32_16x16x32_bf16 v[140:143], v[96:99], v[160:163], v[140:143]
	v_mfma_f32_16x16x32_bf16 v[136:139], v[108:111], v[160:163], v[136:139]
	v_mfma_f32_16x16x32_bf16 v[124:127], v[96:99], v[182:185], v[124:127]
	v_mfma_f32_16x16x32_bf16 v[120:123], v[108:111], v[182:185], v[120:123]
	v_mfma_f32_16x16x32_bf16 v[92:95], v[96:99], v[194:197], v[92:95]
	v_mfma_f32_16x16x32_bf16 v[88:91], v[108:111], v[194:197], v[88:91]
	v_mfma_f32_16x16x32_bf16 v[76:79], v[96:99], v[208:211], v[76:79]
	v_mfma_f32_16x16x32_bf16 v[72:75], v[108:111], v[208:211], v[72:75]
	v_mfma_f32_16x16x32_bf16 v[140:143], v[100:103], v[164:167], v[140:143]
	v_mfma_f32_16x16x32_bf16 v[136:139], v[116:119], v[164:167], v[136:139]
	v_mfma_f32_16x16x32_bf16 v[124:127], v[100:103], v[186:189], v[124:127]
	v_mfma_f32_16x16x32_bf16 v[120:123], v[116:119], v[186:189], v[120:123]
	v_mfma_f32_16x16x32_bf16 v[92:95], v[100:103], v[204:207], v[92:95]
	v_mfma_f32_16x16x32_bf16 v[88:91], v[116:119], v[204:207], v[88:91]
	v_mfma_f32_16x16x32_bf16 v[76:79], v[100:103], v[212:215], v[76:79]
	v_mfma_f32_16x16x32_bf16 v[72:75], v[116:119], v[212:215], v[72:75]
	v_mfma_f32_16x16x32_bf16 v[132:135], v[144:147], v[160:163], v[132:135]
	v_mfma_f32_16x16x32_bf16 v[128:131], v[152:155], v[160:163], v[128:131]
	v_mfma_f32_16x16x32_bf16 v[112:115], v[144:147], v[182:185], v[112:115]
	v_mfma_f32_16x16x32_bf16 v[104:107], v[152:155], v[182:185], v[104:107]
	v_mfma_f32_16x16x32_bf16 v[84:87], v[144:147], v[194:197], v[84:87]
	v_mfma_f32_16x16x32_bf16 v[80:83], v[152:155], v[194:197], v[80:83]
	v_mfma_f32_16x16x32_bf16 v[68:71], v[144:147], v[208:211], v[68:71]
	v_mfma_f32_16x16x32_bf16 v[64:67], v[152:155], v[208:211], v[64:67]
	v_mfma_f32_16x16x32_bf16 v[132:135], v[148:151], v[164:167], v[132:135]
	v_mfma_f32_16x16x32_bf16 v[128:131], v[156:159], v[164:167], v[128:131]
	v_mfma_f32_16x16x32_bf16 v[112:115], v[148:151], v[186:189], v[112:115]
	v_mfma_f32_16x16x32_bf16 v[104:107], v[156:159], v[186:189], v[104:107]
	v_mfma_f32_16x16x32_bf16 v[84:87], v[148:151], v[204:207], v[84:87]
	v_mfma_f32_16x16x32_bf16 v[80:83], v[156:159], v[204:207], v[80:83]
	v_mfma_f32_16x16x32_bf16 v[68:71], v[148:151], v[212:215], v[68:71]
	v_mfma_f32_16x16x32_bf16 v[64:67], v[156:159], v[212:215], v[64:67]
	s_barrier
; #define PG8_STAGE(bufoff, gbase, voff) do { _Pragma("unroll") for (int _i = 0; _i < 2; ++_i) \
;         __builtin_amdgcn_global_load_lds((const unsigned*)((const char*)(gbase) + (voff)[_i]), (LAS unsigned*)(lds + (bufoff) + ldsw + _i * 8192), 16, 0, 0); } while (0)
; #define PG8_LDA(dst, b, h) do { _Pragma("unroll") for (int m = 0; m < 4; ++m) _Pragma("unroll") for (int k = 0; k < 2; ++k) dst[m][k] = *(const LAS bf16x8*)(lds + PG8_SA(b, h) + aoff + m * 2048 + k * 1024); } while (0)
; #define PG8_LDB(dst, b, h) do { _Pragma("unroll") for (int n = 0; n < 2; ++n) _Pragma("unroll") for (int k = 0; k < 2; ++k) dst[n][k] = *(const LAS bf16x8*)(lds + PG8_SB(b, h) + boff + n * 2048 + k * 1024); } while (0)
; #define PG8_MMA(ai, bj, At, Bt) do { __builtin_amdgcn_s_setprio(1); _Pragma("unroll") for (int m = 0; m < 4; ++m) _Pragma("unroll") for (int n = 0; n < 2; ++n) _Pragma("unroll") for (int k = 0; k < 2; ++k) \
;         acc[ai][bj][m][n] = __builtin_amdgcn_mfma_f32_16x16x32_bf16(Bt[n][k], At[m][k], acc[ai][bj][m][n], 0, 0, 0); __builtin_amdgcn_s_setprio(0); } while (0)
; #define PG8_BAR __builtin_amdgcn_s_barrier()
; template <class Epi, class Sched = StaticOrder, class EpiSub = NoSub, bool FAST = false>
; __device__ __forceinline__ void gemm_phase(LAS unsigned char* lds, const Gemm g, const Sched& S, const Epi& E, const EpiSub& ES = EpiSub()) {
;     ...
;             PG8_LDB(B0, 0, 0); PG8_LDB(B1, 0, 1); PG8_SCHED; PG8_LDA(At, 0, 0); PG8_STAGE(PG8_SA(1, 1), a1 + hstepA, voffA);
;             PG8_WAIT_V(8); PG8_WAIT_L(0); PG8_BAR; PG8_MMA(0, 0, At, B0); PG8_MMA(0, 1, At, B1); PG8_BAR; PG8_SCHED;
;             PG8_LDA(At, 0, 1); PG8_STAGE(PG8_SB(0, 0), b2, voffB); PG8_STAGE(PG8_SB(0, 1), b2 + hstepB, voffB); PG8_STAGE(PG8_SA(0, 0), a2, voffA);
;             PG8_WAIT_V(8); PG8_WAIT_L(0); PG8_BAR; PG8_MMA(1, 0, At, B0); PG8_MMA(1, 1, At, B1); PG8_BAR; PG8_SCHED;
;             PG8_LDB(B0, 1, 0); PG8_LDB(B1, 1, 1); PG8_SCHED; PG8_LDA(At, 1, 0); PG8_STAGE(PG8_SA(0, 1), a2 + hstepA, voffA);
;             PG8_WAIT_V(8); PG8_WAIT_L(0); PG8_BAR; PG8_MMA(0, 0, At, B0); PG8_MMA(0, 1, At, B1); PG8_BAR; PG8_SCHED;
;             PG8_LDA(At, 1, 1); PG8_STAGE(PG8_SB(1, 0), b3, voffB); PG8_STAGE(PG8_SB(1, 1), b3 + hstepB, voffB); PG8_STAGE(PG8_SA(1, 0), a3, voffA);
;             PG8_WAIT_V(8); PG8_WAIT_L(0); PG8_BAR; PG8_MMA(1, 0, At, B0); PG8_MMA(1, 1, At, B1); PG8_BAR; PG8_SCHED;
	s_add_i32 s46, s86, s27
	v_lshl_add_u64 v[190:191], v[190:191], 0, s[16:17]
	s_mov_b32 m0, s46
	ds_read_b128 v[160:163], v203 offset:49152
	ds_read_b128 v[164:167], v203 offset:50176
	ds_read_b128 v[182:185], v203 offset:51200
	ds_read_b128 v[186:189], v203 offset:52224
	ds_read_b128 v[194:197], v203 offset:53248
	ds_read_b128 v[204:207], v203 offset:54272
	ds_read_b128 v[208:211], v203 offset:55296
	ds_read_b128 v[212:215], v203 offset:56320
	global_load_lds_dwordx4 v[190:191], off
	s_add_i32 m0, s46, 0x2000
	s_add_u32 s44, s44, 0x160080
	v_lshl_add_u64 v[190:191], v[216:217], 0, s[16:17]
	s_addc_u32 s45, s45, 0
	s_add_i32 s46, s87, s27
	global_load_lds_dwordx4 v[190:191], off
	v_lshl_add_u64 v[190:191], s[44:45], 0, v[170:171]
	s_mov_b32 m0, s46
	s_nop 0
	global_load_lds_dwordx4 v[190:191], off
	v_lshl_add_u64 v[190:191], s[44:45], 0, v[174:175]
	s_add_i32 m0, s46, 0x2000
	s_nop 0
	global_load_lds_dwordx4 v[190:191], off
	v_lshl_add_u64 v[190:191], v[218:219], 0, s[16:17]
	s_mov_b32 m0, s53
	s_nop 0
	global_load_lds_dwordx4 v[190:191], off
	v_lshl_add_u64 v[190:191], v[220:221], 0, s[16:17]
	s_mov_b32 m0, s54
	s_nop 0
	global_load_lds_dwordx4 v[190:191], off
	s_waitcnt vmcnt(8)
	s_waitcnt lgkmcnt(0)
	s_barrier
	v_mfma_f32_16x16x32_bf16 v[60:63], v[96:99], v[160:163], v[60:63]
	v_mfma_f32_16x16x32_bf16 v[56:59], v[108:111], v[160:163], v[56:59]
	v_mfma_f32_16x16x32_bf16 v[44:47], v[96:99], v[182:185], v[44:47]
	v_mfma_f32_16x16x32_bf16 v[40:43], v[108:111], v[182:185], v[40:43]
	v_mfma_f32_16x16x32_bf16 v[28:31], v[96:99], v[194:197], v[28:31]
	v_mfma_f32_16x16x32_bf16 v[24:27], v[108:111], v[194:197], v[24:27]
	v_mfma_f32_16x16x32_bf16 v[12:15], v[96:99], v[208:211], v[12:15]
	v_mfma_f32_16x16x32_bf16 v[8:11], v[108:111], v[208:211], v[8:11]
	v_mfma_f32_16x16x32_bf16 v[60:63], v[100:103], v[164:167], v[60:63]
	v_mfma_f32_16x16x32_bf16 v[56:59], v[116:119], v[164:167], v[56:59]
	v_mfma_f32_16x16x32_bf16 v[44:47], v[100:103], v[186:189], v[44:47]
	v_mfma_f32_16x16x32_bf16 v[40:43], v[116:119], v[186:189], v[40:43]
	v_mfma_f32_16x16x32_bf16 v[28:31], v[100:103], v[204:207], v[28:31]
	v_mfma_f32_16x16x32_bf16 v[24:27], v[116:119], v[204:207], v[24:27]
	v_mfma_f32_16x16x32_bf16 v[12:15], v[100:103], v[212:215], v[12:15]
	v_mfma_f32_16x16x32_bf16 v[8:11], v[116:119], v[212:215], v[8:11]
	v_mfma_f32_16x16x32_bf16 v[52:55], v[144:147], v[160:163], v[52:55]
	v_mfma_f32_16x16x32_bf16 v[48:51], v[152:155], v[160:163], v[48:51]
	v_mfma_f32_16x16x32_bf16 v[36:39], v[144:147], v[182:185], v[36:39]
	v_mfma_f32_16x16x32_bf16 v[32:35], v[152:155], v[182:185], v[32:35]
	v_mfma_f32_16x16x32_bf16 v[20:23], v[144:147], v[194:197], v[20:23]
	v_mfma_f32_16x16x32_bf16 v[16:19], v[152:155], v[194:197], v[16:19]
	v_mfma_f32_16x16x32_bf16 v[4:7], v[144:147], v[208:211], v[4:7]
	v_mfma_f32_16x16x32_bf16 v[0:3], v[152:155], v[208:211], v[0:3]
	v_mfma_f32_16x16x32_bf16 v[52:55], v[148:151], v[164:167], v[52:55]
	v_mfma_f32_16x16x32_bf16 v[48:51], v[156:159], v[164:167], v[48:51]
	v_mfma_f32_16x16x32_bf16 v[36:39], v[148:151], v[186:189], v[36:39]
	v_mfma_f32_16x16x32_bf16 v[32:35], v[156:159], v[186:189], v[32:35]
	v_mfma_f32_16x16x32_bf16 v[20:23], v[148:151], v[204:207], v[20:23]
	v_mfma_f32_16x16x32_bf16 v[16:19], v[156:159], v[204:207], v[16:19]
	v_mfma_f32_16x16x32_bf16 v[4:7], v[148:151], v[212:215], v[4:7]
	v_mfma_f32_16x16x32_bf16 v[0:3], v[156:159], v[212:215], v[0:3]
	s_barrier
	s_add_u32 s42, s42, 0x100
	s_addc_u32 s43, s43, 0
	s_add_u32 s83, s83, 0x100
	s_addc_u32 s84, s84, 0
	s_cmp_ge_u32 s85, s70
	s_mov_b32 s46, s85
	s_cbranch_scc1 .Lkpeel_1079_exit
.LBB0_1079:
	ds_read_b128 v[96:99], v201
	ds_read_b128 v[100:103], v201 offset:1024
	ds_read_b128 v[108:111], v201 offset:2048
	ds_read_b128 v[116:119], v201 offset:3072
	ds_read_b128 v[144:147], v202
	ds_read_b128 v[148:151], v202 offset:1024
	ds_read_b128 v[152:155], v202 offset:2048
	ds_read_b128 v[156:159], v202 offset:3072
	s_add_i32 s85, s46, 2
	s_add_u32 s44, s42, 0xffea0080
	s_addc_u32 s45, s43, -1
	s_cmp_eq_u32 s71, s46
	s_cselect_b32 s46, s38, s44
	s_cselect_b32 s47, s39, s45
	s_cselect_b32 s45, s41, s84
	s_cselect_b32 s44, s40, s83
	v_lshl_add_u64 v[190:191], s[42:43], 0, v[176:177]
	s_add_i32 m0, s48, 0xc000
	ds_read_b128 v[160:163], v203
	ds_read_b128 v[164:167], v203 offset:1024
	ds_read_b128 v[182:185], v203 offset:2048
	ds_read_b128 v[186:189], v203 offset:3072
	ds_read_b128 v[194:197], v203 offset:4096
	ds_read_b128 v[204:207], v203 offset:5120
	ds_read_b128 v[208:211], v203 offset:6144
	ds_read_b128 v[212:215], v203 offset:7168
	global_load_lds_dwordx4 v[190:191], off
	v_lshl_add_u64 v[190:191], s[42:43], 0, v[178:179]
	s_add_i32 m0, s48, 0xe000
	s_nop 0
	global_load_lds_dwordx4 v[190:191], off
	s_waitcnt vmcnt(8)
	s_waitcnt lgkmcnt(0)
	s_barrier
; #define PG8_STAGE(bufoff, gbase, voff) do { _Pragma("unroll") for (int _i = 0; _i < 2; ++_i) \
;         __builtin_amdgcn_global_load_lds((const unsigned*)((const char*)(gbase) + (voff)[_i]), (LAS unsigned*)(lds + (bufoff) + ldsw + _i * 8192), 16, 0, 0); } while (0)
; #define PG8_LDA(dst, b, h) do { _Pragma("unroll") for (int m = 0; m < 4; ++m) _Pragma("unroll") for (int k = 0; k < 2; ++k) dst[m][k] = *(const LAS bf16x8*)(lds + PG8_SA(b, h) + aoff + m * 2048 + k * 1024); } while (0)
; #define PG8_LDB(dst, b, h) do { _Pragma("unroll") for (int n = 0; n < 2; ++n) _Pragma("unroll") for (int k = 0; k < 2; ++k) dst[n][k] = *(const LAS bf16x8*)(lds + PG8_SB(b, h) + boff + n * 2048 + k * 1024); } while (0)
; #define PG8_MMA(ai, bj, At, Bt) do { __builtin_amdgcn_s_setprio(1); _Pragma("unroll") for (int m = 0; m < 4; ++m) _Pragma("unroll") for (int n = 0; n < 2; ++n) _Pragma("unroll") for (int k = 0; k < 2; ++k) \
;         acc[ai][bj][m][n] = __builtin_amdgcn_mfma_f32_16x16x32_bf16(Bt[n][k], At[m][k], acc[ai][bj][m][n], 0, 0, 0); __builtin_amdgcn_s_setprio(0); } while (0)
; #define PG8_WAIT_V(n) asm volatile("s_waitcnt vmcnt(" #n ")" ::: "memory")
; #define PG8_WAIT_L(n) asm volatile("s_waitcnt lgkmcnt(" #n ")" ::: "memory")
; #define PG8_BAR __builtin_amdgcn_s_barrier()
; #define PG8_SCHED __builtin_amdgcn_sched_barrier(0)
; template <class Epi, class Sched = StaticOrder, class EpiSub = NoSub, bool FAST = false>
; __device__ __forceinline__ void gemm_phase(LAS unsigned char* lds, const Gemm g, const Sched& S, const Epi& E, const EpiSub& ES = EpiSub()) {
;     ...
;             PG8_LDB(B0, 0, 0); PG8_LDB(B1, 0, 1); PG8_SCHED; PG8_LDA(At, 0, 0); PG8_STAGE(PG8_SA(1, 1), a1 + hstepA, voffA);
;             PG8_WAIT_V(8); PG8_WAIT_L(0); PG8_BAR; PG8_MMA(0, 0, At, B0); PG8_MMA(0, 1, At, B1); PG8_BAR; PG8_SCHED;
;             PG8_LDA(At, 0, 1); PG8_STAGE(PG8_SB(0, 0), b2, voffB); PG8_STAGE(PG8_SB(0, 1), b2 + hstepB, voffB); PG8_STAGE(PG8_SA(0, 0), a2, voffA);
;             PG8_WAIT_V(8); PG8_WAIT_L(0); PG8_BAR; PG8_MMA(1, 0, At, B0); PG8_MMA(1, 1, At, B1); PG8_BAR; PG8_SCHED;
;             PG8_LDB(B0, 1, 0); PG8_LDB(B1, 1, 1); PG8_SCHED; PG8_LDA(At, 1, 0); PG8_STAGE(PG8_SA(0, 1), a2 + hstepA, voffA);
;             PG8_WAIT_V(8); PG8_WAIT_L(0); PG8_BAR; PG8_MMA(0, 0, At, B0); PG8_MMA(0, 1, At, B1); PG8_BAR; PG8_SCHED;
	v_mfma_f32_16x16x32_bf16 v[140:143], v[96:99], v[160:163], v[140:143]
	v_mfma_f32_16x16x32_bf16 v[136:139], v[108:111], v[160:163], v[136:139]
	v_mfma_f32_16x16x32_bf16 v[124:127], v[96:99], v[182:185], v[124:127]
	v_mfma_f32_16x16x32_bf16 v[120:123], v[108:111], v[182:185], v[120:123]
	v_mfma_f32_16x16x32_bf16 v[92:95], v[96:99], v[194:197], v[92:95]
	v_mfma_f32_16x16x32_bf16 v[88:91], v[108:111], v[194:197], v[88:91]
	v_mfma_f32_16x16x32_bf16 v[76:79], v[96:99], v[208:211], v[76:79]
	v_mfma_f32_16x16x32_bf16 v[72:75], v[108:111], v[208:211], v[72:75]
	v_mfma_f32_16x16x32_bf16 v[140:143], v[100:103], v[164:167], v[140:143]
	v_mfma_f32_16x16x32_bf16 v[136:139], v[116:119], v[164:167], v[136:139]
	v_mfma_f32_16x16x32_bf16 v[124:127], v[100:103], v[186:189], v[124:127]
	v_mfma_f32_16x16x32_bf16 v[120:123], v[116:119], v[186:189], v[120:123]
	v_mfma_f32_16x16x32_bf16 v[92:95], v[100:103], v[204:207], v[92:95]
	v_mfma_f32_16x16x32_bf16 v[88:91], v[116:119], v[204:207], v[88:91]
	v_mfma_f32_16x16x32_bf16 v[76:79], v[100:103], v[212:215], v[76:79]
	v_mfma_f32_16x16x32_bf16 v[72:75], v[116:119], v[212:215], v[72:75]
	v_mfma_f32_16x16x32_bf16 v[132:135], v[144:147], v[160:163], v[132:135]
	v_mfma_f32_16x16x32_bf16 v[128:131], v[152:155], v[160:163], v[128:131]
	v_mfma_f32_16x16x32_bf16 v[112:115], v[144:147], v[182:185], v[112:115]
	v_mfma_f32_16x16x32_bf16 v[104:107], v[152:155], v[182:185], v[104:107]
	v_mfma_f32_16x16x32_bf16 v[84:87], v[144:147], v[194:197], v[84:87]
	v_mfma_f32_16x16x32_bf16 v[80:83], v[152:155], v[194:197], v[80:83]
	v_mfma_f32_16x16x32_bf16 v[68:71], v[144:147], v[208:211], v[68:71]
	v_mfma_f32_16x16x32_bf16 v[64:67], v[152:155], v[208:211], v[64:67]
	v_mfma_f32_16x16x32_bf16 v[132:135], v[148:151], v[164:167], v[132:135]
	v_mfma_f32_16x16x32_bf16 v[128:131], v[156:159], v[164:167], v[128:131]
	v_mfma_f32_16x16x32_bf16 v[112:115], v[148:151], v[186:189], v[112:115]
	v_mfma_f32_16x16x32_bf16 v[104:107], v[156:159], v[186:189], v[104:107]
	v_mfma_f32_16x16x32_bf16 v[84:87], v[148:151], v[204:207], v[84:87]
	v_mfma_f32_16x16x32_bf16 v[80:83], v[156:159], v[204:207], v[80:83]
	v_mfma_f32_16x16x32_bf16 v[68:71], v[148:151], v[212:215], v[68:71]
	v_mfma_f32_16x16x32_bf16 v[64:67], v[156:159], v[212:215], v[64:67]
	s_barrier
	s_add_i32 s86, s58, s27
	v_lshl_add_u64 v[190:191], s[44:45], 0, v[170:171]
	s_mov_b32 m0, s86
	ds_read_b128 v[160:163], v203 offset:16384
	ds_read_b128 v[164:167], v203 offset:17408
	ds_read_b128 v[182:185], v203 offset:18432
	ds_read_b128 v[186:189], v203 offset:19456
	ds_read_b128 v[194:197], v203 offset:20480
	ds_read_b128 v[204:207], v203 offset:21504
	ds_read_b128 v[208:211], v203 offset:22528
	ds_read_b128 v[212:215], v203 offset:23552
	global_load_lds_dwordx4 v[190:191], off
	s_add_i32 m0, s86, 0x2000
	s_add_u32 s86, s44, 0x160000
	v_lshl_add_u64 v[216:217], s[44:45], 0, v[174:175]
	s_addc_u32 s87, s45, 0
	s_add_i32 s88, s59, s27
	global_load_lds_dwordx4 v[216:217], off
	v_lshl_add_u64 v[218:219], s[86:87], 0, v[170:171]
	s_mov_b32 m0, s88
	v_lshl_add_u64 v[220:221], s[46:47], 0, v[172:173]
	global_load_lds_dwordx4 v[218:219], off
	v_lshl_add_u64 v[218:219], s[86:87], 0, v[174:175]
	s_add_i32 m0, s88, 0x2000
	s_nop 0
	global_load_lds_dwordx4 v[218:219], off
	v_lshl_add_u64 v[218:219], s[46:47], 0, v[168:169]
	s_mov_b32 m0, s48
	s_nop 0
	global_load_lds_dwordx4 v[218:219], off
	s_mov_b32 m0, s49
	s_nop 0
	global_load_lds_dwordx4 v[220:221], off
	s_waitcnt vmcnt(8)
	s_waitcnt lgkmcnt(0)
	s_barrier
	v_mfma_f32_16x16x32_bf16 v[60:63], v[96:99], v[160:163], v[60:63]
	v_mfma_f32_16x16x32_bf16 v[56:59], v[108:111], v[160:163], v[56:59]
	v_mfma_f32_16x16x32_bf16 v[44:47], v[96:99], v[182:185], v[44:47]
	v_mfma_f32_16x16x32_bf16 v[40:43], v[108:111], v[182:185], v[40:43]
	v_mfma_f32_16x16x32_bf16 v[28:31], v[96:99], v[194:197], v[28:31]
	v_mfma_f32_16x16x32_bf16 v[24:27], v[108:111], v[194:197], v[24:27]
	v_mfma_f32_16x16x32_bf16 v[12:15], v[96:99], v[208:211], v[12:15]
	v_mfma_f32_16x16x32_bf16 v[8:11], v[108:111], v[208:211], v[8:11]
	v_mfma_f32_16x16x32_bf16 v[60:63], v[100:103], v[164:167], v[60:63]
	v_mfma_f32_16x16x32_bf16 v[56:59], v[116:119], v[164:167], v[56:59]
	v_mfma_f32_16x16x32_bf16 v[44:47], v[100:103], v[186:189], v[44:47]
	v_mfma_f32_16x16x32_bf16 v[40:43], v[116:119], v[186:189], v[40:43]
	v_mfma_f32_16x16x32_bf16 v[28:31], v[100:103], v[204:207], v[28:31]
	v_mfma_f32_16x16x32_bf16 v[24:27], v[116:119], v[204:207], v[24:27]
	v_mfma_f32_16x16x32_bf16 v[12:15], v[100:103], v[212:215], v[12:15]
	v_mfma_f32_16x16x32_bf16 v[8:11], v[116:119], v[212:215], v[8:11]
	v_mfma_f32_16x16x32_bf16 v[52:55], v[144:147], v[160:163], v[52:55]
	v_mfma_f32_16x16x32_bf16 v[48:51], v[152:155], v[160:163], v[48:51]
	v_mfma_f32_16x16x32_bf16 v[36:39], v[144:147], v[182:185], v[36:39]
	v_mfma_f32_16x16x32_bf16 v[32:35], v[152:155], v[182:185], v[32:35]
	v_mfma_f32_16x16x32_bf16 v[20:23], v[144:147], v[194:197], v[20:23]
	v_mfma_f32_16x16x32_bf16 v[16:19], v[152:155], v[194:197], v[16:19]
	v_mfma_f32_16x16x32_bf16 v[4:7], v[144:147], v[208:211], v[4:7]
	v_mfma_f32_16x16x32_bf16 v[0:3], v[152:155], v[208:211], v[0:3]
	v_mfma_f32_16x16x32_bf16 v[52:55], v[148:151], v[164:167], v[52:55]
	v_mfma_f32_16x16x32_bf16 v[48:51], v[156:159], v[164:167], v[48:51]
	v_mfma_f32_16x16x32_bf16 v[36:39], v[148:151], v[186:189], v[36:39]
	v_mfma_f32_16x16x32_bf16 v[32:35], v[156:159], v[186:189], v[32:35]
	v_mfma_f32_16x16x32_bf16 v[20:23], v[148:151], v[204:207], v[20:23]
	v_mfma_f32_16x16x32_bf16 v[16:19], v[156:159], v[204:207], v[16:19]
	v_mfma_f32_16x16x32_bf16 v[4:7], v[148:151], v[212:215], v[4:7]
	v_mfma_f32_16x16x32_bf16 v[0:3], v[156:159], v[212:215], v[0:3]
	s_barrier
; #define PG8_STAGE(bufoff, gbase, voff) do { _Pragma("unroll") for (int _i = 0; _i < 2; ++_i) \
;         __builtin_amdgcn_global_load_lds((const unsigned*)((const char*)(gbase) + (voff)[_i]), (LAS unsigned*)(lds + (bufoff) + ldsw + _i * 8192), 16, 0, 0); } while (0)
; #define PG8_LDA(dst, b, h) do { _Pragma("unroll") for (int m = 0; m < 4; ++m) _Pragma("unroll") for (int k = 0; k < 2; ++k) dst[m][k] = *(const LAS bf16x8*)(lds + PG8_SA(b, h) + aoff + m * 2048 + k * 1024); } while (0)
; #define PG8_LDB(dst, b, h) do { _Pragma("unroll") for (int n = 0; n < 2; ++n) _Pragma("unroll") for (int k = 0; k < 2; ++k) dst[n][k] = *(const LAS bf16x8*)(lds + PG8_SB(b, h) + boff + n * 2048 + k * 1024); } while (0)
; #define PG8_MMA(ai, bj, At, Bt) do { __builtin_amdgcn_s_setprio(1); _Pragma("unroll") for (int m = 0; m < 4; ++m) _Pragma("unroll") for (int n = 0; n < 2; ++n) _Pragma("unroll") for (int k = 0; k < 2; ++k) \
;         acc[ai][bj][m][n] = __builtin_amdgcn_mfma_f32_16x16x32_bf16(Bt[n][k], At[m][k], acc[ai][bj][m][n], 0, 0, 0); __builtin_amdgcn_s_setprio(0); } while (0)
; #define PG8_WAIT_V(n) asm volatile("s_waitcnt vmcnt(" #n ")" ::: "memory")
; #define PG8_WAIT_L(n) asm volatile("s_waitcnt lgkmcnt(" #n ")" ::: "memory")
; #define PG8_BAR __builtin_amdgcn_s_barrier()
; #define PG8_SCHED __builtin_amdgcn_sched_barrier(0)
; template <class Epi, class Sched = StaticOrder, class EpiSub = NoSub, bool FAST = false>
; __device__ __forceinline__ void gemm_phase(LAS unsigned char* lds, const Gemm g, const Sched& S, const Epi& E, const EpiSub& ES = EpiSub()) {
;     ...
;         for (int t = 0; t < nt; t += 2) {
;     ...
;             PG8_LDB(B0, 1, 0); PG8_LDB(B1, 1, 1); PG8_SCHED; PG8_LDA(At, 1, 0); PG8_STAGE(PG8_SA(0, 1), a2 + hstepA, voffA);
;             PG8_WAIT_V(8); PG8_WAIT_L(0); PG8_BAR; PG8_MMA(0, 0, At, B0); PG8_MMA(0, 1, At, B1); PG8_BAR; PG8_SCHED;
;             PG8_LDA(At, 1, 1); PG8_STAGE(PG8_SB(1, 0), b3, voffB); PG8_STAGE(PG8_SB(1, 1), b3 + hstepB, voffB); PG8_STAGE(PG8_SA(1, 0), a3, voffA);
;             PG8_WAIT_V(8); PG8_WAIT_L(0); PG8_BAR; PG8_MMA(1, 0, At, B0); PG8_MMA(1, 1, At, B1); PG8_BAR; PG8_SCHED;
	s_add_i32 s86, 0, 0x18000
	s_add_i32 s87, 0, 0x1c000
	v_add_u32_e32 v116, s86, v198
	v_add_u32_e32 v156, s87, v198
	ds_read_b128 v[96:99], v116
	ds_read_b128 v[100:103], v116 offset:1024
	ds_read_b128 v[108:111], v116 offset:2048
	ds_read_b128 v[116:119], v116 offset:3072
	ds_read_b128 v[144:147], v156
	ds_read_b128 v[148:151], v156 offset:1024
	ds_read_b128 v[152:155], v156 offset:2048
	ds_read_b128 v[156:159], v156 offset:3072
	s_add_u32 s46, s46, 0x160000
	s_addc_u32 s47, s47, 0
	s_mov_b32 m0, s50
	v_lshl_add_u64 v[222:223], s[46:47], 0, v[168:169]
	ds_read_b128 v[160:163], v203 offset:32768
	ds_read_b128 v[164:167], v203 offset:33792
	ds_read_b128 v[182:185], v203 offset:34816
	ds_read_b128 v[186:189], v203 offset:35840
	ds_read_b128 v[194:197], v203 offset:36864
	ds_read_b128 v[204:207], v203 offset:37888
	ds_read_b128 v[208:211], v203 offset:38912
	ds_read_b128 v[212:215], v203 offset:39936
	global_load_lds_dwordx4 v[222:223], off
	v_lshl_add_u64 v[222:223], s[46:47], 0, v[172:173]
	s_mov_b32 m0, s51
	s_nop 0
	global_load_lds_dwordx4 v[222:223], off
	s_waitcnt vmcnt(8)
	s_waitcnt lgkmcnt(0)
	s_barrier
	v_mfma_f32_16x16x32_bf16 v[140:143], v[96:99], v[160:163], v[140:143]
	v_mfma_f32_16x16x32_bf16 v[136:139], v[108:111], v[160:163], v[136:139]
	v_mfma_f32_16x16x32_bf16 v[124:127], v[96:99], v[182:185], v[124:127]
	v_mfma_f32_16x16x32_bf16 v[120:123], v[108:111], v[182:185], v[120:123]
	v_mfma_f32_16x16x32_bf16 v[92:95], v[96:99], v[194:197], v[92:95]
	v_mfma_f32_16x16x32_bf16 v[88:91], v[108:111], v[194:197], v[88:91]
	v_mfma_f32_16x16x32_bf16 v[76:79], v[96:99], v[208:211], v[76:79]
	v_mfma_f32_16x16x32_bf16 v[72:75], v[108:111], v[208:211], v[72:75]
	v_mfma_f32_16x16x32_bf16 v[140:143], v[100:103], v[164:167], v[140:143]
	v_mfma_f32_16x16x32_bf16 v[136:139], v[116:119], v[164:167], v[136:139]
	v_mfma_f32_16x16x32_bf16 v[124:127], v[100:103], v[186:189], v[124:127]
	v_mfma_f32_16x16x32_bf16 v[120:123], v[116:119], v[186:189], v[120:123]
	v_mfma_f32_16x16x32_bf16 v[92:95], v[100:103], v[204:207], v[92:95]
	v_mfma_f32_16x16x32_bf16 v[88:91], v[116:119], v[204:207], v[88:91]
	v_mfma_f32_16x16x32_bf16 v[76:79], v[100:103], v[212:215], v[76:79]
	v_mfma_f32_16x16x32_bf16 v[72:75], v[116:119], v[212:215], v[72:75]
	v_mfma_f32_16x16x32_bf16 v[132:135], v[144:147], v[160:163], v[132:135]
	v_mfma_f32_16x16x32_bf16 v[128:131], v[152:155], v[160:163], v[128:131]
	v_mfma_f32_16x16x32_bf16 v[112:115], v[144:147], v[182:185], v[112:115]
	v_mfma_f32_16x16x32_bf16 v[104:107], v[152:155], v[182:185], v[104:107]
	v_mfma_f32_16x16x32_bf16 v[84:87], v[144:147], v[194:197], v[84:87]
	v_mfma_f32_16x16x32_bf16 v[80:83], v[152:155], v[194:197], v[80:83]
	v_mfma_f32_16x16x32_bf16 v[68:71], v[144:147], v[208:211], v[68:71]
	v_mfma_f32_16x16x32_bf16 v[64:67], v[152:155], v[208:211], v[64:67]
	v_mfma_f32_16x16x32_bf16 v[132:135], v[148:151], v[164:167], v[132:135]
	v_mfma_f32_16x16x32_bf16 v[128:131], v[156:159], v[164:167], v[128:131]
	v_mfma_f32_16x16x32_bf16 v[112:115], v[148:151], v[186:189], v[112:115]
	v_mfma_f32_16x16x32_bf16 v[104:107], v[156:159], v[186:189], v[104:107]
	v_mfma_f32_16x16x32_bf16 v[84:87], v[148:151], v[204:207], v[84:87]
	v_mfma_f32_16x16x32_bf16 v[80:83], v[156:159], v[204:207], v[80:83]
	v_mfma_f32_16x16x32_bf16 v[68:71], v[148:151], v[212:215], v[68:71]
	v_mfma_f32_16x16x32_bf16 v[64:67], v[156:159], v[212:215], v[64:67]
	s_barrier
	s_add_i32 s46, s86, s27
	v_lshl_add_u64 v[190:191], v[190:191], 0, s[16:17]
	s_mov_b32 m0, s46
	ds_read_b128 v[160:163], v203 offset:49152
	ds_read_b128 v[164:167], v203 offset:50176
	ds_read_b128 v[182:185], v203 offset:51200
	ds_read_b128 v[186:189], v203 offset:52224
	ds_read_b128 v[194:197], v203 offset:53248
	ds_read_b128 v[204:207], v203 offset:54272
	ds_read_b128 v[208:211], v203 offset:55296
	ds_read_b128 v[212:215], v203 offset:56320
	global_load_lds_dwordx4 v[190:191], off
	s_add_i32 m0, s46, 0x2000
	s_add_u32 s44, s44, 0x160080
	v_lshl_add_u64 v[190:191], v[216:217], 0, s[16:17]
	s_addc_u32 s45, s45, 0
	s_add_i32 s46, s87, s27
	global_load_lds_dwordx4 v[190:191], off
	v_lshl_add_u64 v[190:191], s[44:45], 0, v[170:171]
	s_mov_b32 m0, s46
	s_nop 0
	global_load_lds_dwordx4 v[190:191], off
	v_lshl_add_u64 v[190:191], s[44:45], 0, v[174:175]
	s_add_i32 m0, s46, 0x2000
	s_nop 0
	global_load_lds_dwordx4 v[190:191], off
	v_lshl_add_u64 v[190:191], v[218:219], 0, s[16:17]
	s_mov_b32 m0, s53
	s_nop 0
	global_load_lds_dwordx4 v[190:191], off
	v_lshl_add_u64 v[190:191], v[220:221], 0, s[16:17]
	s_mov_b32 m0, s54
	s_nop 0
	global_load_lds_dwordx4 v[190:191], off
	s_waitcnt vmcnt(8)
	s_waitcnt lgkmcnt(0)
	s_barrier
	v_mfma_f32_16x16x32_bf16 v[60:63], v[96:99], v[160:163], v[60:63]
	v_mfma_f32_16x16x32_bf16 v[56:59], v[108:111], v[160:163], v[56:59]
	v_mfma_f32_16x16x32_bf16 v[44:47], v[96:99], v[182:185], v[44:47]
	v_mfma_f32_16x16x32_bf16 v[40:43], v[108:111], v[182:185], v[40:43]
	v_mfma_f32_16x16x32_bf16 v[28:31], v[96:99], v[194:197], v[28:31]
	v_mfma_f32_16x16x32_bf16 v[24:27], v[108:111], v[194:197], v[24:27]
	v_mfma_f32_16x16x32_bf16 v[12:15], v[96:99], v[208:211], v[12:15]
	v_mfma_f32_16x16x32_bf16 v[8:11], v[108:111], v[208:211], v[8:11]
	v_mfma_f32_16x16x32_bf16 v[60:63], v[100:103], v[164:167], v[60:63]
	v_mfma_f32_16x16x32_bf16 v[56:59], v[116:119], v[164:167], v[56:59]
	v_mfma_f32_16x16x32_bf16 v[44:47], v[100:103], v[186:189], v[44:47]
	v_mfma_f32_16x16x32_bf16 v[40:43], v[116:119], v[186:189], v[40:43]
	v_mfma_f32_16x16x32_bf16 v[28:31], v[100:103], v[204:207], v[28:31]
	v_mfma_f32_16x16x32_bf16 v[24:27], v[116:119], v[204:207], v[24:27]
	v_mfma_f32_16x16x32_bf16 v[12:15], v[100:103], v[212:215], v[12:15]
	v_mfma_f32_16x16x32_bf16 v[8:11], v[116:119], v[212:215], v[8:11]
	v_mfma_f32_16x16x32_bf16 v[52:55], v[144:147], v[160:163], v[52:55]
	v_mfma_f32_16x16x32_bf16 v[48:51], v[152:155], v[160:163], v[48:51]
	v_mfma_f32_16x16x32_bf16 v[36:39], v[144:147], v[182:185], v[36:39]
	v_mfma_f32_16x16x32_bf16 v[32:35], v[152:155], v[182:185], v[32:35]
	v_mfma_f32_16x16x32_bf16 v[20:23], v[144:147], v[194:197], v[20:23]
	v_mfma_f32_16x16x32_bf16 v[16:19], v[152:155], v[194:197], v[16:19]
	v_mfma_f32_16x16x32_bf16 v[4:7], v[144:147], v[208:211], v[4:7]
	v_mfma_f32_16x16x32_bf16 v[0:3], v[152:155], v[208:211], v[0:3]
	v_mfma_f32_16x16x32_bf16 v[52:55], v[148:151], v[164:167], v[52:55]
	v_mfma_f32_16x16x32_bf16 v[48:51], v[156:159], v[164:167], v[48:51]
	v_mfma_f32_16x16x32_bf16 v[36:39], v[148:151], v[186:189], v[36:39]
	v_mfma_f32_16x16x32_bf16 v[32:35], v[156:159], v[186:189], v[32:35]
	v_mfma_f32_16x16x32_bf16 v[20:23], v[148:151], v[204:207], v[20:23]
	v_mfma_f32_16x16x32_bf16 v[16:19], v[156:159], v[204:207], v[16:19]
	v_mfma_f32_16x16x32_bf16 v[4:7], v[148:151], v[212:215], v[4:7]
	v_mfma_f32_16x16x32_bf16 v[0:3], v[156:159], v[212:215], v[0:3]
	s_barrier
	s_add_u32 s42, s42, 0x100
	s_addc_u32 s43, s43, 0
	s_add_u32 s83, s83, 0x100
	s_addc_u32 s84, s84, 0
	s_cmp_ge_u32 s85, s70
	s_mov_b32 s46, s85
	s_cbranch_scc0 .LBB0_1079
